# peeled first K-tile with C=0 MFMAs (no accumulator zeroing), relaxed first-tile vmcnt after SwiGLU epilogue stores
# speedup vs baseline: 1.0063x; 1.0063x over previous
; #define LAS __attribute__((address_space(3)))
; __global__ void __launch_bounds__(NWAVES * 64, 2) fwd_megakernel(Args args) {
;     ...
;     const int tid = threadIdx.x, lane = tid & 63, wave = __builtin_amdgcn_readfirstlane(tid >> 6);
;     const int G = gridDim.x, bx = blockIdx.x;
;     const int gw = bx * NWAVES + wave, NGW = G * NWAVES;
;     unsigned char* ws = args.ws;
;     float* ss0 = (float*)(ws + WS_SS); float* ss1 = ss0 + M; float* ss2 = ss1 + M; float* ss3 = ss2 + M;
;     const int lo = args.ph_lo, hi = args.ph_hi;
;     LAS float* rsl = (LAS float*)(lds + RING_BYTES);
;     if (tid < 4) ((LAS unsigned*)(lds + LDS_BARW))[tid] = 0u;
;     for (unsigned i = (unsigned)(bx * (NWAVES * 64) + tid); i < (unsigned)(CTL_USED_BYTES / 16); i += (unsigned)(G * NWAVES * 64)) ((u32x4*)(ws + WS_CTL))[i] = (u32x4){0u, 0u, 0u, 0u};
_Z14fwd_megakernel4Args:
	s_mov_b32 s101, 0
	s_load_dword s94, s[0:1], 0xc0
	s_load_dwordx4 s[72:75], s[0:1], 0xa0
	s_load_dwordx2 s[76:77], s[0:1], 0xb8
	s_load_dwordx8 s[80:87], s[0:1], 0x80
	s_mov_b32 s95, s2
	s_add_u32 s2, s0, 0xb8
	v_and_b32_e32 v153, 0x3ff, v0
	s_addc_u32 s3, s1, 0
	v_readfirstlane_b32 s96, v153
	v_cmp_gt_u32_e32 vcc, 4, v153
	s_and_saveexec_b64 s[4:5], vcc
	v_lshl_add_u32 v1, v153, 2, 0
	v_add_u32_e32 v1, 0x23fc0, v1
	v_mov_b32_e32 v2, 0
	ds_write_b32 v1, v2
	s_or_b64 exec, exec, s[4:5]
	s_or_b32 s100, s95, s96
	s_cmp_eq_u32 s100, 0
	s_cselect_b32 s100, 1, 0
	s_load_dwordx2 s[88:89], s[0:1], 0xb0
	v_lshl_add_u32 v2, s95, 9, v153
	v_add_u32_e32 v2, 0x3000, v2
	s_mov_b32 s4, 0x9000
	v_cmp_gt_u32_e32 vcc, s4, v2
	s_and_saveexec_b64 s[4:5], vcc
	s_cbranch_execz .LBB0_5
	v_mov_b32_e32 v3, 0
	s_waitcnt lgkmcnt(0)
	s_lshl_b32 s8, s76, 9
	s_mov_b64 s[6:7], 0
	v_mov_b32_e32 v4, v3
	v_mov_b32_e32 v5, v3
	v_mov_b32_e32 v6, v3
	v_mov_b32_e32 v7, v3
	s_mov_b32 s9, 0x8fff

; template <class Epi, class Sched, bool ALIGN_EPI>
; __device__ __forceinline__ void gemm_phase(LAS unsigned char* lds, const Gemm g, const Sched& S, const Epi& E) {
;     ...
;         const bool has_next = S.next(ui + 1, nxt);
;         const char* nA = has_next ? (const char*)g.A + (size_t)nxt.pm * tstepA : cA; const char* nB = has_next ? (const char*)g.Bt + (size_t)nxt.pn * tstepB : cB;
.LBB0_606:
	s_ashr_i32 s15, s14, 31
	s_lshl_b64 s[16:17], s[14:15], 19
	s_add_u32 s16, s29, s16
	s_addc_u32 s17, s30, s17
	s_and_b64 s[18:19], s[2:3], exec
	s_cselect_b32 s15, s17, s23
	s_cselect_b32 s48, s16, s22
	s_ashr_i32 s13, s12, 31
	s_lshl_b64 s[18:19], s[12:13], 19
	s_add_u32 s18, s31, s18
	s_addc_u32 s19, s33, s19
	s_and_b64 s[26:27], s[2:3], exec
	s_cselect_b32 s13, s19, s25
	s_cselect_b32 s49, s18, s24
	s_add_u32 s22, s22, 0x40080
	s_addc_u32 s23, s23, 0
	s_add_u32 s50, s24, 0x100
	v_mov_b32_e32 v0, 0
	s_addc_u32 s51, s25, 0
	s_mov_b32 s52, -2
	ds_read_b128 v[154:157], v148
	ds_read_b128 v[158:161], v148 offset:1024
	ds_read_b128 v[162:165], v148 offset:2048
	ds_read_b128 v[166:169], v148 offset:3072
	ds_read_b128 v[170:173], v149
	ds_read_b128 v[174:177], v149 offset:1024
	ds_read_b128 v[178:181], v149 offset:2048
	ds_read_b128 v[182:185], v149 offset:3072
	s_add_u32 s24, s22, 0xfffc0080
	s_addc_u32 s25, s23, -1
	s_cmp_eq_u32 s52, 12
	s_cselect_b32 s27, s15, s25
	s_cselect_b32 s26, s48, s24
	s_cselect_b32 s25, s13, s51
	s_cselect_b32 s24, s49, s50
	v_lshl_add_u64 v[218:219], s[22:23], 0, v[136:137]
	s_add_i32 m0, s21, 0xc000
	ds_read_b128 v[186:189], v150
	ds_read_b128 v[190:193], v150 offset:1024
	ds_read_b128 v[194:197], v150 offset:2048
	ds_read_b128 v[198:201], v150 offset:3072
	ds_read_b128 v[202:205], v150 offset:4096
	ds_read_b128 v[206:209], v150 offset:5120
	ds_read_b128 v[210:213], v150 offset:6144
	ds_read_b128 v[214:217], v150 offset:7168
	global_load_lds_dwordx4 v[218:219], off
	v_lshl_add_u64 v[218:219], s[22:23], 0, v[138:139]
	s_add_i32 m0, s21, 0xe000
	s_nop 0
	global_load_lds_dwordx4 v[218:219], off
	s_cmp_eq_u32 s101, 1
	s_cbranch_scc1 .Lpk607_r1
	s_waitcnt vmcnt(8)
	s_branch .Lpk607_j1
.Lpk607_r1:
	s_waitcnt vmcnt(16)
.Lpk607_j1:
	s_waitcnt lgkmcnt(0)
	s_barrier
	s_setprio 1
	s_waitcnt lgkmcnt(0)
	v_mfma_f32_16x16x32_bf16 v[124:127], v[154:157], v[186:189], 0
	v_mfma_f32_16x16x32_bf16 v[116:119], v[162:165], v[186:189], 0
	v_mfma_f32_16x16x32_bf16 v[108:111], v[154:157], v[194:197], 0
	v_mfma_f32_16x16x32_bf16 v[100:103], v[162:165], v[194:197], 0
	v_mfma_f32_16x16x32_bf16 v[92:95], v[154:157], v[202:205], 0
	v_mfma_f32_16x16x32_bf16 v[84:87], v[162:165], v[202:205], 0
	v_mfma_f32_16x16x32_bf16 v[76:79], v[154:157], v[210:213], 0
	v_mfma_f32_16x16x32_bf16 v[68:71], v[162:165], v[210:213], 0
	v_mfma_f32_16x16x32_bf16 v[124:127], v[158:161], v[190:193], v[124:127]
	v_mfma_f32_16x16x32_bf16 v[116:119], v[166:169], v[190:193], v[116:119]
	v_mfma_f32_16x16x32_bf16 v[108:111], v[158:161], v[198:201], v[108:111]
	v_mfma_f32_16x16x32_bf16 v[100:103], v[166:169], v[198:201], v[100:103]
	v_mfma_f32_16x16x32_bf16 v[92:95], v[158:161], v[206:209], v[92:95]
	v_mfma_f32_16x16x32_bf16 v[84:87], v[166:169], v[206:209], v[84:87]
	v_mfma_f32_16x16x32_bf16 v[76:79], v[158:161], v[214:217], v[76:79]
	v_mfma_f32_16x16x32_bf16 v[68:71], v[166:169], v[214:217], v[68:71]
	s_setprio 0
	s_setprio 1
	v_mfma_f32_16x16x32_bf16 v[120:123], v[170:173], v[186:189], 0
	v_mfma_f32_16x16x32_bf16 v[112:115], v[178:181], v[186:189], 0
	v_mfma_f32_16x16x32_bf16 v[104:107], v[170:173], v[194:197], 0
	v_mfma_f32_16x16x32_bf16 v[96:99], v[178:181], v[194:197], 0
	v_mfma_f32_16x16x32_bf16 v[88:91], v[170:173], v[202:205], 0
	v_mfma_f32_16x16x32_bf16 v[80:83], v[178:181], v[202:205], 0
	v_mfma_f32_16x16x32_bf16 v[72:75], v[170:173], v[210:213], 0
	v_mfma_f32_16x16x32_bf16 v[64:67], v[178:181], v[210:213], 0
	v_mfma_f32_16x16x32_bf16 v[120:123], v[174:177], v[190:193], v[120:123]
	v_mfma_f32_16x16x32_bf16 v[112:115], v[182:185], v[190:193], v[112:115]
	v_mfma_f32_16x16x32_bf16 v[104:107], v[174:177], v[198:201], v[104:107]
	v_mfma_f32_16x16x32_bf16 v[96:99], v[182:185], v[198:201], v[96:99]
	v_mfma_f32_16x16x32_bf16 v[88:91], v[174:177], v[206:209], v[88:91]
	v_mfma_f32_16x16x32_bf16 v[80:83], v[182:185], v[206:209], v[80:83]
	v_mfma_f32_16x16x32_bf16 v[72:75], v[174:177], v[214:217], v[72:75]
	v_mfma_f32_16x16x32_bf16 v[64:67], v[182:185], v[214:217], v[64:67]
	s_setprio 0
	s_barrier
	s_add_i32 s53, s40, s28
	v_lshl_add_u64 v[218:219], s[24:25], 0, v[132:133]
	s_mov_b32 m0, s53
	ds_read_b128 v[186:189], v150 offset:16384
	ds_read_b128 v[190:193], v150 offset:17408
	global_load_lds_dwordx4 v[218:219], off
	s_add_i32 m0, s53, 0x2000
	s_add_u32 s66, s24, 0x40000
	v_lshl_add_u64 v[220:221], s[24:25], 0, v[128:129]
	s_addc_u32 s67, s25, 0
	s_add_i32 s53, s41, s28
	ds_read_b128 v[194:197], v150 offset:18432
	ds_read_b128 v[198:201], v150 offset:19456
	global_load_lds_dwordx4 v[220:221], off
	v_lshl_add_u64 v[222:223], s[66:67], 0, v[132:133]
	s_mov_b32 m0, s53
	v_lshl_add_u64 v[224:225], s[26:27], 0, v[130:131]
	ds_read_b128 v[202:205], v150 offset:20480
	global_load_lds_dwordx4 v[222:223], off
	v_lshl_add_u64 v[222:223], s[66:67], 0, v[128:129]
	s_add_i32 m0, s53, 0x2000
	ds_read_b128 v[206:209], v150 offset:21504
	global_load_lds_dwordx4 v[222:223], off
	v_lshl_add_u64 v[222:223], s[26:27], 0, v[134:135]
	s_mov_b32 m0, s21
	ds_read_b128 v[210:213], v150 offset:22528
	global_load_lds_dwordx4 v[222:223], off
	s_mov_b32 m0, s35
	ds_read_b128 v[214:217], v150 offset:23552
	global_load_lds_dwordx4 v[224:225], off
	s_cmp_eq_u32 s101, 1
	s_cbranch_scc1 .Lpk607_r2
	s_waitcnt vmcnt(8)
	s_branch .Lpk607_j2

.Lpk607_j2:
	s_mov_b32 s101, 0
	s_waitcnt lgkmcnt(0)
	s_barrier
	s_setprio 1
	s_waitcnt lgkmcnt(0)
	v_mfma_f32_16x16x32_bf16 v[60:63], v[154:157], v[186:189], 0
	v_mfma_f32_16x16x32_bf16 v[52:55], v[162:165], v[186:189], 0
	v_mfma_f32_16x16x32_bf16 v[44:47], v[154:157], v[194:197], 0
	v_mfma_f32_16x16x32_bf16 v[36:39], v[162:165], v[194:197], 0
	v_mfma_f32_16x16x32_bf16 v[28:31], v[154:157], v[202:205], 0
	v_mfma_f32_16x16x32_bf16 v[20:23], v[162:165], v[202:205], 0
	v_mfma_f32_16x16x32_bf16 v[12:15], v[154:157], v[210:213], 0
	v_mfma_f32_16x16x32_bf16 v[4:7], v[162:165], v[210:213], 0
	v_mfma_f32_16x16x32_bf16 v[60:63], v[158:161], v[190:193], v[60:63]
	v_mfma_f32_16x16x32_bf16 v[52:55], v[166:169], v[190:193], v[52:55]
	v_mfma_f32_16x16x32_bf16 v[44:47], v[158:161], v[198:201], v[44:47]
	v_mfma_f32_16x16x32_bf16 v[36:39], v[166:169], v[198:201], v[36:39]
	v_mfma_f32_16x16x32_bf16 v[28:31], v[158:161], v[206:209], v[28:31]
	v_mfma_f32_16x16x32_bf16 v[20:23], v[166:169], v[206:209], v[20:23]
	v_mfma_f32_16x16x32_bf16 v[12:15], v[158:161], v[214:217], v[12:15]
	v_mfma_f32_16x16x32_bf16 v[4:7], v[166:169], v[214:217], v[4:7]
	s_setprio 0
	s_setprio 1
	v_mfma_f32_16x16x32_bf16 v[56:59], v[170:173], v[186:189], 0
	v_mfma_f32_16x16x32_bf16 v[48:51], v[178:181], v[186:189], 0
	v_mfma_f32_16x16x32_bf16 v[40:43], v[170:173], v[194:197], 0
	v_mfma_f32_16x16x32_bf16 v[32:35], v[178:181], v[194:197], 0
	v_mfma_f32_16x16x32_bf16 v[24:27], v[170:173], v[202:205], 0
	v_mfma_f32_16x16x32_bf16 v[16:19], v[178:181], v[202:205], 0
	v_mfma_f32_16x16x32_bf16 v[8:11], v[170:173], v[210:213], 0
	v_mfma_f32_16x16x32_bf16 v[0:3], v[178:181], v[210:213], 0
	v_mfma_f32_16x16x32_bf16 v[56:59], v[174:177], v[190:193], v[56:59]
	v_mfma_f32_16x16x32_bf16 v[48:51], v[182:185], v[190:193], v[48:51]
	v_mfma_f32_16x16x32_bf16 v[40:43], v[174:177], v[198:201], v[40:43]
	v_mfma_f32_16x16x32_bf16 v[32:35], v[182:185], v[198:201], v[32:35]
	v_mfma_f32_16x16x32_bf16 v[24:27], v[174:177], v[206:209], v[24:27]
	v_mfma_f32_16x16x32_bf16 v[16:19], v[182:185], v[206:209], v[16:19]
	v_mfma_f32_16x16x32_bf16 v[8:11], v[174:177], v[214:217], v[8:11]
	v_mfma_f32_16x16x32_bf16 v[0:3], v[182:185], v[214:217], v[0:3]
	s_setprio 0
	s_barrier
	s_branch .Lpk607_seg3

.Lpk607_seg3:
	s_add_i32 s53, 0, 0x18000
	v_add_u32_e32 v151, s53, v145
	s_add_i32 s54, 0, 0x1c000
	ds_read_b128 v[154:157], v151
	ds_read_b128 v[158:161], v151 offset:1024
	ds_read_b128 v[162:165], v151 offset:2048
	ds_read_b128 v[166:169], v151 offset:3072
	v_add_u32_e32 v151, s54, v145
	ds_read_b128 v[170:173], v151
	ds_read_b128 v[174:177], v151 offset:1024
	ds_read_b128 v[178:181], v151 offset:2048
	ds_read_b128 v[182:185], v151 offset:3072
	s_add_u32 s26, s26, 0x40000
	s_addc_u32 s27, s27, 0
	s_mov_b32 m0, s36
	v_lshl_add_u64 v[226:227], s[26:27], 0, v[134:135]
	ds_read_b128 v[186:189], v150 offset:32768
	ds_read_b128 v[190:193], v150 offset:33792
	ds_read_b128 v[194:197], v150 offset:34816
	ds_read_b128 v[198:201], v150 offset:35840
	ds_read_b128 v[202:205], v150 offset:36864
	ds_read_b128 v[206:209], v150 offset:37888
	ds_read_b128 v[210:213], v150 offset:38912
	ds_read_b128 v[214:217], v150 offset:39936
	global_load_lds_dwordx4 v[226:227], off
	v_lshl_add_u64 v[226:227], s[26:27], 0, v[130:131]
	s_mov_b32 m0, s37
	s_nop 0
	global_load_lds_dwordx4 v[226:227], off
	s_waitcnt vmcnt(8)
	s_waitcnt lgkmcnt(0)
	s_barrier
	s_setprio 1
	s_waitcnt lgkmcnt(0)
	v_mfma_f32_16x16x32_bf16 v[124:127], v[154:157], v[186:189], v[124:127]
	v_mfma_f32_16x16x32_bf16 v[116:119], v[162:165], v[186:189], v[116:119]
	v_mfma_f32_16x16x32_bf16 v[108:111], v[154:157], v[194:197], v[108:111]
	v_mfma_f32_16x16x32_bf16 v[100:103], v[162:165], v[194:197], v[100:103]
	v_mfma_f32_16x16x32_bf16 v[92:95], v[154:157], v[202:205], v[92:95]
	v_mfma_f32_16x16x32_bf16 v[84:87], v[162:165], v[202:205], v[84:87]
	v_mfma_f32_16x16x32_bf16 v[76:79], v[154:157], v[210:213], v[76:79]
	v_mfma_f32_16x16x32_bf16 v[68:71], v[162:165], v[210:213], v[68:71]
	v_mfma_f32_16x16x32_bf16 v[124:127], v[158:161], v[190:193], v[124:127]
	v_mfma_f32_16x16x32_bf16 v[116:119], v[166:169], v[190:193], v[116:119]
	v_mfma_f32_16x16x32_bf16 v[108:111], v[158:161], v[198:201], v[108:111]
	v_mfma_f32_16x16x32_bf16 v[100:103], v[166:169], v[198:201], v[100:103]
	v_mfma_f32_16x16x32_bf16 v[92:95], v[158:161], v[206:209], v[92:95]
	v_mfma_f32_16x16x32_bf16 v[84:87], v[166:169], v[206:209], v[84:87]
	v_mfma_f32_16x16x32_bf16 v[76:79], v[158:161], v[214:217], v[76:79]
	v_mfma_f32_16x16x32_bf16 v[68:71], v[166:169], v[214:217], v[68:71]
	s_setprio 0
	s_setprio 1
	v_mfma_f32_16x16x32_bf16 v[120:123], v[170:173], v[186:189], v[120:123]
	v_mfma_f32_16x16x32_bf16 v[112:115], v[178:181], v[186:189], v[112:115]
	v_mfma_f32_16x16x32_bf16 v[104:107], v[170:173], v[194:197], v[104:107]
	v_mfma_f32_16x16x32_bf16 v[96:99], v[178:181], v[194:197], v[96:99]
	v_mfma_f32_16x16x32_bf16 v[88:91], v[170:173], v[202:205], v[88:91]
	v_mfma_f32_16x16x32_bf16 v[80:83], v[178:181], v[202:205], v[80:83]
	v_mfma_f32_16x16x32_bf16 v[72:75], v[170:173], v[210:213], v[72:75]
	v_mfma_f32_16x16x32_bf16 v[64:67], v[178:181], v[210:213], v[64:67]
	v_mfma_f32_16x16x32_bf16 v[120:123], v[174:177], v[190:193], v[120:123]
	v_mfma_f32_16x16x32_bf16 v[112:115], v[182:185], v[190:193], v[112:115]
	v_mfma_f32_16x16x32_bf16 v[104:107], v[174:177], v[198:201], v[104:107]
	v_mfma_f32_16x16x32_bf16 v[96:99], v[182:185], v[198:201], v[96:99]
	v_mfma_f32_16x16x32_bf16 v[88:91], v[174:177], v[206:209], v[88:91]
	v_mfma_f32_16x16x32_bf16 v[80:83], v[182:185], v[206:209], v[80:83]
	v_mfma_f32_16x16x32_bf16 v[72:75], v[174:177], v[214:217], v[72:75]
	v_mfma_f32_16x16x32_bf16 v[64:67], v[182:185], v[214:217], v[64:67]
	s_setprio 0
	s_barrier
	s_add_i32 s26, s53, s28
	v_lshl_add_u64 v[218:219], v[218:219], 0, s[8:9]
	s_mov_b32 m0, s26
	ds_read_b128 v[186:189], v150 offset:49152
	ds_read_b128 v[190:193], v150 offset:50176
	global_load_lds_dwordx4 v[218:219], off
	s_add_i32 m0, s26, 0x2000
	s_add_u32 s24, s24, 0x40080
	v_lshl_add_u64 v[218:219], v[220:221], 0, s[8:9]
	s_addc_u32 s25, s25, 0
	s_add_i32 s26, s54, s28
	ds_read_b128 v[194:197], v150 offset:51200
	ds_read_b128 v[198:201], v150 offset:52224
	global_load_lds_dwordx4 v[218:219], off
	v_lshl_add_u64 v[218:219], s[24:25], 0, v[132:133]
	s_mov_b32 m0, s26
	ds_read_b128 v[202:205], v150 offset:53248
	global_load_lds_dwordx4 v[218:219], off
	v_lshl_add_u64 v[218:219], s[24:25], 0, v[128:129]
	s_add_i32 m0, s26, 0x2000
	ds_read_b128 v[206:209], v150 offset:54272
	global_load_lds_dwordx4 v[218:219], off
	v_lshl_add_u64 v[218:219], v[222:223], 0, s[8:9]
	s_mov_b32 m0, s38
	ds_read_b128 v[210:213], v150 offset:55296
	global_load_lds_dwordx4 v[218:219], off
	v_lshl_add_u64 v[218:219], v[224:225], 0, s[8:9]
	s_mov_b32 m0, s39
	ds_read_b128 v[214:217], v150 offset:56320
	global_load_lds_dwordx4 v[218:219], off
	s_waitcnt vmcnt(8)
	s_waitcnt lgkmcnt(0)
	s_barrier
; __device__ __forceinline__ unsigned cvt_pk_bf16(float lo, float hi) { unsigned r; asm volatile("v_cvt_pk_bf16_f32 %0, %1, %2" : "=v"(r) : "v"(lo), "v"(hi)); return r; }
;     __device__ __forceinline__ void operator()(Acc& acc, const Unit& u, int wr, int wc, int fr, int fq) const { scale(acc, u, wr, wc, fr, fq, PC_GA, true); }
;     __device__ __forceinline__ void operator()(Acc& acc, const Unit& u, int wr, int wc, int fr, int fq) const {
;         const int row0 = u.pm * BM + wr * 64 + fr, col0 = u.pn * 128 + wc * 32 + 8 * fq;
; #pragma unroll
;         for (int ai = 0; ai < 2; ++ai)
; #pragma unroll
;             for (int m = 0; m < 4; ++m) {
;                 const int row = row0 + ai * HALF + m * 16;
;                 const float r = rs[u.idx * BM + wr * 64 + fr + ai * HALF + m * 16];
;                 const float c1 = -r * 1.4426950408889634f, r2 = r * r;
;                 f32x4 o[2];
; #pragma unroll
;                 for (int n = 0; n < 2; ++n) {
;                     const f32x4 g = acc[ai][0][m][n], up = acc[ai][1][m][n];
;                     const f32x4 t = g * c1; f32x4 e;
; #pragma unroll
;                     for (int i = 0; i < 4; ++i) e[i] = __builtin_amdgcn_exp2f(t[i]);
;                     const f32x4 d = e + 1.0f; f32x4 q;
; #pragma unroll
;                     for (int i = 0; i < 4; ++i) q[i] = __builtin_amdgcn_rcpf(d[i]);
;                     o[n] = (g * up) * (q * r2);
;                 }
;                 u32x4 w; w.x = cvt_pk_bf16(o[0][0], o[0][1]); w.y = cvt_pk_bf16(o[0][2], o[0][3]); w.z = cvt_pk_bf16(o[1][0], o[1][1]); w.w = cvt_pk_bf16(o[1][2], o[1][3]);
;                 *(u32x4*)(O + (size_t)row * DFF + col0) = w;
;             }
	s_setprio 1
	s_waitcnt lgkmcnt(0)
	v_mfma_f32_16x16x32_bf16 v[60:63], v[154:157], v[186:189], v[60:63]
	v_mfma_f32_16x16x32_bf16 v[52:55], v[162:165], v[186:189], v[52:55]
	v_mfma_f32_16x16x32_bf16 v[44:47], v[154:157], v[194:197], v[44:47]
	v_mfma_f32_16x16x32_bf16 v[36:39], v[162:165], v[194:197], v[36:39]
	v_mfma_f32_16x16x32_bf16 v[28:31], v[154:157], v[202:205], v[28:31]
	v_mfma_f32_16x16x32_bf16 v[20:23], v[162:165], v[202:205], v[20:23]
	v_mfma_f32_16x16x32_bf16 v[12:15], v[154:157], v[210:213], v[12:15]
	v_mfma_f32_16x16x32_bf16 v[4:7], v[162:165], v[210:213], v[4:7]
	v_mfma_f32_16x16x32_bf16 v[60:63], v[158:161], v[190:193], v[60:63]
	v_mfma_f32_16x16x32_bf16 v[52:55], v[166:169], v[190:193], v[52:55]
	v_mfma_f32_16x16x32_bf16 v[44:47], v[158:161], v[198:201], v[44:47]
	v_mfma_f32_16x16x32_bf16 v[36:39], v[166:169], v[198:201], v[36:39]
	v_mfma_f32_16x16x32_bf16 v[28:31], v[158:161], v[206:209], v[28:31]
	v_mfma_f32_16x16x32_bf16 v[20:23], v[166:169], v[206:209], v[20:23]
	v_mfma_f32_16x16x32_bf16 v[12:15], v[158:161], v[214:217], v[12:15]
	v_mfma_f32_16x16x32_bf16 v[4:7], v[166:169], v[214:217], v[4:7]
	s_setprio 0
	s_setprio 1
	v_mfma_f32_16x16x32_bf16 v[56:59], v[170:173], v[186:189], v[56:59]
	v_mfma_f32_16x16x32_bf16 v[48:51], v[178:181], v[186:189], v[48:51]
	v_mfma_f32_16x16x32_bf16 v[40:43], v[170:173], v[194:197], v[40:43]
	v_mfma_f32_16x16x32_bf16 v[32:35], v[178:181], v[194:197], v[32:35]
	v_mfma_f32_16x16x32_bf16 v[24:27], v[170:173], v[202:205], v[24:27]
	v_mfma_f32_16x16x32_bf16 v[16:19], v[178:181], v[202:205], v[16:19]
	v_mfma_f32_16x16x32_bf16 v[8:11], v[170:173], v[210:213], v[8:11]
	v_mfma_f32_16x16x32_bf16 v[0:3], v[178:181], v[210:213], v[0:3]
	v_mfma_f32_16x16x32_bf16 v[56:59], v[174:177], v[190:193], v[56:59]
	v_mfma_f32_16x16x32_bf16 v[48:51], v[182:185], v[190:193], v[48:51]
	v_mfma_f32_16x16x32_bf16 v[40:43], v[174:177], v[198:201], v[40:43]
	v_mfma_f32_16x16x32_bf16 v[32:35], v[182:185], v[198:201], v[32:35]
	v_mfma_f32_16x16x32_bf16 v[24:27], v[174:177], v[206:209], v[24:27]
	v_mfma_f32_16x16x32_bf16 v[16:19], v[182:185], v[206:209], v[16:19]
	v_mfma_f32_16x16x32_bf16 v[8:11], v[174:177], v[214:217], v[8:11]
	v_mfma_f32_16x16x32_bf16 v[0:3], v[182:185], v[214:217], v[0:3]
	s_setprio 0
	s_barrier
	s_add_i32 s52, s52, 2
	s_add_u32 s22, s22, 0x100
	s_addc_u32 s23, s23, 0
	s_add_u32 s50, s50, 0x100
	s_addc_u32 s51, s51, 0
	s_cmp_gt_u32 s52, 13
	s_cbranch_scc0 .LBB0_607
	s_and_b64 vcc, exec, s[10:11]
	s_cbranch_vccz .LBB0_610
	s_barrier
.LBB0_610:
	v_lshl_add_u32 v154, s45, 10, v146
	ds_read_b32 v155, v154
	v_pk_mul_f32 v[122:123], v[126:127], v[122:123]
	v_pk_mul_f32 v[120:121], v[124:125], v[120:121]
	v_pk_mul_f32 v[114:115], v[118:119], v[114:115]
	v_pk_mul_f32 v[112:113], v[116:117], v[112:113]
	s_waitcnt lgkmcnt(0)
	v_mul_f32_e32 v158, 0xbfb8aa3b, v155
	v_pk_mul_f32 v[164:165], v[124:125], v[158:159] op_sel_hi:[1,0]
	v_mul_f32_e32 v160, v155, v155
	v_exp_f32_e32 v155, v164
	v_pk_mul_f32 v[162:163], v[126:127], v[158:159] op_sel_hi:[1,0]
	v_exp_f32_e32 v159, v165
	v_exp_f32_e32 v161, v162
	v_exp_f32_e32 v165, v163
	v_add_f32_e32 v155, 1.0, v155
	v_rcp_f32_e32 v162, v155
	v_add_f32_e32 v155, 1.0, v159
	v_rcp_f32_e32 v163, v155
	v_add_f32_e32 v155, 1.0, v161
	v_rcp_f32_e32 v164, v155
	v_add_f32_e32 v155, 1.0, v165
	v_rcp_f32_e32 v165, v155
	v_pk_mul_f32 v[124:125], v[160:161], v[162:163] op_sel_hi:[0,1]
	v_pk_mul_f32 v[120:121], v[120:121], v[124:125]
	v_pk_mul_f32 v[124:125], v[118:119], v[158:159] op_sel_hi:[1,0]
	v_pk_mul_f32 v[126:127], v[160:161], v[164:165] op_sel_hi:[0,1]
	v_pk_mul_f32 v[122:123], v[122:123], v[126:127]
	v_pk_mul_f32 v[126:127], v[116:117], v[158:159] op_sel_hi:[1,0]
	v_exp_f32_e32 v155, v124
	v_exp_f32_e32 v126, v126
	v_exp_f32_e32 v127, v127
	v_exp_f32_e32 v158, v125
	v_lshl_or_b32 v156, s47, 7, v147
	v_add_f32_e32 v124, 1.0, v126
	v_add_f32_e32 v125, 1.0, v127
	v_add_f32_e32 v126, 1.0, v155
	v_add_f32_e32 v127, 1.0, v158
	v_rcp_f32_e32 v124, v124
	v_rcp_f32_e32 v125, v125
	v_rcp_f32_e32 v126, v126
	v_rcp_f32_e32 v127, v127
	v_lshl_add_u32 v151, s20, 8, v144
	v_pk_mul_f32 v[116:117], v[160:161], v[124:125] op_sel_hi:[0,1]
	v_pk_mul_f32 v[112:113], v[112:113], v[116:117]
	v_pk_mul_f32 v[118:119], v[160:161], v[126:127] op_sel_hi:[0,1]
	v_pk_mul_f32 v[114:115], v[114:115], v[118:119]
	v_cvt_pk_bf16_f32 v116, v120, v121
	v_cvt_pk_bf16_f32 v117, v122, v123
	v_cvt_pk_bf16_f32 v118, v112, v113
	v_ashrrev_i32_e32 v157, 31, v156
	v_cvt_pk_bf16_f32 v119, v114, v115
	ds_read_b32 v122, v154 offset:64
	v_mov_b64_e32 v[112:113], s[64:65]
	v_mad_i64_i32 v[120:121], s[22:23], v151, s42, v[112:113]
	v_lshlrev_b64 v[114:115], 1, v[156:157]
	v_lshl_add_u64 v[120:121], v[120:121], 0, v[114:115]
	global_store_dwordx4 v[120:121], v[116:119], off
	v_pk_mul_f32 v[106:107], v[110:111], v[106:107]
	v_pk_mul_f32 v[104:105], v[108:109], v[104:105]
	s_waitcnt lgkmcnt(0)
; __device__ __forceinline__ unsigned cvt_pk_bf16(float lo, float hi) { unsigned r; asm volatile("v_cvt_pk_bf16_f32 %0, %1, %2" : "=v"(r) : "v"(lo), "v"(hi)); return r; }
;     __device__ __forceinline__ void operator()(Acc& acc, const Unit& u, int wr, int wc, int fr, int fq) const { scale(acc, u, wr, wc, fr, fq, PC_GA, true); }
;     __device__ __forceinline__ void operator()(Acc& acc, const Unit& u, int wr, int wc, int fr, int fq) const {
;         const int row0 = u.pm * BM + wr * 64 + fr, col0 = u.pn * 128 + wc * 32 + 8 * fq;
; #pragma unroll
;         for (int ai = 0; ai < 2; ++ai)
; #pragma unroll
;             for (int m = 0; m < 4; ++m) {
;                 const int row = row0 + ai * HALF + m * 16;
;                 const float r = rs[u.idx * BM + wr * 64 + fr + ai * HALF + m * 16];
;                 const float c1 = -r * 1.4426950408889634f, r2 = r * r;
;                 f32x4 o[2];
; #pragma unroll
;                 for (int n = 0; n < 2; ++n) {
;                     const f32x4 g = acc[ai][0][m][n], up = acc[ai][1][m][n];
;                     const f32x4 t = g * c1; f32x4 e;
; #pragma unroll
;                     for (int i = 0; i < 4; ++i) e[i] = __builtin_amdgcn_exp2f(t[i]);
;                     const f32x4 d = e + 1.0f; f32x4 q;
; #pragma unroll
;                     for (int i = 0; i < 4; ++i) q[i] = __builtin_amdgcn_rcpf(d[i]);
;                     o[n] = (g * up) * (q * r2);
;                 }
;                 u32x4 w; w.x = cvt_pk_bf16(o[0][0], o[0][1]); w.y = cvt_pk_bf16(o[0][2], o[0][3]); w.z = cvt_pk_bf16(o[1][0], o[1][1]); w.w = cvt_pk_bf16(o[1][2], o[1][3]);
;                 *(u32x4*)(O + (size_t)row * DFF + col0) = w;
;             }
	v_mul_f32_e32 v116, 0xbfb8aa3b, v122
	v_mul_f32_e32 v118, v122, v122
	v_pk_mul_f32 v[122:123], v[108:109], v[116:117] op_sel_hi:[1,0]
	v_pk_mul_f32 v[120:121], v[110:111], v[116:117] op_sel_hi:[1,0]
	v_exp_f32_e32 v117, v122
	v_exp_f32_e32 v119, v123
	v_exp_f32_e32 v122, v120
	v_exp_f32_e32 v123, v121
	v_add_f32_e32 v117, 1.0, v117
	v_rcp_f32_e32 v120, v117
	v_add_f32_e32 v117, 1.0, v119
	v_rcp_f32_e32 v121, v117
	v_add_f32_e32 v117, 1.0, v122
	v_rcp_f32_e32 v122, v117
	v_add_f32_e32 v117, 1.0, v123
	v_rcp_f32_e32 v123, v117
	v_pk_mul_f32 v[108:109], v[118:119], v[120:121] op_sel_hi:[0,1]
	v_pk_mul_f32 v[104:105], v[104:105], v[108:109]
	v_pk_mul_f32 v[108:109], v[102:103], v[116:117] op_sel_hi:[1,0]
	v_pk_mul_f32 v[110:111], v[118:119], v[122:123] op_sel_hi:[0,1]
	v_pk_mul_f32 v[106:107], v[106:107], v[110:111]
	v_pk_mul_f32 v[110:111], v[100:101], v[116:117] op_sel_hi:[1,0]
	v_exp_f32_e32 v116, v108
	v_exp_f32_e32 v110, v110
	v_exp_f32_e32 v111, v111
	v_exp_f32_e32 v117, v109
	v_pk_mul_f32 v[98:99], v[102:103], v[98:99]
	v_add_f32_e32 v108, 1.0, v110
	v_add_f32_e32 v109, 1.0, v111
	v_add_f32_e32 v110, 1.0, v116
	v_add_f32_e32 v111, 1.0, v117
	v_rcp_f32_e32 v108, v108
	v_rcp_f32_e32 v109, v109
	v_rcp_f32_e32 v110, v110
	v_rcp_f32_e32 v111, v111
	v_pk_mul_f32 v[96:97], v[100:101], v[96:97]
	v_pk_mul_f32 v[100:101], v[118:119], v[108:109] op_sel_hi:[0,1]
	v_pk_mul_f32 v[90:91], v[94:95], v[90:91]
	v_pk_mul_f32 v[102:103], v[118:119], v[110:111] op_sel_hi:[0,1]
	v_pk_mul_f32 v[102:103], v[98:99], v[102:103]
	v_pk_mul_f32 v[98:99], v[96:97], v[100:101]
	v_cvt_pk_bf16_f32 v96, v104, v105
	v_cvt_pk_bf16_f32 v97, v106, v107
	v_or_b32_e32 v100, 16, v151
	v_cvt_pk_bf16_f32 v98, v98, v99
	v_cvt_pk_bf16_f32 v99, v102, v103
	ds_read_b32 v102, v154 offset:128
	v_mad_i64_i32 v[100:101], s[22:23], v100, s42, v[112:113]
	v_lshl_add_u64 v[100:101], v[100:101], 0, v[114:115]
	global_store_dwordx4 v[100:101], v[96:99], off
	v_pk_mul_f32 v[88:89], v[92:93], v[88:89]
	v_pk_mul_f32 v[82:83], v[86:87], v[82:83]
	s_waitcnt lgkmcnt(0)
	v_mul_f32_e32 v96, 0xbfb8aa3b, v102
	v_mul_f32_e32 v98, v102, v102
	v_pk_mul_f32 v[102:103], v[92:93], v[96:97] op_sel_hi:[1,0]
	v_pk_mul_f32 v[100:101], v[94:95], v[96:97] op_sel_hi:[1,0]
	v_exp_f32_e32 v97, v102
	v_exp_f32_e32 v99, v103
	v_exp_f32_e32 v102, v100
	v_exp_f32_e32 v103, v101
	v_add_f32_e32 v97, 1.0, v97
	v_rcp_f32_e32 v100, v97
	v_add_f32_e32 v97, 1.0, v99
	v_rcp_f32_e32 v101, v97
	v_add_f32_e32 v97, 1.0, v102
	v_rcp_f32_e32 v102, v97
	v_add_f32_e32 v97, 1.0, v103
	v_rcp_f32_e32 v103, v97
	v_pk_mul_f32 v[92:93], v[98:99], v[100:101] op_sel_hi:[0,1]
	v_pk_mul_f32 v[88:89], v[88:89], v[92:93]
	v_pk_mul_f32 v[92:93], v[86:87], v[96:97] op_sel_hi:[1,0]
	v_pk_mul_f32 v[94:95], v[98:99], v[102:103] op_sel_hi:[0,1]
	v_pk_mul_f32 v[90:91], v[90:91], v[94:95]
	v_pk_mul_f32 v[94:95], v[84:85], v[96:97] op_sel_hi:[1,0]
	v_exp_f32_e32 v96, v92
	v_exp_f32_e32 v94, v94
	v_exp_f32_e32 v95, v95
	v_exp_f32_e32 v97, v93
	v_pk_mul_f32 v[80:81], v[84:85], v[80:81]
	v_add_f32_e32 v92, 1.0, v94
	v_add_f32_e32 v93, 1.0, v95
	v_add_f32_e32 v94, 1.0, v96
	v_add_f32_e32 v95, 1.0, v97
	v_rcp_f32_e32 v92, v92
	v_rcp_f32_e32 v93, v93
	v_rcp_f32_e32 v94, v94
	v_rcp_f32_e32 v95, v95
	v_pk_mul_f32 v[74:75], v[78:79], v[74:75]
	v_pk_mul_f32 v[84:85], v[98:99], v[92:93] op_sel_hi:[0,1]
	v_pk_mul_f32 v[72:73], v[76:77], v[72:73]
	v_pk_mul_f32 v[86:87], v[98:99], v[94:95] op_sel_hi:[0,1]
	v_pk_mul_f32 v[86:87], v[82:83], v[86:87]
	v_pk_mul_f32 v[82:83], v[80:81], v[84:85]
	v_cvt_pk_bf16_f32 v80, v88, v89
	v_cvt_pk_bf16_f32 v81, v90, v91
	v_or_b32_e32 v84, 32, v151
	v_cvt_pk_bf16_f32 v82, v82, v83
	v_cvt_pk_bf16_f32 v83, v86, v87
	ds_read_b32 v86, v154 offset:192
	v_mad_i64_i32 v[84:85], s[22:23], v84, s42, v[112:113]
	v_lshl_add_u64 v[84:85], v[84:85], 0, v[114:115]
	global_store_dwordx4 v[84:85], v[80:83], off
	v_pk_mul_f32 v[66:67], v[70:71], v[66:67]
	v_pk_mul_f32 v[64:65], v[68:69], v[64:65]
	s_waitcnt lgkmcnt(0)
	v_mul_f32_e32 v80, 0xbfb8aa3b, v86
	v_mul_f32_e32 v82, v86, v86
	v_pk_mul_f32 v[86:87], v[76:77], v[80:81] op_sel_hi:[1,0]
	v_pk_mul_f32 v[84:85], v[78:79], v[80:81] op_sel_hi:[1,0]
	v_exp_f32_e32 v81, v86
	v_exp_f32_e32 v83, v87
	v_exp_f32_e32 v86, v84
	v_exp_f32_e32 v87, v85
	v_add_f32_e32 v81, 1.0, v81
	v_rcp_f32_e32 v84, v81
	v_add_f32_e32 v81, 1.0, v83
	v_rcp_f32_e32 v85, v81
	v_add_f32_e32 v81, 1.0, v86
	v_rcp_f32_e32 v86, v81
	v_add_f32_e32 v81, 1.0, v87
	v_rcp_f32_e32 v87, v81
	v_pk_mul_f32 v[76:77], v[82:83], v[84:85] op_sel_hi:[0,1]
	v_pk_mul_f32 v[72:73], v[72:73], v[76:77]
	v_pk_mul_f32 v[76:77], v[70:71], v[80:81] op_sel_hi:[1,0]
	v_pk_mul_f32 v[78:79], v[82:83], v[86:87] op_sel_hi:[0,1]
	v_pk_mul_f32 v[74:75], v[74:75], v[78:79]
	v_pk_mul_f32 v[78:79], v[68:69], v[80:81] op_sel_hi:[1,0]
	v_exp_f32_e32 v80, v76
	v_exp_f32_e32 v78, v78
	v_exp_f32_e32 v79, v79
	v_exp_f32_e32 v81, v77
	v_pk_mul_f32 v[58:59], v[62:63], v[58:59]
	v_add_f32_e32 v76, 1.0, v78
	v_add_f32_e32 v77, 1.0, v79
	v_add_f32_e32 v78, 1.0, v80
	v_add_f32_e32 v79, 1.0, v81
	v_rcp_f32_e32 v76, v76
	v_rcp_f32_e32 v77, v77
	v_rcp_f32_e32 v78, v78
	v_rcp_f32_e32 v79, v79
	v_pk_mul_f32 v[56:57], v[60:61], v[56:57]
	v_pk_mul_f32 v[68:69], v[82:83], v[76:77] op_sel_hi:[0,1]
	v_pk_mul_f32 v[50:51], v[54:55], v[50:51]
	v_pk_mul_f32 v[70:71], v[82:83], v[78:79] op_sel_hi:[0,1]
	v_pk_mul_f32 v[70:71], v[66:67], v[70:71]
	v_pk_mul_f32 v[66:67], v[64:65], v[68:69]
	v_cvt_pk_bf16_f32 v64, v72, v73
	v_cvt_pk_bf16_f32 v65, v74, v75
	v_or_b32_e32 v68, 48, v151
	v_cvt_pk_bf16_f32 v66, v66, v67
	v_cvt_pk_bf16_f32 v67, v70, v71
	ds_read_b32 v70, v154 offset:512
	v_mad_i64_i32 v[68:69], s[22:23], v68, s42, v[112:113]
	v_lshl_add_u64 v[68:69], v[68:69], 0, v[114:115]
	global_store_dwordx4 v[68:69], v[64:67], off
	v_pk_mul_f32 v[48:49], v[52:53], v[48:49]
	v_pk_mul_f32 v[42:43], v[46:47], v[42:43]
	v_add_u32_e32 v65, 0x80, v151
	s_waitcnt lgkmcnt(0)
; __device__ __forceinline__ unsigned cvt_pk_bf16(float lo, float hi) { unsigned r; asm volatile("v_cvt_pk_bf16_f32 %0, %1, %2" : "=v"(r) : "v"(lo), "v"(hi)); return r; }
;     __device__ __forceinline__ void operator()(Acc& acc, const Unit& u, int wr, int wc, int fr, int fq) const { scale(acc, u, wr, wc, fr, fq, PC_GA, true); }
;     __device__ __forceinline__ void operator()(Acc& acc, const Unit& u, int wr, int wc, int fr, int fq) const {
;         const int row0 = u.pm * BM + wr * 64 + fr, col0 = u.pn * 128 + wc * 32 + 8 * fq;
; #pragma unroll
;         for (int ai = 0; ai < 2; ++ai)
; #pragma unroll
;             for (int m = 0; m < 4; ++m) {
;                 const int row = row0 + ai * HALF + m * 16;
;                 const float r = rs[u.idx * BM + wr * 64 + fr + ai * HALF + m * 16];
;                 const float c1 = -r * 1.4426950408889634f, r2 = r * r;
;                 f32x4 o[2];
; #pragma unroll
;                 for (int n = 0; n < 2; ++n) {
;                     const f32x4 g = acc[ai][0][m][n], up = acc[ai][1][m][n];
;                     const f32x4 t = g * c1; f32x4 e;
; #pragma unroll
;                     for (int i = 0; i < 4; ++i) e[i] = __builtin_amdgcn_exp2f(t[i]);
;                     const f32x4 d = e + 1.0f; f32x4 q;
; #pragma unroll
;                     for (int i = 0; i < 4; ++i) q[i] = __builtin_amdgcn_rcpf(d[i]);
;                     o[n] = (g * up) * (q * r2);
;                 }
;                 u32x4 w; w.x = cvt_pk_bf16(o[0][0], o[0][1]); w.y = cvt_pk_bf16(o[0][2], o[0][3]); w.z = cvt_pk_bf16(o[1][0], o[1][1]); w.w = cvt_pk_bf16(o[1][2], o[1][3]);
;                 *(u32x4*)(O + (size_t)row * DFF + col0) = w;
;             }
	v_mul_f32_e32 v64, 0xbfb8aa3b, v70
	v_mul_f32_e32 v66, v70, v70
	v_pk_mul_f32 v[70:71], v[60:61], v[64:65] op_sel_hi:[1,0]
	v_pk_mul_f32 v[68:69], v[62:63], v[64:65] op_sel_hi:[1,0]
	v_exp_f32_e32 v67, v70
	v_exp_f32_e32 v70, v71
	v_exp_f32_e32 v71, v68
	v_exp_f32_e32 v72, v69
	v_add_f32_e32 v67, 1.0, v67
	v_rcp_f32_e32 v68, v67
	v_add_f32_e32 v67, 1.0, v70
	v_rcp_f32_e32 v69, v67
	v_add_f32_e32 v67, 1.0, v71
	v_rcp_f32_e32 v70, v67
	v_add_f32_e32 v67, 1.0, v72
	v_rcp_f32_e32 v71, v67
	v_pk_mul_f32 v[60:61], v[66:67], v[68:69] op_sel_hi:[0,1]
	v_pk_mul_f32 v[56:57], v[56:57], v[60:61]
	v_pk_mul_f32 v[60:61], v[54:55], v[64:65] op_sel_hi:[1,0]
	v_pk_mul_f32 v[62:63], v[66:67], v[70:71] op_sel_hi:[0,1]
	v_pk_mul_f32 v[58:59], v[58:59], v[62:63]
	v_pk_mul_f32 v[62:63], v[52:53], v[64:65] op_sel_hi:[1,0]
	v_exp_f32_e32 v64, v60
	v_exp_f32_e32 v62, v62
	v_exp_f32_e32 v63, v63
	v_exp_f32_e32 v67, v61
	v_pk_mul_f32 v[40:41], v[44:45], v[40:41]
	v_add_f32_e32 v60, 1.0, v62
	v_add_f32_e32 v61, 1.0, v63
	v_add_f32_e32 v62, 1.0, v64
	v_add_f32_e32 v63, 1.0, v67
	v_rcp_f32_e32 v60, v60
	v_rcp_f32_e32 v61, v61
	v_rcp_f32_e32 v62, v62
	v_rcp_f32_e32 v63, v63
	v_pk_mul_f32 v[34:35], v[38:39], v[34:35]
	v_pk_mul_f32 v[52:53], v[66:67], v[60:61] op_sel_hi:[0,1]
	v_pk_mul_f32 v[32:33], v[36:37], v[32:33]
	v_pk_mul_f32 v[54:55], v[66:67], v[62:63] op_sel_hi:[0,1]
	v_pk_mul_f32 v[54:55], v[50:51], v[54:55]
	v_pk_mul_f32 v[50:51], v[48:49], v[52:53]
	v_cvt_pk_bf16_f32 v48, v56, v57
	v_cvt_pk_bf16_f32 v49, v58, v59
	v_mad_i64_i32 v[52:53], s[22:23], v65, s42, v[112:113]
	v_cvt_pk_bf16_f32 v50, v50, v51
	v_cvt_pk_bf16_f32 v51, v54, v55
	ds_read_b32 v54, v154 offset:576
	v_lshl_add_u64 v[52:53], v[52:53], 0, v[114:115]
	global_store_dwordx4 v[52:53], v[48:51], off
	v_pk_mul_f32 v[26:27], v[30:31], v[26:27]
	v_pk_mul_f32 v[24:25], v[28:29], v[24:25]
	s_waitcnt lgkmcnt(0)
	v_mul_f32_e32 v48, 0xbfb8aa3b, v54
	v_mul_f32_e32 v50, v54, v54
	v_pk_mul_f32 v[54:55], v[44:45], v[48:49] op_sel_hi:[1,0]
	v_pk_mul_f32 v[52:53], v[46:47], v[48:49] op_sel_hi:[1,0]
	v_exp_f32_e32 v49, v54
	v_exp_f32_e32 v51, v55
	v_exp_f32_e32 v54, v52
	v_exp_f32_e32 v55, v53
	v_add_f32_e32 v49, 1.0, v49
	v_rcp_f32_e32 v52, v49
	v_add_f32_e32 v49, 1.0, v51
	v_rcp_f32_e32 v53, v49
	v_add_f32_e32 v49, 1.0, v54
	v_rcp_f32_e32 v54, v49
	v_add_f32_e32 v49, 1.0, v55
	v_rcp_f32_e32 v55, v49
	v_pk_mul_f32 v[44:45], v[50:51], v[52:53] op_sel_hi:[0,1]
	v_pk_mul_f32 v[40:41], v[40:41], v[44:45]
	v_pk_mul_f32 v[44:45], v[38:39], v[48:49] op_sel_hi:[1,0]
	v_pk_mul_f32 v[46:47], v[50:51], v[54:55] op_sel_hi:[0,1]
	v_pk_mul_f32 v[42:43], v[42:43], v[46:47]
	v_pk_mul_f32 v[46:47], v[36:37], v[48:49] op_sel_hi:[1,0]
	v_exp_f32_e32 v48, v44
	v_exp_f32_e32 v46, v46
	v_exp_f32_e32 v47, v47
	v_exp_f32_e32 v49, v45
	v_pk_mul_f32 v[18:19], v[22:23], v[18:19]
	v_add_f32_e32 v44, 1.0, v46
	v_add_f32_e32 v45, 1.0, v47
	v_add_f32_e32 v46, 1.0, v48
	v_add_f32_e32 v47, 1.0, v49
	v_rcp_f32_e32 v44, v44
	v_rcp_f32_e32 v45, v45
	v_rcp_f32_e32 v46, v46
	v_rcp_f32_e32 v47, v47
	v_pk_mul_f32 v[16:17], v[20:21], v[16:17]
	v_pk_mul_f32 v[36:37], v[50:51], v[44:45] op_sel_hi:[0,1]
	v_pk_mul_f32 v[10:11], v[14:15], v[10:11]
	v_pk_mul_f32 v[38:39], v[50:51], v[46:47] op_sel_hi:[0,1]
	v_pk_mul_f32 v[38:39], v[34:35], v[38:39]
	v_pk_mul_f32 v[34:35], v[32:33], v[36:37]
	v_cvt_pk_bf16_f32 v32, v40, v41
	v_cvt_pk_bf16_f32 v33, v42, v43
	v_add_u32_e32 v36, 0x90, v151
	v_cvt_pk_bf16_f32 v34, v34, v35
	v_cvt_pk_bf16_f32 v35, v38, v39
	ds_read_b32 v38, v154 offset:640
	v_mad_i64_i32 v[36:37], s[22:23], v36, s42, v[112:113]
	v_lshl_add_u64 v[36:37], v[36:37], 0, v[114:115]
	global_store_dwordx4 v[36:37], v[32:35], off
	v_pk_mul_f32 v[8:9], v[12:13], v[8:9]
	v_pk_mul_f32 v[2:3], v[6:7], v[2:3]
	s_waitcnt lgkmcnt(0)
; __device__ __forceinline__ unsigned cvt_pk_bf16(float lo, float hi) { unsigned r; asm volatile("v_cvt_pk_bf16_f32 %0, %1, %2" : "=v"(r) : "v"(lo), "v"(hi)); return r; }
;     __device__ __forceinline__ void operator()(Acc& acc, const Unit& u, int wr, int wc, int fr, int fq) const { scale(acc, u, wr, wc, fr, fq, PC_GA, true); }
; #define PG8_WAIT_V(n) asm volatile("s_waitcnt vmcnt(" #n ")" ::: "memory")
; #define PG8_BAR __builtin_amdgcn_s_barrier()
;     __device__ __forceinline__ void operator()(Acc& acc, const Unit& u, int wr, int wc, int fr, int fq) const {
;         const int row0 = u.pm * BM + wr * 64 + fr, col0 = u.pn * 128 + wc * 32 + 8 * fq;
; #pragma unroll
;         for (int ai = 0; ai < 2; ++ai)
; #pragma unroll
;             for (int m = 0; m < 4; ++m) {
;                 const int row = row0 + ai * HALF + m * 16;
;                 const float r = rs[u.idx * BM + wr * 64 + fr + ai * HALF + m * 16];
;                 const float c1 = -r * 1.4426950408889634f, r2 = r * r;
;                 f32x4 o[2];
; #pragma unroll
;                 for (int n = 0; n < 2; ++n) {
;                     const f32x4 g = acc[ai][0][m][n], up = acc[ai][1][m][n];
;                     const f32x4 t = g * c1; f32x4 e;
; #pragma unroll
;                     for (int i = 0; i < 4; ++i) e[i] = __builtin_amdgcn_exp2f(t[i]);
;                     const f32x4 d = e + 1.0f; f32x4 q;
; #pragma unroll
;                     for (int i = 0; i < 4; ++i) q[i] = __builtin_amdgcn_rcpf(d[i]);
;                     o[n] = (g * up) * (q * r2);
;                 }
;                 u32x4 w; w.x = cvt_pk_bf16(o[0][0], o[0][1]); w.y = cvt_pk_bf16(o[0][2], o[0][3]); w.z = cvt_pk_bf16(o[1][0], o[1][1]); w.w = cvt_pk_bf16(o[1][2], o[1][3]);
;                 *(u32x4*)(O + (size_t)row * DFF + col0) = w;
;             }
; template <class Epi, class Sched, bool ALIGN_EPI>
; __device__ __forceinline__ void gemm_phase(LAS unsigned char* lds, const Gemm g, const Sched& S, const Epi& E) {
;     ...
;         cur = nxt; cA = nA; cB = nB; ++ui;
;         if constexpr (ALIGN_EPI) { if (wr == 1) PG8_BAR; }
;     }
;     PG8_WAIT_V(0);
;     if constexpr (!ALIGN_EPI) { if (wr == 0) PG8_BAR; }
;     PG8_BAR;
	v_mul_f32_e32 v32, 0xbfb8aa3b, v38
	v_mul_f32_e32 v34, v38, v38
	v_pk_mul_f32 v[38:39], v[28:29], v[32:33] op_sel_hi:[1,0]
	v_pk_mul_f32 v[36:37], v[30:31], v[32:33] op_sel_hi:[1,0]
	v_exp_f32_e32 v33, v38
	v_exp_f32_e32 v35, v39
	v_exp_f32_e32 v38, v36
	v_exp_f32_e32 v39, v37
	v_add_f32_e32 v33, 1.0, v33
	v_rcp_f32_e32 v36, v33
	v_add_f32_e32 v33, 1.0, v35
	v_rcp_f32_e32 v37, v33
	v_add_f32_e32 v33, 1.0, v38
	v_rcp_f32_e32 v38, v33
	v_add_f32_e32 v33, 1.0, v39
	v_rcp_f32_e32 v39, v33
	v_pk_mul_f32 v[28:29], v[34:35], v[36:37] op_sel_hi:[0,1]
	v_pk_mul_f32 v[24:25], v[24:25], v[28:29]
	v_pk_mul_f32 v[28:29], v[22:23], v[32:33] op_sel_hi:[1,0]
	v_pk_mul_f32 v[30:31], v[34:35], v[38:39] op_sel_hi:[0,1]
	v_pk_mul_f32 v[26:27], v[26:27], v[30:31]
	v_pk_mul_f32 v[30:31], v[20:21], v[32:33] op_sel_hi:[1,0]
	v_exp_f32_e32 v32, v28
	v_exp_f32_e32 v30, v30
	v_exp_f32_e32 v31, v31
	v_exp_f32_e32 v33, v29
	v_pk_mul_f32 v[0:1], v[4:5], v[0:1]
	v_add_f32_e32 v28, 1.0, v30
	v_add_f32_e32 v29, 1.0, v31
	v_add_f32_e32 v30, 1.0, v32
	v_add_f32_e32 v31, 1.0, v33
	v_rcp_f32_e32 v28, v28
	v_rcp_f32_e32 v29, v29
	v_rcp_f32_e32 v30, v30
	v_rcp_f32_e32 v31, v31
	s_andn2_b64 vcc, exec, s[2:3]
	v_pk_mul_f32 v[20:21], v[34:35], v[28:29] op_sel_hi:[0,1]
	s_mov_b64 s[2:3], -1
	v_pk_mul_f32 v[22:23], v[34:35], v[30:31] op_sel_hi:[0,1]
	v_pk_mul_f32 v[22:23], v[18:19], v[22:23]
	v_pk_mul_f32 v[18:19], v[16:17], v[20:21]
	v_cvt_pk_bf16_f32 v16, v24, v25
	v_cvt_pk_bf16_f32 v17, v26, v27
	v_add_u32_e32 v20, 0xa0, v151
	v_cvt_pk_bf16_f32 v18, v18, v19
	v_cvt_pk_bf16_f32 v19, v22, v23
	ds_read_b32 v22, v154 offset:704
	v_mad_i64_i32 v[20:21], s[22:23], v20, s42, v[112:113]
	v_lshl_add_u64 v[20:21], v[20:21], 0, v[114:115]
	global_store_dwordx4 v[20:21], v[16:19], off
	s_waitcnt lgkmcnt(0)
	s_nop 0
	v_mul_f32_e32 v16, 0xbfb8aa3b, v22
	v_mul_f32_e32 v18, v22, v22
	v_pk_mul_f32 v[22:23], v[12:13], v[16:17] op_sel_hi:[1,0]
	v_pk_mul_f32 v[20:21], v[14:15], v[16:17] op_sel_hi:[1,0]
	v_exp_f32_e32 v17, v22
	v_exp_f32_e32 v19, v23
	v_exp_f32_e32 v22, v20
	v_exp_f32_e32 v23, v21
	v_add_f32_e32 v17, 1.0, v17
	v_rcp_f32_e32 v20, v17
	v_add_f32_e32 v17, 1.0, v19
	v_rcp_f32_e32 v21, v17
	v_add_f32_e32 v17, 1.0, v22
	v_rcp_f32_e32 v22, v17
	v_add_f32_e32 v17, 1.0, v23
	v_rcp_f32_e32 v23, v17
	v_pk_mul_f32 v[12:13], v[18:19], v[20:21] op_sel_hi:[0,1]
	v_pk_mul_f32 v[8:9], v[8:9], v[12:13]
	v_pk_mul_f32 v[12:13], v[6:7], v[16:17] op_sel_hi:[1,0]
	v_pk_mul_f32 v[14:15], v[18:19], v[22:23] op_sel_hi:[0,1]
	v_pk_mul_f32 v[10:11], v[10:11], v[14:15]
	v_pk_mul_f32 v[14:15], v[4:5], v[16:17] op_sel_hi:[1,0]
	v_exp_f32_e32 v16, v12
	v_exp_f32_e32 v14, v14
	v_exp_f32_e32 v15, v15
	v_exp_f32_e32 v17, v13
	v_add_f32_e32 v12, 1.0, v14
	v_add_f32_e32 v13, 1.0, v15
	v_add_f32_e32 v14, 1.0, v16
	v_add_f32_e32 v15, 1.0, v17
	v_rcp_f32_e32 v12, v12
	v_rcp_f32_e32 v13, v13
	v_rcp_f32_e32 v14, v14
	v_rcp_f32_e32 v15, v15
	v_pk_mul_f32 v[4:5], v[18:19], v[12:13] op_sel_hi:[0,1]
	v_pk_mul_f32 v[6:7], v[18:19], v[14:15] op_sel_hi:[0,1]
	v_pk_mul_f32 v[6:7], v[2:3], v[6:7]
	v_pk_mul_f32 v[2:3], v[0:1], v[4:5]
	v_add_u32_e32 v4, 0xb0, v151
	v_mad_i64_i32 v[4:5], s[22:23], v4, s42, v[112:113]
	v_lshl_add_u64 v[4:5], v[4:5], 0, v[114:115]
	v_cvt_pk_bf16_f32 v0, v8, v9
	v_cvt_pk_bf16_f32 v1, v10, v11
	v_cvt_pk_bf16_f32 v2, v2, v3
	v_cvt_pk_bf16_f32 v3, v6, v7
	global_store_dwordx4 v[4:5], v[0:3], off
	s_mov_b32 s101, 1
	s_cbranch_vccnz .LBB0_603
	s_andn2_b64 vcc, exec, s[6:7]
	s_cbranch_vccnz .LBB0_602
	s_barrier
	s_branch .LBB0_602
.LBB0_613:
	s_mov_b32 s101, 0
	s_waitcnt vmcnt(0)
	s_barrier

; template <class Epi, class Sched, bool ALIGN_EPI>
; __device__ __forceinline__ void gemm_phase(LAS unsigned char* lds, const Gemm g, const Sched& S, const Epi& E) {
;     ...
;         const bool has_next = S.next(ui + 1, nxt);
;         const char* nA = has_next ? (const char*)g.A + (size_t)nxt.pm * tstepA : cA; const char* nB = has_next ? (const char*)g.Bt + (size_t)nxt.pn * tstepB : cB;
.LBB0_715:
	s_add_u32 s20, s20, 0xb0080
	s_addc_u32 s21, s21, 0
	s_add_u32 s44, s22, 0x100
	v_mov_b32_e32 v0, 0
	s_addc_u32 s45, s23, 0
	s_mov_b32 s47, -2
	s_waitcnt lgkmcnt(0)
	ds_read_b128 v[128:131], v191
	ds_read_b128 v[132:135], v191 offset:1024
	ds_read_b128 v[136:139], v191 offset:2048
	ds_read_b128 v[140:143], v191 offset:3072
	ds_read_b128 v[144:147], v192
	ds_read_b128 v[148:151], v192 offset:1024
	ds_read_b128 v[170:173], v192 offset:2048
	ds_read_b128 v[174:177], v192 offset:3072
	s_add_u32 s22, s20, 0xfff50080
	s_addc_u32 s23, s21, -1
	s_cmp_eq_u32 s47, 40
	s_cselect_b32 s25, s7, s23
	s_cselect_b32 s24, s6, s22
	s_cselect_b32 s23, s19, s45
	s_cselect_b32 s22, s18, s44
	v_lshl_add_u64 v[186:187], s[20:21], 0, v[162:163]
	s_add_i32 m0, s27, 0xc000
	ds_read_b128 v[178:181], v193
	ds_read_b128 v[182:185], v193 offset:1024
	ds_read_b128 v[196:199], v193 offset:2048
	ds_read_b128 v[200:203], v193 offset:3072
	ds_read_b128 v[204:207], v193 offset:4096
	ds_read_b128 v[208:211], v193 offset:5120
	ds_read_b128 v[212:215], v193 offset:6144
	ds_read_b128 v[216:219], v193 offset:7168
	global_load_lds_dwordx4 v[186:187], off
	v_lshl_add_u64 v[186:187], s[20:21], 0, v[164:165]
	s_add_i32 m0, s27, 0xe000
	s_nop 0
	global_load_lds_dwordx4 v[186:187], off
	s_waitcnt vmcnt(8)
	s_waitcnt lgkmcnt(0)
	s_barrier
	s_setprio 1
	s_waitcnt lgkmcnt(0)
	v_mfma_f32_16x16x32_bf16 v[124:127], v[128:131], v[178:181], 0
	v_mfma_f32_16x16x32_bf16 v[120:123], v[136:139], v[178:181], 0
	v_mfma_f32_16x16x32_bf16 v[108:111], v[128:131], v[196:199], 0
	v_mfma_f32_16x16x32_bf16 v[104:107], v[136:139], v[196:199], 0
	v_mfma_f32_16x16x32_bf16 v[92:95], v[128:131], v[204:207], 0
	v_mfma_f32_16x16x32_bf16 v[88:91], v[136:139], v[204:207], 0
	v_mfma_f32_16x16x32_bf16 v[76:79], v[128:131], v[212:215], 0
	v_mfma_f32_16x16x32_bf16 v[72:75], v[136:139], v[212:215], 0
	v_mfma_f32_16x16x32_bf16 v[124:127], v[132:135], v[182:185], v[124:127]
	v_mfma_f32_16x16x32_bf16 v[120:123], v[140:143], v[182:185], v[120:123]
	v_mfma_f32_16x16x32_bf16 v[108:111], v[132:135], v[200:203], v[108:111]
	v_mfma_f32_16x16x32_bf16 v[104:107], v[140:143], v[200:203], v[104:107]
	v_mfma_f32_16x16x32_bf16 v[92:95], v[132:135], v[208:211], v[92:95]
	v_mfma_f32_16x16x32_bf16 v[88:91], v[140:143], v[208:211], v[88:91]
	v_mfma_f32_16x16x32_bf16 v[76:79], v[132:135], v[216:219], v[76:79]
	v_mfma_f32_16x16x32_bf16 v[72:75], v[140:143], v[216:219], v[72:75]
	s_setprio 0
	s_setprio 1
	v_mfma_f32_16x16x32_bf16 v[116:119], v[144:147], v[178:181], 0
	v_mfma_f32_16x16x32_bf16 v[112:115], v[170:173], v[178:181], 0
	v_mfma_f32_16x16x32_bf16 v[100:103], v[144:147], v[196:199], 0
	v_mfma_f32_16x16x32_bf16 v[96:99], v[170:173], v[196:199], 0
	v_mfma_f32_16x16x32_bf16 v[84:87], v[144:147], v[204:207], 0
	v_mfma_f32_16x16x32_bf16 v[80:83], v[170:173], v[204:207], 0
	v_mfma_f32_16x16x32_bf16 v[68:71], v[144:147], v[212:215], 0
	v_mfma_f32_16x16x32_bf16 v[64:67], v[170:173], v[212:215], 0
	v_mfma_f32_16x16x32_bf16 v[116:119], v[148:151], v[182:185], v[116:119]
	v_mfma_f32_16x16x32_bf16 v[112:115], v[174:177], v[182:185], v[112:115]
	v_mfma_f32_16x16x32_bf16 v[100:103], v[148:151], v[200:203], v[100:103]
	v_mfma_f32_16x16x32_bf16 v[96:99], v[174:177], v[200:203], v[96:99]
	v_mfma_f32_16x16x32_bf16 v[84:87], v[148:151], v[208:211], v[84:87]
	v_mfma_f32_16x16x32_bf16 v[80:83], v[174:177], v[208:211], v[80:83]
	v_mfma_f32_16x16x32_bf16 v[68:71], v[148:151], v[216:219], v[68:71]
	v_mfma_f32_16x16x32_bf16 v[64:67], v[174:177], v[216:219], v[64:67]
	s_setprio 0
	s_barrier
	s_add_i32 s48, s38, s26
	v_lshl_add_u64 v[186:187], s[22:23], 0, v[156:157]
	s_mov_b32 m0, s48
	ds_read_b128 v[178:181], v193 offset:16384
	ds_read_b128 v[182:185], v193 offset:17408
	global_load_lds_dwordx4 v[186:187], off
	s_add_i32 m0, s48, 0x2000
	s_add_u32 s48, s22, 0xb0000
	v_lshl_add_u64 v[220:221], s[22:23], 0, v[160:161]
	s_addc_u32 s49, s23, 0
	s_add_i32 s50, s39, s26
	ds_read_b128 v[196:199], v193 offset:18432
	ds_read_b128 v[200:203], v193 offset:19456
	global_load_lds_dwordx4 v[220:221], off
	v_lshl_add_u64 v[222:223], s[48:49], 0, v[156:157]
	s_mov_b32 m0, s50
	v_lshl_add_u64 v[224:225], s[24:25], 0, v[158:159]
	ds_read_b128 v[204:207], v193 offset:20480
	global_load_lds_dwordx4 v[222:223], off
	v_lshl_add_u64 v[222:223], s[48:49], 0, v[160:161]
	s_add_i32 m0, s50, 0x2000
	ds_read_b128 v[208:211], v193 offset:21504
	global_load_lds_dwordx4 v[222:223], off
	v_lshl_add_u64 v[222:223], s[24:25], 0, v[154:155]
	s_mov_b32 m0, s27
	ds_read_b128 v[212:215], v193 offset:22528
	global_load_lds_dwordx4 v[222:223], off
	s_mov_b32 m0, s28
	ds_read_b128 v[216:219], v193 offset:23552
	global_load_lds_dwordx4 v[224:225], off
	s_waitcnt vmcnt(8)
	s_waitcnt lgkmcnt(0)
	s_barrier
	s_setprio 1
	s_waitcnt lgkmcnt(0)
	v_mfma_f32_16x16x32_bf16 v[60:63], v[128:131], v[178:181], 0
	v_mfma_f32_16x16x32_bf16 v[56:59], v[136:139], v[178:181], 0
	v_mfma_f32_16x16x32_bf16 v[44:47], v[128:131], v[196:199], 0
	v_mfma_f32_16x16x32_bf16 v[40:43], v[136:139], v[196:199], 0
	v_mfma_f32_16x16x32_bf16 v[28:31], v[128:131], v[204:207], 0
	v_mfma_f32_16x16x32_bf16 v[24:27], v[136:139], v[204:207], 0
	v_mfma_f32_16x16x32_bf16 v[12:15], v[128:131], v[212:215], 0
	v_mfma_f32_16x16x32_bf16 v[8:11], v[136:139], v[212:215], 0
	v_mfma_f32_16x16x32_bf16 v[60:63], v[132:135], v[182:185], v[60:63]
	v_mfma_f32_16x16x32_bf16 v[56:59], v[140:143], v[182:185], v[56:59]
	v_mfma_f32_16x16x32_bf16 v[44:47], v[132:135], v[200:203], v[44:47]
	v_mfma_f32_16x16x32_bf16 v[40:43], v[140:143], v[200:203], v[40:43]
	v_mfma_f32_16x16x32_bf16 v[28:31], v[132:135], v[208:211], v[28:31]
	v_mfma_f32_16x16x32_bf16 v[24:27], v[140:143], v[208:211], v[24:27]
	v_mfma_f32_16x16x32_bf16 v[12:15], v[132:135], v[216:219], v[12:15]
	v_mfma_f32_16x16x32_bf16 v[8:11], v[140:143], v[216:219], v[8:11]
	s_setprio 0
	s_setprio 1
	v_mfma_f32_16x16x32_bf16 v[52:55], v[144:147], v[178:181], 0
	v_mfma_f32_16x16x32_bf16 v[48:51], v[170:173], v[178:181], 0
	v_mfma_f32_16x16x32_bf16 v[36:39], v[144:147], v[196:199], 0
	v_mfma_f32_16x16x32_bf16 v[32:35], v[170:173], v[196:199], 0
	v_mfma_f32_16x16x32_bf16 v[20:23], v[144:147], v[204:207], 0
	v_mfma_f32_16x16x32_bf16 v[16:19], v[170:173], v[204:207], 0
	v_mfma_f32_16x16x32_bf16 v[4:7], v[144:147], v[212:215], 0
	v_mfma_f32_16x16x32_bf16 v[0:3], v[170:173], v[212:215], 0
	v_mfma_f32_16x16x32_bf16 v[52:55], v[148:151], v[182:185], v[52:55]
	v_mfma_f32_16x16x32_bf16 v[48:51], v[174:177], v[182:185], v[48:51]
	v_mfma_f32_16x16x32_bf16 v[36:39], v[148:151], v[200:203], v[36:39]
	v_mfma_f32_16x16x32_bf16 v[32:35], v[174:177], v[200:203], v[32:35]
	v_mfma_f32_16x16x32_bf16 v[20:23], v[148:151], v[208:211], v[20:23]
	v_mfma_f32_16x16x32_bf16 v[16:19], v[174:177], v[208:211], v[16:19]
	v_mfma_f32_16x16x32_bf16 v[4:7], v[148:151], v[216:219], v[4:7]
	v_mfma_f32_16x16x32_bf16 v[0:3], v[174:177], v[216:219], v[0:3]
	s_setprio 0
	s_barrier
	s_branch .Lpk716_seg3

.Lpk716_seg3:
	s_add_i32 s48, 0, 0x18000
	s_add_i32 s49, 0, 0x1c000
	v_add_u32_e32 v140, s48, v189
	v_add_u32_e32 v174, s49, v189
	ds_read_b128 v[128:131], v140
	ds_read_b128 v[132:135], v140 offset:1024
	ds_read_b128 v[136:139], v140 offset:2048
	ds_read_b128 v[140:143], v140 offset:3072
	ds_read_b128 v[144:147], v174
	ds_read_b128 v[148:151], v174 offset:1024
	ds_read_b128 v[170:173], v174 offset:2048
	ds_read_b128 v[174:177], v174 offset:3072
	s_add_u32 s24, s24, 0xb0000
	s_addc_u32 s25, s25, 0
	s_mov_b32 m0, s29
	v_lshl_add_u64 v[226:227], s[24:25], 0, v[154:155]
	ds_read_b128 v[178:181], v193 offset:32768
	ds_read_b128 v[182:185], v193 offset:33792
	ds_read_b128 v[196:199], v193 offset:34816
	ds_read_b128 v[200:203], v193 offset:35840
	ds_read_b128 v[204:207], v193 offset:36864
	ds_read_b128 v[208:211], v193 offset:37888
	ds_read_b128 v[212:215], v193 offset:38912
	ds_read_b128 v[216:219], v193 offset:39936
	global_load_lds_dwordx4 v[226:227], off
	v_lshl_add_u64 v[226:227], s[24:25], 0, v[158:159]
	s_mov_b32 m0, s30
	s_nop 0
	global_load_lds_dwordx4 v[226:227], off
	s_waitcnt vmcnt(8)
	s_waitcnt lgkmcnt(0)
	s_barrier
	s_setprio 1
	s_waitcnt lgkmcnt(0)
	v_mfma_f32_16x16x32_bf16 v[124:127], v[128:131], v[178:181], v[124:127]
	v_mfma_f32_16x16x32_bf16 v[120:123], v[136:139], v[178:181], v[120:123]
	v_mfma_f32_16x16x32_bf16 v[108:111], v[128:131], v[196:199], v[108:111]
	v_mfma_f32_16x16x32_bf16 v[104:107], v[136:139], v[196:199], v[104:107]
	v_mfma_f32_16x16x32_bf16 v[92:95], v[128:131], v[204:207], v[92:95]
	v_mfma_f32_16x16x32_bf16 v[88:91], v[136:139], v[204:207], v[88:91]
	v_mfma_f32_16x16x32_bf16 v[76:79], v[128:131], v[212:215], v[76:79]
	v_mfma_f32_16x16x32_bf16 v[72:75], v[136:139], v[212:215], v[72:75]
	v_mfma_f32_16x16x32_bf16 v[124:127], v[132:135], v[182:185], v[124:127]
	v_mfma_f32_16x16x32_bf16 v[120:123], v[140:143], v[182:185], v[120:123]
	v_mfma_f32_16x16x32_bf16 v[108:111], v[132:135], v[200:203], v[108:111]
	v_mfma_f32_16x16x32_bf16 v[104:107], v[140:143], v[200:203], v[104:107]
	v_mfma_f32_16x16x32_bf16 v[92:95], v[132:135], v[208:211], v[92:95]
	v_mfma_f32_16x16x32_bf16 v[88:91], v[140:143], v[208:211], v[88:91]
	v_mfma_f32_16x16x32_bf16 v[76:79], v[132:135], v[216:219], v[76:79]
	v_mfma_f32_16x16x32_bf16 v[72:75], v[140:143], v[216:219], v[72:75]
	s_setprio 0
	s_setprio 1
	v_mfma_f32_16x16x32_bf16 v[116:119], v[144:147], v[178:181], v[116:119]
	v_mfma_f32_16x16x32_bf16 v[112:115], v[170:173], v[178:181], v[112:115]
	v_mfma_f32_16x16x32_bf16 v[100:103], v[144:147], v[196:199], v[100:103]
	v_mfma_f32_16x16x32_bf16 v[96:99], v[170:173], v[196:199], v[96:99]
	v_mfma_f32_16x16x32_bf16 v[84:87], v[144:147], v[204:207], v[84:87]
	v_mfma_f32_16x16x32_bf16 v[80:83], v[170:173], v[204:207], v[80:83]
	v_mfma_f32_16x16x32_bf16 v[68:71], v[144:147], v[212:215], v[68:71]
	v_mfma_f32_16x16x32_bf16 v[64:67], v[170:173], v[212:215], v[64:67]
	v_mfma_f32_16x16x32_bf16 v[116:119], v[148:151], v[182:185], v[116:119]
	v_mfma_f32_16x16x32_bf16 v[112:115], v[174:177], v[182:185], v[112:115]
	v_mfma_f32_16x16x32_bf16 v[100:103], v[148:151], v[200:203], v[100:103]
	v_mfma_f32_16x16x32_bf16 v[96:99], v[174:177], v[200:203], v[96:99]
	v_mfma_f32_16x16x32_bf16 v[84:87], v[148:151], v[208:211], v[84:87]
	v_mfma_f32_16x16x32_bf16 v[80:83], v[174:177], v[208:211], v[80:83]
	v_mfma_f32_16x16x32_bf16 v[68:71], v[148:151], v[216:219], v[68:71]
	v_mfma_f32_16x16x32_bf16 v[64:67], v[174:177], v[216:219], v[64:67]
	s_setprio 0
	s_barrier
; #define PG8_BAR __builtin_amdgcn_s_barrier()
; template <class Epi, class Sched, bool ALIGN_EPI>
; __device__ __forceinline__ void gemm_phase(LAS unsigned char* lds, const Gemm g, const Sched& S, const Epi& E) {
;     ...
;         if constexpr (ALIGN_EPI) { if (wr == 0) PG8_BAR; }
	s_add_i32 s24, s48, s26
	v_lshl_add_u64 v[186:187], v[186:187], 0, s[14:15]
	s_mov_b32 m0, s24
	ds_read_b128 v[178:181], v193 offset:49152
	ds_read_b128 v[182:185], v193 offset:50176
	global_load_lds_dwordx4 v[186:187], off
	s_add_i32 m0, s24, 0x2000
	s_add_u32 s22, s22, 0xb0080
	v_lshl_add_u64 v[186:187], v[220:221], 0, s[14:15]
	s_addc_u32 s23, s23, 0
	s_add_i32 s24, s49, s26
	ds_read_b128 v[196:199], v193 offset:51200
	ds_read_b128 v[200:203], v193 offset:52224
	global_load_lds_dwordx4 v[186:187], off
	v_lshl_add_u64 v[186:187], s[22:23], 0, v[156:157]
	s_mov_b32 m0, s24
	ds_read_b128 v[204:207], v193 offset:53248
	global_load_lds_dwordx4 v[186:187], off
	v_lshl_add_u64 v[186:187], s[22:23], 0, v[160:161]
	s_add_i32 m0, s24, 0x2000
	ds_read_b128 v[208:211], v193 offset:54272
	global_load_lds_dwordx4 v[186:187], off
	v_lshl_add_u64 v[186:187], v[222:223], 0, s[14:15]
	s_mov_b32 m0, s33
	ds_read_b128 v[212:215], v193 offset:55296
	global_load_lds_dwordx4 v[186:187], off
	v_lshl_add_u64 v[186:187], v[224:225], 0, s[14:15]
	s_mov_b32 m0, s34
	ds_read_b128 v[216:219], v193 offset:56320
	global_load_lds_dwordx4 v[186:187], off
	s_waitcnt vmcnt(8)
	s_waitcnt lgkmcnt(0)
	s_barrier
	s_setprio 1
	s_waitcnt lgkmcnt(0)
	v_mfma_f32_16x16x32_bf16 v[60:63], v[128:131], v[178:181], v[60:63]
	v_mfma_f32_16x16x32_bf16 v[56:59], v[136:139], v[178:181], v[56:59]
	v_mfma_f32_16x16x32_bf16 v[44:47], v[128:131], v[196:199], v[44:47]
	v_mfma_f32_16x16x32_bf16 v[40:43], v[136:139], v[196:199], v[40:43]
	v_mfma_f32_16x16x32_bf16 v[28:31], v[128:131], v[204:207], v[28:31]
	v_mfma_f32_16x16x32_bf16 v[24:27], v[136:139], v[204:207], v[24:27]
	v_mfma_f32_16x16x32_bf16 v[12:15], v[128:131], v[212:215], v[12:15]
	v_mfma_f32_16x16x32_bf16 v[8:11], v[136:139], v[212:215], v[8:11]
	v_mfma_f32_16x16x32_bf16 v[60:63], v[132:135], v[182:185], v[60:63]
	v_mfma_f32_16x16x32_bf16 v[56:59], v[140:143], v[182:185], v[56:59]
	v_mfma_f32_16x16x32_bf16 v[44:47], v[132:135], v[200:203], v[44:47]
	v_mfma_f32_16x16x32_bf16 v[40:43], v[140:143], v[200:203], v[40:43]
	v_mfma_f32_16x16x32_bf16 v[28:31], v[132:135], v[208:211], v[28:31]
	v_mfma_f32_16x16x32_bf16 v[24:27], v[140:143], v[208:211], v[24:27]
	v_mfma_f32_16x16x32_bf16 v[12:15], v[132:135], v[216:219], v[12:15]
	v_mfma_f32_16x16x32_bf16 v[8:11], v[140:143], v[216:219], v[8:11]
	s_setprio 0
	s_setprio 1
	v_mfma_f32_16x16x32_bf16 v[52:55], v[144:147], v[178:181], v[52:55]
	v_mfma_f32_16x16x32_bf16 v[48:51], v[170:173], v[178:181], v[48:51]
	v_mfma_f32_16x16x32_bf16 v[36:39], v[144:147], v[196:199], v[36:39]
	v_mfma_f32_16x16x32_bf16 v[32:35], v[170:173], v[196:199], v[32:35]
	v_mfma_f32_16x16x32_bf16 v[20:23], v[144:147], v[204:207], v[20:23]
	v_mfma_f32_16x16x32_bf16 v[16:19], v[170:173], v[204:207], v[16:19]
	v_mfma_f32_16x16x32_bf16 v[4:7], v[144:147], v[212:215], v[4:7]
	v_mfma_f32_16x16x32_bf16 v[0:3], v[170:173], v[212:215], v[0:3]
	v_mfma_f32_16x16x32_bf16 v[52:55], v[148:151], v[182:185], v[52:55]
	v_mfma_f32_16x16x32_bf16 v[48:51], v[174:177], v[182:185], v[48:51]
	v_mfma_f32_16x16x32_bf16 v[36:39], v[148:151], v[200:203], v[36:39]
	v_mfma_f32_16x16x32_bf16 v[32:35], v[174:177], v[200:203], v[32:35]
	v_mfma_f32_16x16x32_bf16 v[20:23], v[148:151], v[208:211], v[20:23]
	v_mfma_f32_16x16x32_bf16 v[16:19], v[174:177], v[208:211], v[16:19]
	v_mfma_f32_16x16x32_bf16 v[4:7], v[148:151], v[216:219], v[4:7]
	v_mfma_f32_16x16x32_bf16 v[0:3], v[174:177], v[216:219], v[0:3]
	s_setprio 0
	s_barrier
	s_add_i32 s47, s47, 2
	s_add_u32 s20, s20, 0x100
	s_addc_u32 s21, s21, 0
	s_add_u32 s44, s44, 0x100
	s_addc_u32 s45, s45, 0
	s_cmp_gt_u32 s47, 41
	s_cbranch_scc0 .LBB0_716
	s_and_b64 vcc, exec, s[16:17]
	s_cbranch_vccz .LBB0_719
	s_barrier

; template <class Epi, class Sched, bool ALIGN_EPI>
; __device__ __forceinline__ void gemm_phase(LAS unsigned char* lds, const Gemm g, const Sched& S, const Epi& E) {
;     ...
;         const bool has_next = S.next(ui + 1, nxt);
;         const char* nA = has_next ? (const char*)g.A + (size_t)nxt.pm * tstepA : cA; const char* nB = has_next ? (const char*)g.Bt + (size_t)nxt.pn * tstepB : cB;
.LBB0_873:
	s_ashr_i32 s21, s20, 31
	s_lshl_b64 s[22:23], s[20:21], 19
	s_add_u32 s22, s34, s22
	s_addc_u32 s23, s35, s23
	s_and_b64 s[24:25], s[4:5], exec
	s_cselect_b32 s21, s23, s27
	s_cselect_b32 s50, s22, s26
	s_ashr_i32 s19, s18, 31
	s_lshl_b64 s[24:25], s[18:19], 19
	s_add_u32 s24, s36, s24
	s_addc_u32 s25, s37, s25
	s_and_b64 s[30:31], s[4:5], exec
	s_cselect_b32 s19, s25, s29
	s_cselect_b32 s51, s24, s28
	s_add_u32 s26, s26, 0x40080
	s_addc_u32 s27, s27, 0
	s_add_u32 s52, s28, 0x100
	v_mov_b32_e32 v8, 0
	s_addc_u32 s53, s29, 0
	s_mov_b32 s66, -2
	s_waitcnt lgkmcnt(0)
	ds_read_b128 v[146:149], v158
	ds_read_b128 v[162:165], v158 offset:1024
	ds_read_b128 v[166:169], v158 offset:2048
	ds_read_b128 v[170:173], v158 offset:3072
	ds_read_b128 v[174:177], v159
	ds_read_b128 v[178:181], v159 offset:1024
	ds_read_b128 v[182:185], v159 offset:2048
	ds_read_b128 v[186:189], v159 offset:3072
	s_add_u32 s28, s26, 0xfffc0080
	s_addc_u32 s29, s27, -1
	s_cmp_eq_u32 s66, 12
	s_cselect_b32 s31, s21, s29
	s_cselect_b32 s30, s50, s28
	s_cselect_b32 s29, s19, s53
	s_cselect_b32 s28, s51, s52
	v_lshl_add_u64 v[222:223], s[26:27], 0, v[138:139]
	s_add_i32 m0, s9, 0xc000
	ds_read_b128 v[190:193], v160
	ds_read_b128 v[194:197], v160 offset:1024
	ds_read_b128 v[198:201], v160 offset:2048
	ds_read_b128 v[202:205], v160 offset:3072
	ds_read_b128 v[206:209], v160 offset:4096
	ds_read_b128 v[210:213], v160 offset:5120
	ds_read_b128 v[214:217], v160 offset:6144
	ds_read_b128 v[218:221], v160 offset:7168
	global_load_lds_dwordx4 v[222:223], off
	v_lshl_add_u64 v[222:223], s[26:27], 0, v[140:141]
	s_add_i32 m0, s9, 0xe000
	s_nop 0
	global_load_lds_dwordx4 v[222:223], off
	s_waitcnt vmcnt(8)
	s_waitcnt lgkmcnt(0)
	s_barrier
	s_setprio 1
	s_waitcnt lgkmcnt(0)
	v_mfma_f32_16x16x32_bf16 v[116:119], v[146:149], v[190:193], 0
	v_mfma_f32_16x16x32_bf16 v[112:115], v[166:169], v[190:193], 0
	v_mfma_f32_16x16x32_bf16 v[100:103], v[146:149], v[198:201], 0
	v_mfma_f32_16x16x32_bf16 v[96:99], v[166:169], v[198:201], 0
	v_mfma_f32_16x16x32_bf16 v[84:87], v[146:149], v[206:209], 0
	v_mfma_f32_16x16x32_bf16 v[80:83], v[166:169], v[206:209], 0
	v_mfma_f32_16x16x32_bf16 v[68:71], v[146:149], v[214:217], 0
	v_mfma_f32_16x16x32_bf16 v[64:67], v[166:169], v[214:217], 0
	v_mfma_f32_16x16x32_bf16 v[116:119], v[162:165], v[194:197], v[116:119]
	v_mfma_f32_16x16x32_bf16 v[112:115], v[170:173], v[194:197], v[112:115]
	v_mfma_f32_16x16x32_bf16 v[100:103], v[162:165], v[202:205], v[100:103]
	v_mfma_f32_16x16x32_bf16 v[96:99], v[170:173], v[202:205], v[96:99]
	v_mfma_f32_16x16x32_bf16 v[84:87], v[162:165], v[210:213], v[84:87]
	v_mfma_f32_16x16x32_bf16 v[80:83], v[170:173], v[210:213], v[80:83]
	v_mfma_f32_16x16x32_bf16 v[68:71], v[162:165], v[218:221], v[68:71]
	v_mfma_f32_16x16x32_bf16 v[64:67], v[170:173], v[218:221], v[64:67]
	s_setprio 0
	s_setprio 1
	v_mfma_f32_16x16x32_bf16 v[124:127], v[174:177], v[190:193], 0
	v_mfma_f32_16x16x32_bf16 v[120:123], v[182:185], v[190:193], 0
	v_mfma_f32_16x16x32_bf16 v[108:111], v[174:177], v[198:201], 0
	v_mfma_f32_16x16x32_bf16 v[104:107], v[182:185], v[198:201], 0
	v_mfma_f32_16x16x32_bf16 v[92:95], v[174:177], v[206:209], 0
	v_mfma_f32_16x16x32_bf16 v[88:91], v[182:185], v[206:209], 0
	v_mfma_f32_16x16x32_bf16 v[76:79], v[174:177], v[214:217], 0
	v_mfma_f32_16x16x32_bf16 v[72:75], v[182:185], v[214:217], 0
	v_mfma_f32_16x16x32_bf16 v[124:127], v[178:181], v[194:197], v[124:127]
	v_mfma_f32_16x16x32_bf16 v[120:123], v[186:189], v[194:197], v[120:123]
	v_mfma_f32_16x16x32_bf16 v[108:111], v[178:181], v[202:205], v[108:111]
	v_mfma_f32_16x16x32_bf16 v[104:107], v[186:189], v[202:205], v[104:107]
	v_mfma_f32_16x16x32_bf16 v[92:95], v[178:181], v[210:213], v[92:95]
	v_mfma_f32_16x16x32_bf16 v[88:91], v[186:189], v[210:213], v[88:91]
	v_mfma_f32_16x16x32_bf16 v[76:79], v[178:181], v[218:221], v[76:79]
	v_mfma_f32_16x16x32_bf16 v[72:75], v[186:189], v[218:221], v[72:75]
	s_setprio 0
	s_barrier
	s_add_i32 s54, s44, s33
	v_lshl_add_u64 v[222:223], s[28:29], 0, v[130:131]
	s_mov_b32 m0, s54
	ds_read_b128 v[190:193], v160 offset:16384
	ds_read_b128 v[194:197], v160 offset:17408
	global_load_lds_dwordx4 v[222:223], off
	s_add_i32 m0, s54, 0x2000
	s_add_u32 s70, s28, 0x40000
	v_lshl_add_u64 v[224:225], s[28:29], 0, v[134:135]
	s_addc_u32 s71, s29, 0
	s_add_i32 s54, s45, s33
	ds_read_b128 v[198:201], v160 offset:18432
	ds_read_b128 v[202:205], v160 offset:19456
	global_load_lds_dwordx4 v[224:225], off
	v_lshl_add_u64 v[226:227], s[70:71], 0, v[130:131]
	s_mov_b32 m0, s54
	v_lshl_add_u64 v[228:229], s[30:31], 0, v[132:133]
	ds_read_b128 v[206:209], v160 offset:20480
	global_load_lds_dwordx4 v[226:227], off
	v_lshl_add_u64 v[226:227], s[70:71], 0, v[134:135]
	s_add_i32 m0, s54, 0x2000
	ds_read_b128 v[210:213], v160 offset:21504
	global_load_lds_dwordx4 v[226:227], off
	v_lshl_add_u64 v[226:227], s[30:31], 0, v[128:129]
	s_mov_b32 m0, s9
	ds_read_b128 v[214:217], v160 offset:22528
	global_load_lds_dwordx4 v[226:227], off
	s_mov_b32 m0, s38
	ds_read_b128 v[218:221], v160 offset:23552
	global_load_lds_dwordx4 v[228:229], off
	s_waitcnt vmcnt(8)
	s_waitcnt lgkmcnt(0)
	s_barrier
	s_setprio 1
	s_waitcnt lgkmcnt(0)
	v_mfma_f32_16x16x32_bf16 v[52:55], v[146:149], v[190:193], 0
	v_mfma_f32_16x16x32_bf16 v[48:51], v[166:169], v[190:193], 0
	v_mfma_f32_16x16x32_bf16 v[36:39], v[146:149], v[198:201], 0
	v_mfma_f32_16x16x32_bf16 v[32:35], v[166:169], v[198:201], 0
	v_mfma_f32_16x16x32_bf16 v[20:23], v[146:149], v[206:209], 0
	v_mfma_f32_16x16x32_bf16 v[16:19], v[166:169], v[206:209], 0
	v_mfma_f32_16x16x32_bf16 v[4:7], v[146:149], v[214:217], 0
	v_mfma_f32_16x16x32_bf16 v[0:3], v[166:169], v[214:217], 0
	v_mfma_f32_16x16x32_bf16 v[52:55], v[162:165], v[194:197], v[52:55]
	v_mfma_f32_16x16x32_bf16 v[48:51], v[170:173], v[194:197], v[48:51]
	v_mfma_f32_16x16x32_bf16 v[36:39], v[162:165], v[202:205], v[36:39]
	v_mfma_f32_16x16x32_bf16 v[32:35], v[170:173], v[202:205], v[32:35]
	v_mfma_f32_16x16x32_bf16 v[20:23], v[162:165], v[210:213], v[20:23]
	v_mfma_f32_16x16x32_bf16 v[16:19], v[170:173], v[210:213], v[16:19]
	v_mfma_f32_16x16x32_bf16 v[4:7], v[162:165], v[218:221], v[4:7]
	v_mfma_f32_16x16x32_bf16 v[0:3], v[170:173], v[218:221], v[0:3]
	s_setprio 0
	s_setprio 1
	v_mfma_f32_16x16x32_bf16 v[60:63], v[174:177], v[190:193], 0
	v_mfma_f32_16x16x32_bf16 v[56:59], v[182:185], v[190:193], 0
	v_mfma_f32_16x16x32_bf16 v[44:47], v[174:177], v[198:201], 0
	v_mfma_f32_16x16x32_bf16 v[40:43], v[182:185], v[198:201], 0
	v_mfma_f32_16x16x32_bf16 v[28:31], v[174:177], v[206:209], 0
	v_mfma_f32_16x16x32_bf16 v[24:27], v[182:185], v[206:209], 0
	v_mfma_f32_16x16x32_bf16 v[12:15], v[174:177], v[214:217], 0
	v_mfma_f32_16x16x32_bf16 v[8:11], v[182:185], v[214:217], 0
	v_mfma_f32_16x16x32_bf16 v[60:63], v[178:181], v[194:197], v[60:63]
	v_mfma_f32_16x16x32_bf16 v[56:59], v[186:189], v[194:197], v[56:59]
	v_mfma_f32_16x16x32_bf16 v[44:47], v[178:181], v[202:205], v[44:47]
	v_mfma_f32_16x16x32_bf16 v[40:43], v[186:189], v[202:205], v[40:43]
	v_mfma_f32_16x16x32_bf16 v[28:31], v[178:181], v[210:213], v[28:31]
	v_mfma_f32_16x16x32_bf16 v[24:27], v[186:189], v[210:213], v[24:27]
	v_mfma_f32_16x16x32_bf16 v[12:15], v[178:181], v[218:221], v[12:15]
	v_mfma_f32_16x16x32_bf16 v[8:11], v[186:189], v[218:221], v[8:11]
	s_setprio 0
	s_barrier
	s_branch .Lpk874_seg3

.Lpk874_seg3:
	s_add_i32 s54, 0, 0x18000
	v_add_u32_e32 v136, s54, v154
	s_add_i32 s55, 0, 0x1c000
	ds_read_b128 v[146:149], v136
	ds_read_b128 v[162:165], v136 offset:1024
	ds_read_b128 v[166:169], v136 offset:2048
	ds_read_b128 v[170:173], v136 offset:3072
	v_add_u32_e32 v136, s55, v154
	ds_read_b128 v[174:177], v136
	ds_read_b128 v[178:181], v136 offset:1024
	ds_read_b128 v[182:185], v136 offset:2048
	ds_read_b128 v[186:189], v136 offset:3072
	s_add_u32 s30, s30, 0x40000
	s_addc_u32 s31, s31, 0
	s_mov_b32 m0, s39
	v_lshl_add_u64 v[230:231], s[30:31], 0, v[128:129]
	ds_read_b128 v[190:193], v160 offset:32768
	ds_read_b128 v[194:197], v160 offset:33792
	ds_read_b128 v[198:201], v160 offset:34816
	ds_read_b128 v[202:205], v160 offset:35840
	ds_read_b128 v[206:209], v160 offset:36864
	ds_read_b128 v[210:213], v160 offset:37888
	ds_read_b128 v[214:217], v160 offset:38912
	ds_read_b128 v[218:221], v160 offset:39936
	global_load_lds_dwordx4 v[230:231], off
	v_lshl_add_u64 v[230:231], s[30:31], 0, v[132:133]
	s_mov_b32 m0, s40
	s_nop 0
	global_load_lds_dwordx4 v[230:231], off
	s_waitcnt vmcnt(8)
	s_waitcnt lgkmcnt(0)
	s_barrier
	s_setprio 1
	s_waitcnt lgkmcnt(0)
	v_mfma_f32_16x16x32_bf16 v[116:119], v[146:149], v[190:193], v[116:119]
	v_mfma_f32_16x16x32_bf16 v[112:115], v[166:169], v[190:193], v[112:115]
	v_mfma_f32_16x16x32_bf16 v[100:103], v[146:149], v[198:201], v[100:103]
	v_mfma_f32_16x16x32_bf16 v[96:99], v[166:169], v[198:201], v[96:99]
	v_mfma_f32_16x16x32_bf16 v[84:87], v[146:149], v[206:209], v[84:87]
	v_mfma_f32_16x16x32_bf16 v[80:83], v[166:169], v[206:209], v[80:83]
	v_mfma_f32_16x16x32_bf16 v[68:71], v[146:149], v[214:217], v[68:71]
	v_mfma_f32_16x16x32_bf16 v[64:67], v[166:169], v[214:217], v[64:67]
	v_mfma_f32_16x16x32_bf16 v[116:119], v[162:165], v[194:197], v[116:119]
	v_mfma_f32_16x16x32_bf16 v[112:115], v[170:173], v[194:197], v[112:115]
	v_mfma_f32_16x16x32_bf16 v[100:103], v[162:165], v[202:205], v[100:103]
	v_mfma_f32_16x16x32_bf16 v[96:99], v[170:173], v[202:205], v[96:99]
	v_mfma_f32_16x16x32_bf16 v[84:87], v[162:165], v[210:213], v[84:87]
	v_mfma_f32_16x16x32_bf16 v[80:83], v[170:173], v[210:213], v[80:83]
	v_mfma_f32_16x16x32_bf16 v[68:71], v[162:165], v[218:221], v[68:71]
	v_mfma_f32_16x16x32_bf16 v[64:67], v[170:173], v[218:221], v[64:67]
	s_setprio 0
	s_setprio 1
	v_mfma_f32_16x16x32_bf16 v[124:127], v[174:177], v[190:193], v[124:127]
	v_mfma_f32_16x16x32_bf16 v[120:123], v[182:185], v[190:193], v[120:123]
	v_mfma_f32_16x16x32_bf16 v[108:111], v[174:177], v[198:201], v[108:111]
	v_mfma_f32_16x16x32_bf16 v[104:107], v[182:185], v[198:201], v[104:107]
	v_mfma_f32_16x16x32_bf16 v[92:95], v[174:177], v[206:209], v[92:95]
	v_mfma_f32_16x16x32_bf16 v[88:91], v[182:185], v[206:209], v[88:91]
	v_mfma_f32_16x16x32_bf16 v[76:79], v[174:177], v[214:217], v[76:79]
	v_mfma_f32_16x16x32_bf16 v[72:75], v[182:185], v[214:217], v[72:75]
	v_mfma_f32_16x16x32_bf16 v[124:127], v[178:181], v[194:197], v[124:127]
	v_mfma_f32_16x16x32_bf16 v[120:123], v[186:189], v[194:197], v[120:123]
	v_mfma_f32_16x16x32_bf16 v[108:111], v[178:181], v[202:205], v[108:111]
	v_mfma_f32_16x16x32_bf16 v[104:107], v[186:189], v[202:205], v[104:107]
	v_mfma_f32_16x16x32_bf16 v[92:95], v[178:181], v[210:213], v[92:95]
	v_mfma_f32_16x16x32_bf16 v[88:91], v[186:189], v[210:213], v[88:91]
	v_mfma_f32_16x16x32_bf16 v[76:79], v[178:181], v[218:221], v[76:79]
	v_mfma_f32_16x16x32_bf16 v[72:75], v[186:189], v[218:221], v[72:75]
	s_setprio 0
	s_barrier
; #define PG8_BAR __builtin_amdgcn_s_barrier()
; template <class Epi, class Sched, bool ALIGN_EPI>
; __device__ __forceinline__ void gemm_phase(LAS unsigned char* lds, const Gemm g, const Sched& S, const Epi& E) {
;     ...
;         if constexpr (ALIGN_EPI) { if (wr == 0) PG8_BAR; }
	s_add_i32 s30, s54, s33
	v_lshl_add_u64 v[222:223], v[222:223], 0, s[14:15]
	s_mov_b32 m0, s30
	ds_read_b128 v[190:193], v160 offset:49152
	ds_read_b128 v[194:197], v160 offset:50176
	global_load_lds_dwordx4 v[222:223], off
	s_add_i32 m0, s30, 0x2000
	s_add_u32 s28, s28, 0x40080
	v_lshl_add_u64 v[222:223], v[224:225], 0, s[14:15]
	s_addc_u32 s29, s29, 0
	s_add_i32 s30, s55, s33
	ds_read_b128 v[198:201], v160 offset:51200
	ds_read_b128 v[202:205], v160 offset:52224
	global_load_lds_dwordx4 v[222:223], off
	v_lshl_add_u64 v[222:223], s[28:29], 0, v[130:131]
	s_mov_b32 m0, s30
	ds_read_b128 v[206:209], v160 offset:53248
	global_load_lds_dwordx4 v[222:223], off
	v_lshl_add_u64 v[222:223], s[28:29], 0, v[134:135]
	s_add_i32 m0, s30, 0x2000
	ds_read_b128 v[210:213], v160 offset:54272
	global_load_lds_dwordx4 v[222:223], off
	v_lshl_add_u64 v[222:223], v[226:227], 0, s[14:15]
	s_mov_b32 m0, s41
	ds_read_b128 v[214:217], v160 offset:55296
	global_load_lds_dwordx4 v[222:223], off
	v_lshl_add_u64 v[222:223], v[228:229], 0, s[14:15]
	s_mov_b32 m0, s42
	ds_read_b128 v[218:221], v160 offset:56320
	global_load_lds_dwordx4 v[222:223], off
	s_waitcnt vmcnt(8)
	s_waitcnt lgkmcnt(0)
	s_barrier
	s_setprio 1
	s_waitcnt lgkmcnt(0)
	v_mfma_f32_16x16x32_bf16 v[52:55], v[146:149], v[190:193], v[52:55]
	v_mfma_f32_16x16x32_bf16 v[48:51], v[166:169], v[190:193], v[48:51]
	v_mfma_f32_16x16x32_bf16 v[36:39], v[146:149], v[198:201], v[36:39]
	v_mfma_f32_16x16x32_bf16 v[32:35], v[166:169], v[198:201], v[32:35]
	v_mfma_f32_16x16x32_bf16 v[20:23], v[146:149], v[206:209], v[20:23]
	v_mfma_f32_16x16x32_bf16 v[16:19], v[166:169], v[206:209], v[16:19]
	v_mfma_f32_16x16x32_bf16 v[4:7], v[146:149], v[214:217], v[4:7]
	v_mfma_f32_16x16x32_bf16 v[0:3], v[166:169], v[214:217], v[0:3]
	v_mfma_f32_16x16x32_bf16 v[52:55], v[162:165], v[194:197], v[52:55]
	v_mfma_f32_16x16x32_bf16 v[48:51], v[170:173], v[194:197], v[48:51]
	v_mfma_f32_16x16x32_bf16 v[36:39], v[162:165], v[202:205], v[36:39]
	v_mfma_f32_16x16x32_bf16 v[32:35], v[170:173], v[202:205], v[32:35]
	v_mfma_f32_16x16x32_bf16 v[20:23], v[162:165], v[210:213], v[20:23]
	v_mfma_f32_16x16x32_bf16 v[16:19], v[170:173], v[210:213], v[16:19]
	v_mfma_f32_16x16x32_bf16 v[4:7], v[162:165], v[218:221], v[4:7]
	v_mfma_f32_16x16x32_bf16 v[0:3], v[170:173], v[218:221], v[0:3]
	s_setprio 0
	s_setprio 1
	v_mfma_f32_16x16x32_bf16 v[60:63], v[174:177], v[190:193], v[60:63]
	v_mfma_f32_16x16x32_bf16 v[56:59], v[182:185], v[190:193], v[56:59]
	v_mfma_f32_16x16x32_bf16 v[44:47], v[174:177], v[198:201], v[44:47]
	v_mfma_f32_16x16x32_bf16 v[40:43], v[182:185], v[198:201], v[40:43]
	v_mfma_f32_16x16x32_bf16 v[28:31], v[174:177], v[206:209], v[28:31]
	v_mfma_f32_16x16x32_bf16 v[24:27], v[182:185], v[206:209], v[24:27]
	v_mfma_f32_16x16x32_bf16 v[12:15], v[174:177], v[214:217], v[12:15]
	v_mfma_f32_16x16x32_bf16 v[8:11], v[182:185], v[214:217], v[8:11]
	v_mfma_f32_16x16x32_bf16 v[60:63], v[178:181], v[194:197], v[60:63]
	v_mfma_f32_16x16x32_bf16 v[56:59], v[186:189], v[194:197], v[56:59]
	v_mfma_f32_16x16x32_bf16 v[44:47], v[178:181], v[202:205], v[44:47]
	v_mfma_f32_16x16x32_bf16 v[40:43], v[186:189], v[202:205], v[40:43]
	v_mfma_f32_16x16x32_bf16 v[28:31], v[178:181], v[210:213], v[28:31]
	v_mfma_f32_16x16x32_bf16 v[24:27], v[186:189], v[210:213], v[24:27]
	v_mfma_f32_16x16x32_bf16 v[12:15], v[178:181], v[218:221], v[12:15]
	v_mfma_f32_16x16x32_bf16 v[8:11], v[186:189], v[218:221], v[8:11]
	s_setprio 0
	s_barrier
	s_add_i32 s66, s66, 2
	s_add_u32 s26, s26, 0x100
	s_addc_u32 s27, s27, 0
	s_add_u32 s52, s52, 0x100
	s_addc_u32 s53, s53, 0
	s_cmp_gt_u32 s66, 13
	s_cbranch_scc0 .LBB0_874
	s_and_b64 vcc, exec, s[16:17]
	s_cbranch_vccz .LBB0_877
	s_barrier

.LBB0_1349:
	v_mov_b32_e32 v0, 0
	v_lshl_add_u64 v[128:129], s[26:27], 0, v[162:163]
	v_lshl_add_u64 v[130:131], s[26:27], 0, v[164:165]
	v_lshl_add_u64 v[132:133], s[24:25], 0, v[166:167]
	v_lshl_add_u64 v[134:135], s[24:25], 0, v[168:169]
	s_mov_b32 s21, -2
	s_mov_b64 s[28:29], 0
	ds_read_b128 v[136:139], v177
	ds_read_b128 v[140:143], v177 offset:1024
	ds_read_b128 v[144:147], v177 offset:2048
	ds_read_b128 v[148:151], v177 offset:3072
	ds_read_b128 v[180:183], v178
	ds_read_b128 v[184:187], v178 offset:1024
	ds_read_b128 v[188:191], v178 offset:2048
	ds_read_b128 v[192:195], v178 offset:3072
	v_lshl_add_u64 v[230:231], v[130:131], 0, s[28:29]
	s_mov_b32 m0, s50
	v_lshl_add_u64 v[228:229], v[230:231], 0, s[8:9]
	v_lshl_add_u64 v[232:233], v[128:129], 0, s[28:29]
	ds_read_b128 v[196:199], v179
	ds_read_b128 v[200:203], v179 offset:1024
	ds_read_b128 v[204:207], v179 offset:2048
	ds_read_b128 v[208:211], v179 offset:3072
	ds_read_b128 v[212:215], v179 offset:4096
	ds_read_b128 v[216:219], v179 offset:5120
	ds_read_b128 v[220:223], v179 offset:6144
	ds_read_b128 v[224:227], v179 offset:7168
	global_load_lds_dwordx4 v[228:229], off
	v_lshl_add_u64 v[228:229], v[232:233], 0, s[8:9]
	s_mov_b32 m0, s51
	s_nop 0
	global_load_lds_dwordx4 v[228:229], off
	s_waitcnt vmcnt(8)
	s_waitcnt lgkmcnt(0)
	s_barrier
	s_setprio 1
	s_waitcnt lgkmcnt(0)
	v_mfma_f32_16x16x32_bf16 v[124:127], v[136:139], v[196:199], 0
	v_mfma_f32_16x16x32_bf16 v[120:123], v[144:147], v[196:199], 0
	v_mfma_f32_16x16x32_bf16 v[116:119], v[136:139], v[204:207], 0
	v_mfma_f32_16x16x32_bf16 v[112:115], v[144:147], v[204:207], 0
	v_mfma_f32_16x16x32_bf16 v[104:107], v[136:139], v[212:215], 0
	v_mfma_f32_16x16x32_bf16 v[96:99], v[144:147], v[212:215], 0
	v_mfma_f32_16x16x32_bf16 v[84:87], v[136:139], v[220:223], 0
	v_mfma_f32_16x16x32_bf16 v[80:83], v[144:147], v[220:223], 0
	v_mfma_f32_16x16x32_bf16 v[124:127], v[140:143], v[200:203], v[124:127]
	v_mfma_f32_16x16x32_bf16 v[120:123], v[148:151], v[200:203], v[120:123]
	v_mfma_f32_16x16x32_bf16 v[116:119], v[140:143], v[208:211], v[116:119]
	v_mfma_f32_16x16x32_bf16 v[112:115], v[148:151], v[208:211], v[112:115]
	v_mfma_f32_16x16x32_bf16 v[104:107], v[140:143], v[216:219], v[104:107]
	v_mfma_f32_16x16x32_bf16 v[96:99], v[148:151], v[216:219], v[96:99]
	v_mfma_f32_16x16x32_bf16 v[84:87], v[140:143], v[224:227], v[84:87]
	v_mfma_f32_16x16x32_bf16 v[80:83], v[148:151], v[224:227], v[80:83]
	s_setprio 0
	s_setprio 1
	v_mfma_f32_16x16x32_bf16 v[108:111], v[180:183], v[196:199], 0
	v_mfma_f32_16x16x32_bf16 v[100:103], v[188:191], v[196:199], 0
	v_mfma_f32_16x16x32_bf16 v[92:95], v[180:183], v[204:207], 0
	v_mfma_f32_16x16x32_bf16 v[88:91], v[188:191], v[204:207], 0
	v_mfma_f32_16x16x32_bf16 v[76:79], v[180:183], v[212:215], 0
	v_mfma_f32_16x16x32_bf16 v[72:75], v[188:191], v[212:215], 0
	v_mfma_f32_16x16x32_bf16 v[68:71], v[180:183], v[220:223], 0
	v_mfma_f32_16x16x32_bf16 v[64:67], v[188:191], v[220:223], 0
	v_mfma_f32_16x16x32_bf16 v[108:111], v[184:187], v[200:203], v[108:111]
	v_mfma_f32_16x16x32_bf16 v[100:103], v[192:195], v[200:203], v[100:103]
	v_mfma_f32_16x16x32_bf16 v[92:95], v[184:187], v[208:211], v[92:95]
	v_mfma_f32_16x16x32_bf16 v[88:91], v[192:195], v[208:211], v[88:91]
	v_mfma_f32_16x16x32_bf16 v[76:79], v[184:187], v[216:219], v[76:79]
	v_mfma_f32_16x16x32_bf16 v[72:75], v[192:195], v[216:219], v[72:75]
	v_mfma_f32_16x16x32_bf16 v[68:71], v[184:187], v[224:227], v[68:71]
	v_mfma_f32_16x16x32_bf16 v[64:67], v[192:195], v[224:227], v[64:67]
	s_setprio 0
	s_barrier
	v_lshl_add_u64 v[234:235], v[134:135], 0, s[28:29]
	s_add_i32 s53, s48, s38
	v_lshl_add_u64 v[228:229], v[234:235], 0, s[12:13]
	s_mov_b32 m0, s53
	v_lshl_add_u64 v[236:237], v[132:133], 0, s[28:29]
	s_add_i32 s56, s53, 0x2000
	ds_read_b128 v[196:199], v179 offset:16384
	ds_read_b128 v[200:203], v179 offset:17408
	global_load_lds_dwordx4 v[228:229], off
	v_lshl_add_u64 v[228:229], v[236:237], 0, s[12:13]
	s_mov_b32 m0, s56
	s_add_i32 s57, s49, s38
	ds_read_b128 v[204:207], v179 offset:18432
	ds_read_b128 v[208:211], v179 offset:19456
	global_load_lds_dwordx4 v[228:229], off
	v_lshl_add_u64 v[228:229], v[234:235], 0, s[14:15]
	s_mov_b32 m0, s57
	s_add_i32 s58, s57, 0x2000
	ds_read_b128 v[212:215], v179 offset:20480
	global_load_lds_dwordx4 v[228:229], off
	v_lshl_add_u64 v[228:229], v[236:237], 0, s[14:15]
	s_mov_b32 m0, s58
	ds_read_b128 v[216:219], v179 offset:21504
	global_load_lds_dwordx4 v[228:229], off
	v_lshl_add_u64 v[228:229], v[230:231], 0, s[12:13]
	s_mov_b32 m0, s39
	ds_read_b128 v[220:223], v179 offset:22528
	global_load_lds_dwordx4 v[228:229], off
	v_lshl_add_u64 v[228:229], v[232:233], 0, s[12:13]
	s_mov_b32 m0, s40
	ds_read_b128 v[224:227], v179 offset:23552
	global_load_lds_dwordx4 v[228:229], off
	s_waitcnt vmcnt(8)
	s_waitcnt lgkmcnt(0)
	s_barrier
	s_setprio 1
	s_waitcnt lgkmcnt(0)
	v_mfma_f32_16x16x32_bf16 v[60:63], v[136:139], v[196:199], 0
	v_mfma_f32_16x16x32_bf16 v[56:59], v[144:147], v[196:199], 0
	v_mfma_f32_16x16x32_bf16 v[48:51], v[136:139], v[204:207], 0
	v_mfma_f32_16x16x32_bf16 v[40:43], v[144:147], v[204:207], 0
	v_mfma_f32_16x16x32_bf16 v[32:35], v[136:139], v[212:215], 0
	v_mfma_f32_16x16x32_bf16 v[24:27], v[144:147], v[212:215], 0
	v_mfma_f32_16x16x32_bf16 v[16:19], v[136:139], v[220:223], 0
	v_mfma_f32_16x16x32_bf16 v[8:11], v[144:147], v[220:223], 0
	v_mfma_f32_16x16x32_bf16 v[60:63], v[140:143], v[200:203], v[60:63]
	v_mfma_f32_16x16x32_bf16 v[56:59], v[148:151], v[200:203], v[56:59]
	v_mfma_f32_16x16x32_bf16 v[48:51], v[140:143], v[208:211], v[48:51]
	v_mfma_f32_16x16x32_bf16 v[40:43], v[148:151], v[208:211], v[40:43]
	v_mfma_f32_16x16x32_bf16 v[32:35], v[140:143], v[216:219], v[32:35]
	v_mfma_f32_16x16x32_bf16 v[24:27], v[148:151], v[216:219], v[24:27]
	v_mfma_f32_16x16x32_bf16 v[16:19], v[140:143], v[224:227], v[16:19]
	v_mfma_f32_16x16x32_bf16 v[8:11], v[148:151], v[224:227], v[8:11]
	s_setprio 0
	s_setprio 1
	v_mfma_f32_16x16x32_bf16 v[52:55], v[180:183], v[196:199], 0
	v_mfma_f32_16x16x32_bf16 v[44:47], v[188:191], v[196:199], 0
	v_mfma_f32_16x16x32_bf16 v[36:39], v[180:183], v[204:207], 0
	v_mfma_f32_16x16x32_bf16 v[28:31], v[188:191], v[204:207], 0
	v_mfma_f32_16x16x32_bf16 v[20:23], v[180:183], v[212:215], 0
	v_mfma_f32_16x16x32_bf16 v[12:15], v[188:191], v[212:215], 0
	v_mfma_f32_16x16x32_bf16 v[4:7], v[180:183], v[220:223], 0
	v_mfma_f32_16x16x32_bf16 v[0:3], v[188:191], v[220:223], 0
	v_mfma_f32_16x16x32_bf16 v[52:55], v[184:187], v[200:203], v[52:55]
	v_mfma_f32_16x16x32_bf16 v[44:47], v[192:195], v[200:203], v[44:47]
	v_mfma_f32_16x16x32_bf16 v[36:39], v[184:187], v[208:211], v[36:39]
	v_mfma_f32_16x16x32_bf16 v[28:31], v[192:195], v[208:211], v[28:31]
	v_mfma_f32_16x16x32_bf16 v[20:23], v[184:187], v[216:219], v[20:23]
	v_mfma_f32_16x16x32_bf16 v[12:15], v[192:195], v[216:219], v[12:15]
	v_mfma_f32_16x16x32_bf16 v[4:7], v[184:187], v[224:227], v[4:7]
	v_mfma_f32_16x16x32_bf16 v[0:3], v[192:195], v[224:227], v[0:3]
	s_setprio 0
	s_barrier
	s_branch .Lpk1350_seg3

.Lpk1350_seg3:
	s_add_i32 s59, 0, 0x18000
	s_add_i32 s61, 0, 0x1c000
	v_add_u32_e32 v180, s59, v175
	v_add_u32_e32 v181, s61, v175
	ds_read_b128 v[136:139], v180
	ds_read_b128 v[140:143], v180 offset:1024
	ds_read_b128 v[144:147], v180 offset:2048
	ds_read_b128 v[148:151], v180 offset:3072
	ds_read_b128 v[182:185], v181
	ds_read_b128 v[186:189], v181 offset:1024
	ds_read_b128 v[190:193], v181 offset:2048
	ds_read_b128 v[194:197], v181 offset:3072
	s_mov_b32 m0, s41
	v_lshl_add_u64 v[238:239], v[230:231], 0, s[14:15]
	ds_read_b128 v[198:201], v179 offset:32768
	ds_read_b128 v[202:205], v179 offset:33792
	ds_read_b128 v[206:209], v179 offset:34816
	ds_read_b128 v[210:213], v179 offset:35840
	ds_read_b128 v[214:217], v179 offset:36864
	ds_read_b128 v[218:221], v179 offset:37888
	ds_read_b128 v[222:225], v179 offset:38912
	ds_read_b128 v[226:229], v179 offset:39936
	global_load_lds_dwordx4 v[238:239], off
	v_lshl_add_u64 v[238:239], v[232:233], 0, s[14:15]
	s_mov_b32 m0, s42
	s_nop 0
	global_load_lds_dwordx4 v[238:239], off
	s_waitcnt vmcnt(8)
	s_waitcnt lgkmcnt(0)
	s_barrier
	s_setprio 1
	s_waitcnt lgkmcnt(0)
	v_mfma_f32_16x16x32_bf16 v[124:127], v[136:139], v[198:201], v[124:127]
	v_mfma_f32_16x16x32_bf16 v[120:123], v[144:147], v[198:201], v[120:123]
	v_mfma_f32_16x16x32_bf16 v[116:119], v[136:139], v[206:209], v[116:119]
	v_mfma_f32_16x16x32_bf16 v[112:115], v[144:147], v[206:209], v[112:115]
	v_mfma_f32_16x16x32_bf16 v[104:107], v[136:139], v[214:217], v[104:107]
	v_mfma_f32_16x16x32_bf16 v[96:99], v[144:147], v[214:217], v[96:99]
	v_mfma_f32_16x16x32_bf16 v[84:87], v[136:139], v[222:225], v[84:87]
	v_mfma_f32_16x16x32_bf16 v[80:83], v[144:147], v[222:225], v[80:83]
	v_mfma_f32_16x16x32_bf16 v[124:127], v[140:143], v[202:205], v[124:127]
	v_mfma_f32_16x16x32_bf16 v[120:123], v[148:151], v[202:205], v[120:123]
	v_mfma_f32_16x16x32_bf16 v[116:119], v[140:143], v[210:213], v[116:119]
	v_mfma_f32_16x16x32_bf16 v[112:115], v[148:151], v[210:213], v[112:115]
	v_mfma_f32_16x16x32_bf16 v[104:107], v[140:143], v[218:221], v[104:107]
	v_mfma_f32_16x16x32_bf16 v[96:99], v[148:151], v[218:221], v[96:99]
	v_mfma_f32_16x16x32_bf16 v[84:87], v[140:143], v[226:229], v[84:87]
	v_mfma_f32_16x16x32_bf16 v[80:83], v[148:151], v[226:229], v[80:83]
	s_setprio 0
	s_setprio 1
	v_mfma_f32_16x16x32_bf16 v[108:111], v[182:185], v[198:201], v[108:111]
	v_mfma_f32_16x16x32_bf16 v[100:103], v[190:193], v[198:201], v[100:103]
	v_mfma_f32_16x16x32_bf16 v[92:95], v[182:185], v[206:209], v[92:95]
	v_mfma_f32_16x16x32_bf16 v[88:91], v[190:193], v[206:209], v[88:91]
	v_mfma_f32_16x16x32_bf16 v[76:79], v[182:185], v[214:217], v[76:79]
	v_mfma_f32_16x16x32_bf16 v[72:75], v[190:193], v[214:217], v[72:75]
	v_mfma_f32_16x16x32_bf16 v[68:71], v[182:185], v[222:225], v[68:71]
	v_mfma_f32_16x16x32_bf16 v[64:67], v[190:193], v[222:225], v[64:67]
	v_mfma_f32_16x16x32_bf16 v[108:111], v[186:189], v[202:205], v[108:111]
	v_mfma_f32_16x16x32_bf16 v[100:103], v[194:197], v[202:205], v[100:103]
	v_mfma_f32_16x16x32_bf16 v[92:95], v[186:189], v[210:213], v[92:95]
	v_mfma_f32_16x16x32_bf16 v[88:91], v[194:197], v[210:213], v[88:91]
	v_mfma_f32_16x16x32_bf16 v[76:79], v[186:189], v[218:221], v[76:79]
	v_mfma_f32_16x16x32_bf16 v[72:75], v[194:197], v[218:221], v[72:75]
	v_mfma_f32_16x16x32_bf16 v[68:71], v[186:189], v[226:229], v[68:71]
	v_mfma_f32_16x16x32_bf16 v[64:67], v[194:197], v[226:229], v[64:67]
	s_setprio 0
	s_barrier
	s_add_i32 s59, s59, s38
	v_lshl_add_u64 v[238:239], v[234:235], 0, s[16:17]
	s_mov_b32 m0, s59
	s_add_i32 s60, s59, 0x2000
	ds_read_b128 v[198:201], v179 offset:49152
	ds_read_b128 v[202:205], v179 offset:50176
	global_load_lds_dwordx4 v[238:239], off
	v_lshl_add_u64 v[238:239], v[236:237], 0, s[16:17]
	s_mov_b32 m0, s60
	s_add_i32 s61, s61, s38
	ds_read_b128 v[206:209], v179 offset:51200
	ds_read_b128 v[210:213], v179 offset:52224
	global_load_lds_dwordx4 v[238:239], off
	v_lshl_add_u64 v[234:235], v[234:235], 0, s[18:19]
	s_mov_b32 m0, s61
	s_add_i32 s62, s61, 0x2000
	ds_read_b128 v[214:217], v179 offset:53248
	global_load_lds_dwordx4 v[234:235], off
	v_lshl_add_u64 v[234:235], v[236:237], 0, s[18:19]
	s_mov_b32 m0, s62
	v_lshl_add_u64 v[230:231], v[230:231], 0, s[16:17]
	ds_read_b128 v[218:221], v179 offset:54272
	global_load_lds_dwordx4 v[234:235], off
	s_mov_b32 m0, s44
	ds_read_b128 v[222:225], v179 offset:55296
	global_load_lds_dwordx4 v[230:231], off
	v_lshl_add_u64 v[230:231], v[232:233], 0, s[16:17]
	s_mov_b32 m0, s45
	ds_read_b128 v[226:229], v179 offset:56320
	global_load_lds_dwordx4 v[230:231], off
	s_waitcnt vmcnt(8)
	s_waitcnt lgkmcnt(0)
	s_barrier
; __device__ __forceinline__ unsigned cvt_pk_bf16(float lo, float hi) { unsigned r; asm volatile("v_cvt_pk_bf16_f32 %0, %1, %2" : "=v"(r) : "v"(lo), "v"(hi)); return r; }
; __device__ __forceinline__ float bflo(unsigned w) { return __uint_as_float(w << 16); }
; __device__ __forceinline__ float bfhi(unsigned w) { return __uint_as_float(w & 0xffff0000u); }
;     __device__ __forceinline__ void scale(Acc& acc, const Unit& u, int wr, int wc, int fr, int fq, int pc, bool store) const {
;         int row0 = u.pm * BM + wr * 64 + fr, col0 = u.pn * BM + wc * 32 + 8 * fq;
;         asm volatile("" : "+v"(row0), "+v"(col0));
;         const char* Pb = (const char*)P; char* Ob = (char*)O;
; #pragma unroll
;         for (int ai = 0; ai < 2; ++ai) {
;             u32x4 g[4][2];
; #pragma unroll
;             for (int m = 0; m < 4; ++m) {
;                 const unsigned rowoff = (unsigned)(row0 + ai * HALF + m * 16) * (unsigned)(NIN * 2) + (unsigned)col0 * 2u;
; #pragma unroll
;                 for (int bj = 0; bj < 2; ++bj) g[m][bj] = *(const u32x4*)(Pb + (rowoff + (unsigned)((pc + bj * HALF) * 2)));
;             }
; #pragma unroll
;             for (int m = 0; m < 4; ++m) {
;                 const unsigned ooff = (unsigned)(row0 + ai * HALF + m * 16) * (unsigned)(ldo * 2) + (unsigned)col0 * 2u;
; #pragma unroll
;                 for (int bj = 0; bj < 2; ++bj) {
;                     const u32x4 gg = g[m][bj];
;                     const f32x4 s0 = (f32x4){bflo(gg.x), bfhi(gg.x), bflo(gg.y), bfhi(gg.y)}, s1 = (f32x4){bflo(gg.z), bfhi(gg.z), bflo(gg.w), bfhi(gg.w)};
;                     const f32x4 v0 = acc[ai][bj][m][0] * s0, v1 = acc[ai][bj][m][1] * s1;
;                     if (store) { u32x4 w; w.x = cvt_pk_bf16(v0[0], v0[1]); w.y = cvt_pk_bf16(v0[2], v0[3]); w.z = cvt_pk_bf16(v1[0], v1[1]); w.w = cvt_pk_bf16(v1[2], v1[3]); *(u32x4*)(Ob + (ooff + (unsigned)(bj * HALF * 2))) = w; }
;                     else { acc[ai][bj][m][0] = v0; acc[ai][bj][m][1] = v1; }
; template <class Epi, class Sched, bool ALIGN_EPI>
; __device__ __forceinline__ void gemm_phase(LAS unsigned char* lds, const Gemm g, const Sched& S, const Epi& E) {
;     ...
;             for (int t = 0; t < Epi::MID_T; t += 2) PG8_KBODY(t);
;             E.mid(acc, cur, wr, wc, fr, fq);
;             for (int t = Epi::MID_T; t < nt; t += 2) PG8_KBODY(t);
	s_setprio 1
	s_waitcnt lgkmcnt(0)
	v_mfma_f32_16x16x32_bf16 v[60:63], v[136:139], v[198:201], v[60:63]
	v_mfma_f32_16x16x32_bf16 v[56:59], v[144:147], v[198:201], v[56:59]
	v_mfma_f32_16x16x32_bf16 v[48:51], v[136:139], v[206:209], v[48:51]
	v_mfma_f32_16x16x32_bf16 v[40:43], v[144:147], v[206:209], v[40:43]
	v_mfma_f32_16x16x32_bf16 v[32:35], v[136:139], v[214:217], v[32:35]
	v_mfma_f32_16x16x32_bf16 v[24:27], v[144:147], v[214:217], v[24:27]
	v_mfma_f32_16x16x32_bf16 v[16:19], v[136:139], v[222:225], v[16:19]
	v_mfma_f32_16x16x32_bf16 v[8:11], v[144:147], v[222:225], v[8:11]
	v_mfma_f32_16x16x32_bf16 v[60:63], v[140:143], v[202:205], v[60:63]
	v_mfma_f32_16x16x32_bf16 v[56:59], v[148:151], v[202:205], v[56:59]
	v_mfma_f32_16x16x32_bf16 v[48:51], v[140:143], v[210:213], v[48:51]
	v_mfma_f32_16x16x32_bf16 v[40:43], v[148:151], v[210:213], v[40:43]
	v_mfma_f32_16x16x32_bf16 v[32:35], v[140:143], v[218:221], v[32:35]
	v_mfma_f32_16x16x32_bf16 v[24:27], v[148:151], v[218:221], v[24:27]
	v_mfma_f32_16x16x32_bf16 v[16:19], v[140:143], v[226:229], v[16:19]
	v_mfma_f32_16x16x32_bf16 v[8:11], v[148:151], v[226:229], v[8:11]
	s_setprio 0
	s_setprio 1
	v_mfma_f32_16x16x32_bf16 v[52:55], v[182:185], v[198:201], v[52:55]
	v_mfma_f32_16x16x32_bf16 v[44:47], v[190:193], v[198:201], v[44:47]
	v_mfma_f32_16x16x32_bf16 v[36:39], v[182:185], v[206:209], v[36:39]
	v_mfma_f32_16x16x32_bf16 v[28:31], v[190:193], v[206:209], v[28:31]
	v_mfma_f32_16x16x32_bf16 v[20:23], v[182:185], v[214:217], v[20:23]
	v_mfma_f32_16x16x32_bf16 v[12:15], v[190:193], v[214:217], v[12:15]
	v_mfma_f32_16x16x32_bf16 v[4:7], v[182:185], v[222:225], v[4:7]
	v_mfma_f32_16x16x32_bf16 v[0:3], v[190:193], v[222:225], v[0:3]
	v_mfma_f32_16x16x32_bf16 v[52:55], v[186:189], v[202:205], v[52:55]
	v_mfma_f32_16x16x32_bf16 v[44:47], v[194:197], v[202:205], v[44:47]
	v_mfma_f32_16x16x32_bf16 v[36:39], v[186:189], v[210:213], v[36:39]
	v_mfma_f32_16x16x32_bf16 v[28:31], v[194:197], v[210:213], v[28:31]
	v_mfma_f32_16x16x32_bf16 v[20:23], v[186:189], v[218:221], v[20:23]
	v_mfma_f32_16x16x32_bf16 v[12:15], v[194:197], v[218:221], v[12:15]
	v_mfma_f32_16x16x32_bf16 v[4:7], v[186:189], v[226:229], v[4:7]
	v_mfma_f32_16x16x32_bf16 v[0:3], v[194:197], v[226:229], v[0:3]
	s_setprio 0
	s_barrier
	s_add_i32 s21, s21, 2
	s_add_u32 s28, s28, 0x100
	s_addc_u32 s29, s29, 0
	s_cmp_gt_u32 s21, 5
	s_cbranch_scc0 .LBB0_1350
	v_lshl_add_u32 v182, s34, 8, v174
	v_lshl_or_b32 v183, s23, 8, v176
	v_mov_b32_e32 v128, v182
	v_mov_b32_e32 v129, v183
	s_ashr_i32 s23, s22, 31
	v_mul_lo_u32 v128, v128, s52
	v_lshl_add_u32 v228, v129, 1, v128
	v_add_u32_e32 v128, 0x1200, v228
	v_add_u32_e32 v140, 0x49200, v228
	global_load_dwordx4 v[148:151], v128, s[68:69]
	global_load_dwordx4 v[144:147], v140, s[68:69]
	v_add_u32_e32 v128, 0x1300, v228
	v_add_u32_e32 v140, 0x49300, v228
	global_load_dwordx4 v[136:139], v128, s[68:69]
	v_add_u32_e32 v184, 0x6d200, v228
	global_load_dwordx4 v[140:143], v140, s[68:69]
	v_add_u32_e32 v128, 0x25200, v228
	global_load_dwordx4 v[132:135], v128, s[68:69]
	v_add_u32_e32 v128, 0x25300, v228
	global_load_dwordx4 v[128:131], v128, s[68:69]
	v_add_u32_e32 v188, 0x6d300, v228
	global_load_dwordx4 v[184:187], v184, s[68:69]
	s_nop 0
	global_load_dwordx4 v[188:191], v188, s[68:69]
	v_add_u32_e32 v192, 0x121200, v228
	v_add_u32_e32 v196, 0x121300, v228
	global_load_dwordx4 v[192:195], v192, s[68:69]
	s_nop 0
	global_load_dwordx4 v[196:199], v196, s[68:69]
	s_ashr_i32 s21, s20, 31
	s_lshl_b64 s[28:29], s[22:23], 19
	s_lshl_b64 s[30:31], s[20:21], 19
	s_add_u32 s28, s1, s28
	s_addc_u32 s29, s33, s29
	s_add_u32 s30, s36, s30
	s_addc_u32 s31, s37, s31
	s_and_b64 s[34:35], s[2:3], exec
	s_cselect_b32 s21, s29, s27
	s_cselect_b32 s23, s28, s26
	s_cselect_b32 s63, s31, s25
	s_cselect_b32 s66, s30, s24
	s_add_u32 s26, s26, 0x40480
	s_addc_u32 s27, s27, 0
	s_add_u32 s67, s24, 0x500
	s_addc_u32 s70, s25, 0
	s_mov_b32 s71, 6
	s_waitcnt vmcnt(0)
	v_lshlrev_b32_e32 v200, 16, v148
	v_and_b32_e32 v201, 0xffff0000, v148
	v_lshlrev_b32_e32 v148, 16, v149
	v_and_b32_e32 v149, 0xffff0000, v149
	v_lshlrev_b32_e32 v204, 16, v136
	v_and_b32_e32 v205, 0xffff0000, v136
	v_lshlrev_b32_e32 v206, 16, v137
	v_and_b32_e32 v207, 0xffff0000, v137
	v_lshlrev_b32_e32 v202, 16, v150
	v_and_b32_e32 v203, 0xffff0000, v150
	v_lshlrev_b32_e32 v224, 16, v130
	v_and_b32_e32 v225, 0xffff0000, v130
	v_lshlrev_b32_e32 v226, 16, v131
	v_and_b32_e32 v227, 0xffff0000, v131
	v_lshlrev_b32_e32 v150, 16, v151
	v_and_b32_e32 v151, 0xffff0000, v151
	v_lshlrev_b32_e32 v208, 16, v138
	v_and_b32_e32 v209, 0xffff0000, v138
	v_lshlrev_b32_e32 v210, 16, v139
	v_and_b32_e32 v211, 0xffff0000, v139
	v_pk_mul_f32 v[138:139], v[126:127], v[148:149]
	v_pk_mul_f32 v[136:137], v[124:125], v[200:201]
	v_pk_mul_f32 v[126:127], v[110:111], v[206:207]
	v_pk_mul_f32 v[124:125], v[108:109], v[204:205]
	v_pk_mul_f32 v[110:111], v[90:91], v[226:227]
	v_pk_mul_f32 v[108:109], v[88:89], v[224:225]
	v_lshlrev_b32_e32 v88, 16, v144
	v_and_b32_e32 v89, 0xffff0000, v144
	v_add_u32_e32 v91, 0x145200, v228
	v_lshlrev_b32_e32 v212, 16, v132
	v_and_b32_e32 v213, 0xffff0000, v132
	v_lshlrev_b32_e32 v214, 16, v133
	v_and_b32_e32 v215, 0xffff0000, v133
	v_lshlrev_b32_e32 v216, 16, v134
	v_and_b32_e32 v217, 0xffff0000, v134
	v_lshlrev_b32_e32 v218, 16, v135
	v_and_b32_e32 v219, 0xffff0000, v135
	v_lshlrev_b32_e32 v222, 16, v129
	v_and_b32_e32 v223, 0xffff0000, v129
	v_pk_mul_f32 v[134:135], v[122:123], v[150:151]
	v_pk_mul_f32 v[132:133], v[120:121], v[202:203]
	v_pk_mul_f32 v[120:121], v[100:101], v[208:209]
	v_lshlrev_b32_e32 v90, 16, v145
	global_load_dwordx4 v[148:151], v91, s[68:69]
; __device__ __forceinline__ unsigned cvt_pk_bf16(float lo, float hi) { unsigned r; asm volatile("v_cvt_pk_bf16_f32 %0, %1, %2" : "=v"(r) : "v"(lo), "v"(hi)); return r; }
; __device__ __forceinline__ float bflo(unsigned w) { return __uint_as_float(w << 16); }
; __device__ __forceinline__ float bfhi(unsigned w) { return __uint_as_float(w & 0xffff0000u); }
;     __device__ __forceinline__ void scale(Acc& acc, const Unit& u, int wr, int wc, int fr, int fq, int pc, bool store) const {
;     ...
;             u32x4 g[4][2];
; #pragma unroll
;             for (int m = 0; m < 4; ++m) {
;                 const unsigned rowoff = (unsigned)(row0 + ai * HALF + m * 16) * (unsigned)(NIN * 2) + (unsigned)col0 * 2u;
; #pragma unroll
;                 for (int bj = 0; bj < 2; ++bj) g[m][bj] = *(const u32x4*)(Pb + (rowoff + (unsigned)((pc + bj * HALF) * 2)));
;             }
; #pragma unroll
;             for (int m = 0; m < 4; ++m) {
;                 const unsigned ooff = (unsigned)(row0 + ai * HALF + m * 16) * (unsigned)(ldo * 2) + (unsigned)col0 * 2u;
; #pragma unroll
;                 for (int bj = 0; bj < 2; ++bj) {
;                     const u32x4 gg = g[m][bj];
;                     const f32x4 s0 = (f32x4){bflo(gg.x), bfhi(gg.x), bflo(gg.y), bfhi(gg.y)}, s1 = (f32x4){bflo(gg.z), bfhi(gg.z), bflo(gg.w), bfhi(gg.w)};
;                     const f32x4 v0 = acc[ai][bj][m][0] * s0, v1 = acc[ai][bj][m][1] * s1;
;                     if (store) { u32x4 w; w.x = cvt_pk_bf16(v0[0], v0[1]); w.y = cvt_pk_bf16(v0[2], v0[3]); w.z = cvt_pk_bf16(v1[0], v1[1]); w.w = cvt_pk_bf16(v1[2], v1[3]); *(u32x4*)(Ob + (ooff + (unsigned)(bj * HALF * 2))) = w; }
;                     else { acc[ai][bj][m][0] = v0; acc[ai][bj][m][1] = v1; }
	v_and_b32_e32 v91, 0xffff0000, v145
	v_pk_mul_f32 v[100:101], v[104:105], v[88:89]
	v_add_u32_e32 v89, 0x145300, v228
	v_pk_mul_f32 v[122:123], v[102:103], v[210:211]
	v_pk_mul_f32 v[130:131], v[118:119], v[214:215]
	v_pk_mul_f32 v[118:119], v[114:115], v[218:219]
	v_pk_mul_f32 v[114:115], v[94:95], v[222:223]
	v_lshlrev_b32_e32 v94, 16, v147
	v_and_b32_e32 v95, 0xffff0000, v147
	v_pk_mul_f32 v[102:103], v[106:107], v[90:91]
	v_lshlrev_b32_e32 v88, 16, v140
	global_load_dwordx4 v[104:107], v89, s[68:69]
	v_and_b32_e32 v89, 0xffff0000, v140
	v_lshlrev_b32_e32 v90, 16, v141
	v_and_b32_e32 v91, 0xffff0000, v141
	v_lshlrev_b32_e32 v140, 16, v143
	v_and_b32_e32 v141, 0xffff0000, v143
	v_lshlrev_b32_e32 v220, 16, v128
	v_and_b32_e32 v221, 0xffff0000, v128
	v_pk_mul_f32 v[98:99], v[98:99], v[94:95]
	v_pk_mul_f32 v[94:95], v[78:79], v[90:91]
	v_pk_mul_f32 v[90:91], v[74:75], v[140:141]
	v_add_u32_e32 v74, 0x169200, v228
	v_pk_mul_f32 v[128:129], v[116:117], v[212:213]
	v_pk_mul_f32 v[116:117], v[112:113], v[216:217]
	v_pk_mul_f32 v[112:113], v[92:93], v[220:221]
	v_lshlrev_b32_e32 v92, 16, v146
	v_and_b32_e32 v93, 0xffff0000, v146
	v_lshlrev_b32_e32 v144, 16, v142
	v_and_b32_e32 v145, 0xffff0000, v142
	global_load_dwordx4 v[140:143], v74, s[68:69]
	v_lshlrev_b32_e32 v74, 16, v185
	v_and_b32_e32 v75, 0xffff0000, v185
	v_pk_mul_f32 v[96:97], v[96:97], v[92:93]
	v_pk_mul_f32 v[92:93], v[76:77], v[88:89]
	v_pk_mul_f32 v[88:89], v[72:73], v[144:145]
	v_lshlrev_b32_e32 v72, 16, v184
	v_and_b32_e32 v73, 0xffff0000, v184
	v_lshlrev_b32_e32 v76, 16, v186
	v_and_b32_e32 v77, 0xffff0000, v186
	v_pk_mul_f32 v[86:87], v[86:87], v[74:75]
	v_add_u32_e32 v74, 0x169300, v228
	v_lshlrev_b32_e32 v78, 16, v187
	v_and_b32_e32 v79, 0xffff0000, v187
	global_load_dwordx4 v[144:147], v74, s[68:69]
	v_pk_mul_f32 v[84:85], v[84:85], v[72:73]
	v_pk_mul_f32 v[76:77], v[80:81], v[76:77]
	v_lshlrev_b32_e32 v72, 16, v188
	v_and_b32_e32 v73, 0xffff0000, v188
	v_lshlrev_b32_e32 v184, 16, v190
	v_and_b32_e32 v185, 0xffff0000, v190
	v_add_u32_e32 v80, 0x18d200, v228
	v_pk_mul_f32 v[78:79], v[82:83], v[78:79]
	v_lshlrev_b32_e32 v74, 16, v189
	v_and_b32_e32 v75, 0xffff0000, v189
	v_lshlrev_b32_e32 v186, 16, v191
	global_load_dwordx4 v[80:83], v80, s[68:69]
	v_and_b32_e32 v187, 0xffff0000, v191
	v_pk_mul_f32 v[72:73], v[68:69], v[72:73]
	v_pk_mul_f32 v[68:69], v[64:65], v[184:185]
	v_add_u32_e32 v64, 0x18d300, v228
	v_pk_mul_f32 v[74:75], v[70:71], v[74:75]
	v_pk_mul_f32 v[70:71], v[66:67], v[186:187]
	global_load_dwordx4 v[184:187], v64, s[68:69]
	v_lshlrev_b32_e32 v64, 16, v192
	v_and_b32_e32 v65, 0xffff0000, v192
	v_lshlrev_b32_e32 v66, 16, v193
	v_and_b32_e32 v67, 0xffff0000, v193
	v_lshlrev_b32_e32 v188, 16, v194
	v_and_b32_e32 v189, 0xffff0000, v194
	v_lshlrev_b32_e32 v190, 16, v195
	v_and_b32_e32 v191, 0xffff0000, v195
	v_pk_mul_f32 v[62:63], v[62:63], v[66:67]
	v_pk_mul_f32 v[60:61], v[60:61], v[64:65]
	v_pk_mul_f32 v[66:67], v[58:59], v[190:191]
	v_pk_mul_f32 v[64:65], v[56:57], v[188:189]
	v_lshlrev_b32_e32 v56, 16, v196
	v_and_b32_e32 v57, 0xffff0000, v196
	v_lshlrev_b32_e32 v58, 16, v197
	v_and_b32_e32 v59, 0xffff0000, v197
	v_lshlrev_b32_e32 v188, 16, v198
	v_and_b32_e32 v189, 0xffff0000, v198
	v_lshlrev_b32_e32 v190, 16, v199
	v_and_b32_e32 v191, 0xffff0000, v199
	v_pk_mul_f32 v[54:55], v[54:55], v[58:59]
	v_pk_mul_f32 v[52:53], v[52:53], v[56:57]
	v_pk_mul_f32 v[58:59], v[46:47], v[190:191]
	v_pk_mul_f32 v[56:57], v[44:45], v[188:189]
	s_waitcnt vmcnt(5)
	v_lshlrev_b32_e32 v44, 16, v148
	v_and_b32_e32 v45, 0xffff0000, v148
	v_lshlrev_b32_e32 v46, 16, v149
	v_and_b32_e32 v47, 0xffff0000, v149
	v_lshlrev_b32_e32 v148, 16, v150
	v_and_b32_e32 v149, 0xffff0000, v150
	v_lshlrev_b32_e32 v150, 16, v151
	v_and_b32_e32 v151, 0xffff0000, v151
	v_pk_mul_f32 v[46:47], v[50:51], v[46:47]
	v_pk_mul_f32 v[44:45], v[48:49], v[44:45]
	v_pk_mul_f32 v[50:51], v[42:43], v[150:151]
	v_pk_mul_f32 v[48:49], v[40:41], v[148:149]
	s_waitcnt vmcnt(4)
	v_lshlrev_b32_e32 v40, 16, v104
	v_and_b32_e32 v41, 0xffff0000, v104
	v_lshlrev_b32_e32 v42, 16, v105
	v_and_b32_e32 v43, 0xffff0000, v105
	v_lshlrev_b32_e32 v104, 16, v106
	v_and_b32_e32 v105, 0xffff0000, v106
	v_lshlrev_b32_e32 v106, 16, v107
	v_and_b32_e32 v107, 0xffff0000, v107
	v_pk_mul_f32 v[38:39], v[38:39], v[42:43]
	v_pk_mul_f32 v[36:37], v[36:37], v[40:41]
	v_pk_mul_f32 v[42:43], v[30:31], v[106:107]
	v_pk_mul_f32 v[40:41], v[28:29], v[104:105]
	s_waitcnt vmcnt(3)
	v_lshlrev_b32_e32 v28, 16, v140
	v_and_b32_e32 v29, 0xffff0000, v140
	v_lshlrev_b32_e32 v30, 16, v141
	v_and_b32_e32 v31, 0xffff0000, v141
	v_lshlrev_b32_e32 v104, 16, v142
	v_and_b32_e32 v105, 0xffff0000, v142
	v_lshlrev_b32_e32 v106, 16, v143
	v_and_b32_e32 v107, 0xffff0000, v143
	v_pk_mul_f32 v[30:31], v[34:35], v[30:31]
	v_pk_mul_f32 v[28:29], v[32:33], v[28:29]
	v_pk_mul_f32 v[34:35], v[26:27], v[106:107]
	v_pk_mul_f32 v[32:33], v[24:25], v[104:105]
	s_waitcnt vmcnt(2)
	v_lshlrev_b32_e32 v24, 16, v144
	v_and_b32_e32 v25, 0xffff0000, v144
	v_lshlrev_b32_e32 v26, 16, v145
	v_and_b32_e32 v27, 0xffff0000, v145
	v_lshlrev_b32_e32 v104, 16, v146
	v_and_b32_e32 v105, 0xffff0000, v146
	v_lshlrev_b32_e32 v106, 16, v147
	v_and_b32_e32 v107, 0xffff0000, v147
	v_pk_mul_f32 v[22:23], v[22:23], v[26:27]
	v_pk_mul_f32 v[20:21], v[20:21], v[24:25]
	v_pk_mul_f32 v[26:27], v[14:15], v[106:107]
	v_pk_mul_f32 v[24:25], v[12:13], v[104:105]
	s_waitcnt vmcnt(1)
	v_lshlrev_b32_e32 v12, 16, v80
	v_and_b32_e32 v13, 0xffff0000, v80
	v_lshlrev_b32_e32 v14, 16, v81
	v_and_b32_e32 v15, 0xffff0000, v81
	v_lshlrev_b32_e32 v80, 16, v82
	v_and_b32_e32 v81, 0xffff0000, v82
	v_lshlrev_b32_e32 v82, 16, v83
	v_and_b32_e32 v83, 0xffff0000, v83
	v_pk_mul_f32 v[14:15], v[18:19], v[14:15]
	v_pk_mul_f32 v[12:13], v[16:17], v[12:13]
	v_pk_mul_f32 v[10:11], v[10:11], v[82:83]
	v_pk_mul_f32 v[8:9], v[8:9], v[80:81]
	s_waitcnt vmcnt(0)
	v_lshlrev_b32_e32 v16, 16, v184
	v_and_b32_e32 v17, 0xffff0000, v184
	v_lshlrev_b32_e32 v18, 16, v185
	v_and_b32_e32 v19, 0xffff0000, v185
	v_lshlrev_b32_e32 v80, 16, v186
	v_and_b32_e32 v81, 0xffff0000, v186
	v_lshlrev_b32_e32 v82, 16, v187
	v_and_b32_e32 v83, 0xffff0000, v187
	v_pk_mul_f32 v[6:7], v[6:7], v[18:19]
	v_pk_mul_f32 v[4:5], v[4:5], v[16:17]
	v_pk_mul_f32 v[2:3], v[2:3], v[82:83]
	v_pk_mul_f32 v[0:1], v[0:1], v[80:81]

; template <class Epi, class Sched, bool ALIGN_EPI>
; __device__ __forceinline__ void gemm_phase(LAS unsigned char* lds, const Gemm g, const Sched& S, const Epi& E) {
;     ...
;         const bool has_next = S.next(ui + 1, nxt);
;         const char* nA = has_next ? (const char*)g.A + (size_t)nxt.pm * tstepA : cA; const char* nB = has_next ? (const char*)g.Bt + (size_t)nxt.pn * tstepB : cB;
.LBB0_1456:
	s_ashr_i32 s21, s20, 31
	s_lshl_b64 s[22:23], s[20:21], 20
	s_add_u32 s22, s72, s22
	s_addc_u32 s23, s73, s23
	s_and_b64 s[24:25], s[4:5], exec
	s_cselect_b32 s21, s23, s31
	s_cselect_b32 s27, s22, s30
	s_ashr_i32 s19, s18, 31
	s_lshl_b64 s[24:25], s[18:19], 19
	s_add_u32 s24, s0, s24
	s_addc_u32 s25, s1, s25
	s_and_b64 s[36:37], s[4:5], exec
	s_cselect_b32 s19, s25, s35
	s_cselect_b32 s49, s24, s34
	s_add_u32 s30, s30, 0x80080
	s_addc_u32 s31, s31, 0
	s_add_u32 s50, s34, 0x100
	v_mov_b32_e32 v0, 0
	s_addc_u32 s51, s35, 0
	s_mov_b32 s52, -2
	s_waitcnt lgkmcnt(0)
	ds_read_b128 v[128:131], v191
	ds_read_b128 v[132:135], v191 offset:1024
	ds_read_b128 v[136:139], v191 offset:2048
	ds_read_b128 v[140:143], v191 offset:3072
	ds_read_b128 v[144:147], v192
	ds_read_b128 v[148:151], v192 offset:1024
	ds_read_b128 v[170:173], v192 offset:2048
	ds_read_b128 v[174:177], v192 offset:3072
	s_add_u32 s34, s30, 0xfff80080
	s_addc_u32 s35, s31, -1
	s_cmp_eq_u32 s52, 12
	s_cselect_b32 s37, s21, s35
	s_cselect_b32 s36, s27, s34
	s_cselect_b32 s35, s19, s51
	s_cselect_b32 s34, s49, s50
	v_lshl_add_u64 v[186:187], s[30:31], 0, v[162:163]
	s_add_i32 m0, s29, 0xc000
	ds_read_b128 v[178:181], v193
	ds_read_b128 v[182:185], v193 offset:1024
	ds_read_b128 v[196:199], v193 offset:2048
	ds_read_b128 v[200:203], v193 offset:3072
	ds_read_b128 v[204:207], v193 offset:4096
	ds_read_b128 v[208:211], v193 offset:5120
	ds_read_b128 v[212:215], v193 offset:6144
	ds_read_b128 v[216:219], v193 offset:7168
	global_load_lds_dwordx4 v[186:187], off
	v_lshl_add_u64 v[186:187], s[30:31], 0, v[164:165]
	s_add_i32 m0, s29, 0xe000
	s_nop 0
	global_load_lds_dwordx4 v[186:187], off
	s_waitcnt vmcnt(8)
	s_waitcnt lgkmcnt(0)
	s_barrier
	s_setprio 1
	s_waitcnt lgkmcnt(0)
	v_mfma_f32_16x16x32_bf16 v[124:127], v[128:131], v[178:181], 0
	v_mfma_f32_16x16x32_bf16 v[120:123], v[136:139], v[178:181], 0
	v_mfma_f32_16x16x32_bf16 v[108:111], v[128:131], v[196:199], 0
	v_mfma_f32_16x16x32_bf16 v[104:107], v[136:139], v[196:199], 0
	v_mfma_f32_16x16x32_bf16 v[92:95], v[128:131], v[204:207], 0
	v_mfma_f32_16x16x32_bf16 v[88:91], v[136:139], v[204:207], 0
	v_mfma_f32_16x16x32_bf16 v[76:79], v[128:131], v[212:215], 0
	v_mfma_f32_16x16x32_bf16 v[72:75], v[136:139], v[212:215], 0
	v_mfma_f32_16x16x32_bf16 v[124:127], v[132:135], v[182:185], v[124:127]
	v_mfma_f32_16x16x32_bf16 v[120:123], v[140:143], v[182:185], v[120:123]
	v_mfma_f32_16x16x32_bf16 v[108:111], v[132:135], v[200:203], v[108:111]
	v_mfma_f32_16x16x32_bf16 v[104:107], v[140:143], v[200:203], v[104:107]
	v_mfma_f32_16x16x32_bf16 v[92:95], v[132:135], v[208:211], v[92:95]
	v_mfma_f32_16x16x32_bf16 v[88:91], v[140:143], v[208:211], v[88:91]
	v_mfma_f32_16x16x32_bf16 v[76:79], v[132:135], v[216:219], v[76:79]
	v_mfma_f32_16x16x32_bf16 v[72:75], v[140:143], v[216:219], v[72:75]
	s_setprio 0
	s_setprio 1
	v_mfma_f32_16x16x32_bf16 v[116:119], v[144:147], v[178:181], 0
	v_mfma_f32_16x16x32_bf16 v[112:115], v[170:173], v[178:181], 0
	v_mfma_f32_16x16x32_bf16 v[100:103], v[144:147], v[196:199], 0
	v_mfma_f32_16x16x32_bf16 v[96:99], v[170:173], v[196:199], 0
	v_mfma_f32_16x16x32_bf16 v[84:87], v[144:147], v[204:207], 0
	v_mfma_f32_16x16x32_bf16 v[80:83], v[170:173], v[204:207], 0
	v_mfma_f32_16x16x32_bf16 v[68:71], v[144:147], v[212:215], 0
	v_mfma_f32_16x16x32_bf16 v[64:67], v[170:173], v[212:215], 0
	v_mfma_f32_16x16x32_bf16 v[116:119], v[148:151], v[182:185], v[116:119]
	v_mfma_f32_16x16x32_bf16 v[112:115], v[174:177], v[182:185], v[112:115]
	v_mfma_f32_16x16x32_bf16 v[100:103], v[148:151], v[200:203], v[100:103]
	v_mfma_f32_16x16x32_bf16 v[96:99], v[174:177], v[200:203], v[96:99]
	v_mfma_f32_16x16x32_bf16 v[84:87], v[148:151], v[208:211], v[84:87]
	v_mfma_f32_16x16x32_bf16 v[80:83], v[174:177], v[208:211], v[80:83]
	v_mfma_f32_16x16x32_bf16 v[68:71], v[148:151], v[216:219], v[68:71]
	v_mfma_f32_16x16x32_bf16 v[64:67], v[174:177], v[216:219], v[64:67]
	s_setprio 0
	s_barrier
	s_add_i32 s53, s47, s33
	v_lshl_add_u64 v[186:187], s[34:35], 0, v[156:157]
	s_mov_b32 m0, s53
	ds_read_b128 v[178:181], v193 offset:16384
	ds_read_b128 v[182:185], v193 offset:17408
	global_load_lds_dwordx4 v[186:187], off
	s_add_i32 m0, s53, 0x2000
	s_add_u32 s54, s34, 0x40000
	v_lshl_add_u64 v[220:221], s[34:35], 0, v[160:161]
	s_addc_u32 s55, s35, 0
	s_add_i32 s53, s48, s33
	ds_read_b128 v[196:199], v193 offset:18432
	ds_read_b128 v[200:203], v193 offset:19456
	global_load_lds_dwordx4 v[220:221], off
	v_lshl_add_u64 v[222:223], s[54:55], 0, v[156:157]
	s_mov_b32 m0, s53
	v_lshl_add_u64 v[224:225], s[36:37], 0, v[158:159]
	ds_read_b128 v[204:207], v193 offset:20480
	global_load_lds_dwordx4 v[222:223], off
	v_lshl_add_u64 v[222:223], s[54:55], 0, v[160:161]
	s_add_i32 m0, s53, 0x2000
	ds_read_b128 v[208:211], v193 offset:21504
	global_load_lds_dwordx4 v[222:223], off
	v_lshl_add_u64 v[222:223], s[36:37], 0, v[154:155]
	s_mov_b32 m0, s29
	ds_read_b128 v[212:215], v193 offset:22528
	global_load_lds_dwordx4 v[222:223], off
	s_mov_b32 m0, s38
	ds_read_b128 v[216:219], v193 offset:23552
	global_load_lds_dwordx4 v[224:225], off
	s_waitcnt vmcnt(8)
	s_waitcnt lgkmcnt(0)
	s_barrier
	s_setprio 1
	s_waitcnt lgkmcnt(0)
	v_mfma_f32_16x16x32_bf16 v[60:63], v[128:131], v[178:181], 0
	v_mfma_f32_16x16x32_bf16 v[56:59], v[136:139], v[178:181], 0
	v_mfma_f32_16x16x32_bf16 v[44:47], v[128:131], v[196:199], 0
	v_mfma_f32_16x16x32_bf16 v[40:43], v[136:139], v[196:199], 0
	v_mfma_f32_16x16x32_bf16 v[28:31], v[128:131], v[204:207], 0
	v_mfma_f32_16x16x32_bf16 v[24:27], v[136:139], v[204:207], 0
	v_mfma_f32_16x16x32_bf16 v[12:15], v[128:131], v[212:215], 0
	v_mfma_f32_16x16x32_bf16 v[8:11], v[136:139], v[212:215], 0
	v_mfma_f32_16x16x32_bf16 v[60:63], v[132:135], v[182:185], v[60:63]
	v_mfma_f32_16x16x32_bf16 v[56:59], v[140:143], v[182:185], v[56:59]
	v_mfma_f32_16x16x32_bf16 v[44:47], v[132:135], v[200:203], v[44:47]
	v_mfma_f32_16x16x32_bf16 v[40:43], v[140:143], v[200:203], v[40:43]
	v_mfma_f32_16x16x32_bf16 v[28:31], v[132:135], v[208:211], v[28:31]
	v_mfma_f32_16x16x32_bf16 v[24:27], v[140:143], v[208:211], v[24:27]
	v_mfma_f32_16x16x32_bf16 v[12:15], v[132:135], v[216:219], v[12:15]
	v_mfma_f32_16x16x32_bf16 v[8:11], v[140:143], v[216:219], v[8:11]
	s_setprio 0
	s_setprio 1
	v_mfma_f32_16x16x32_bf16 v[52:55], v[144:147], v[178:181], 0
	v_mfma_f32_16x16x32_bf16 v[48:51], v[170:173], v[178:181], 0
	v_mfma_f32_16x16x32_bf16 v[36:39], v[144:147], v[196:199], 0
	v_mfma_f32_16x16x32_bf16 v[32:35], v[170:173], v[196:199], 0
	v_mfma_f32_16x16x32_bf16 v[20:23], v[144:147], v[204:207], 0
	v_mfma_f32_16x16x32_bf16 v[16:19], v[170:173], v[204:207], 0
	v_mfma_f32_16x16x32_bf16 v[4:7], v[144:147], v[212:215], 0
	v_mfma_f32_16x16x32_bf16 v[0:3], v[170:173], v[212:215], 0
	v_mfma_f32_16x16x32_bf16 v[52:55], v[148:151], v[182:185], v[52:55]
	v_mfma_f32_16x16x32_bf16 v[48:51], v[174:177], v[182:185], v[48:51]
	v_mfma_f32_16x16x32_bf16 v[36:39], v[148:151], v[200:203], v[36:39]
	v_mfma_f32_16x16x32_bf16 v[32:35], v[174:177], v[200:203], v[32:35]
	v_mfma_f32_16x16x32_bf16 v[20:23], v[148:151], v[208:211], v[20:23]
	v_mfma_f32_16x16x32_bf16 v[16:19], v[174:177], v[208:211], v[16:19]
	v_mfma_f32_16x16x32_bf16 v[4:7], v[148:151], v[216:219], v[4:7]
	v_mfma_f32_16x16x32_bf16 v[0:3], v[174:177], v[216:219], v[0:3]
	s_setprio 0
	s_barrier
	s_branch .Lpk1457_seg3

.Lpk1457_seg3:
	s_add_i32 s53, 0, 0x18000
	s_add_i32 s54, 0, 0x1c000
	v_add_u32_e32 v140, s53, v189
	v_add_u32_e32 v174, s54, v189
	ds_read_b128 v[128:131], v140
	ds_read_b128 v[132:135], v140 offset:1024
	ds_read_b128 v[136:139], v140 offset:2048
	ds_read_b128 v[140:143], v140 offset:3072
	ds_read_b128 v[144:147], v174
	ds_read_b128 v[148:151], v174 offset:1024
	ds_read_b128 v[170:173], v174 offset:2048
	ds_read_b128 v[174:177], v174 offset:3072
	s_add_u32 s36, s36, 0x80000
	s_addc_u32 s37, s37, 0
	s_mov_b32 m0, s39
	v_lshl_add_u64 v[226:227], s[36:37], 0, v[154:155]
	ds_read_b128 v[178:181], v193 offset:32768
	ds_read_b128 v[182:185], v193 offset:33792
	ds_read_b128 v[196:199], v193 offset:34816
	ds_read_b128 v[200:203], v193 offset:35840
	ds_read_b128 v[204:207], v193 offset:36864
	ds_read_b128 v[208:211], v193 offset:37888
	ds_read_b128 v[212:215], v193 offset:38912
	ds_read_b128 v[216:219], v193 offset:39936
	global_load_lds_dwordx4 v[226:227], off
	v_lshl_add_u64 v[226:227], s[36:37], 0, v[158:159]
	s_mov_b32 m0, s40
	s_nop 0
	global_load_lds_dwordx4 v[226:227], off
	s_waitcnt vmcnt(8)
	s_waitcnt lgkmcnt(0)
	s_barrier
	s_setprio 1
	s_waitcnt lgkmcnt(0)
	v_mfma_f32_16x16x32_bf16 v[124:127], v[128:131], v[178:181], v[124:127]
	v_mfma_f32_16x16x32_bf16 v[120:123], v[136:139], v[178:181], v[120:123]
	v_mfma_f32_16x16x32_bf16 v[108:111], v[128:131], v[196:199], v[108:111]
	v_mfma_f32_16x16x32_bf16 v[104:107], v[136:139], v[196:199], v[104:107]
	v_mfma_f32_16x16x32_bf16 v[92:95], v[128:131], v[204:207], v[92:95]
	v_mfma_f32_16x16x32_bf16 v[88:91], v[136:139], v[204:207], v[88:91]
	v_mfma_f32_16x16x32_bf16 v[76:79], v[128:131], v[212:215], v[76:79]
	v_mfma_f32_16x16x32_bf16 v[72:75], v[136:139], v[212:215], v[72:75]
	v_mfma_f32_16x16x32_bf16 v[124:127], v[132:135], v[182:185], v[124:127]
	v_mfma_f32_16x16x32_bf16 v[120:123], v[140:143], v[182:185], v[120:123]
	v_mfma_f32_16x16x32_bf16 v[108:111], v[132:135], v[200:203], v[108:111]
	v_mfma_f32_16x16x32_bf16 v[104:107], v[140:143], v[200:203], v[104:107]
	v_mfma_f32_16x16x32_bf16 v[92:95], v[132:135], v[208:211], v[92:95]
	v_mfma_f32_16x16x32_bf16 v[88:91], v[140:143], v[208:211], v[88:91]
	v_mfma_f32_16x16x32_bf16 v[76:79], v[132:135], v[216:219], v[76:79]
	v_mfma_f32_16x16x32_bf16 v[72:75], v[140:143], v[216:219], v[72:75]
	s_setprio 0
	s_setprio 1
	v_mfma_f32_16x16x32_bf16 v[116:119], v[144:147], v[178:181], v[116:119]
	v_mfma_f32_16x16x32_bf16 v[112:115], v[170:173], v[178:181], v[112:115]
	v_mfma_f32_16x16x32_bf16 v[100:103], v[144:147], v[196:199], v[100:103]
	v_mfma_f32_16x16x32_bf16 v[96:99], v[170:173], v[196:199], v[96:99]
	v_mfma_f32_16x16x32_bf16 v[84:87], v[144:147], v[204:207], v[84:87]
	v_mfma_f32_16x16x32_bf16 v[80:83], v[170:173], v[204:207], v[80:83]
	v_mfma_f32_16x16x32_bf16 v[68:71], v[144:147], v[212:215], v[68:71]
	v_mfma_f32_16x16x32_bf16 v[64:67], v[170:173], v[212:215], v[64:67]
	v_mfma_f32_16x16x32_bf16 v[116:119], v[148:151], v[182:185], v[116:119]
	v_mfma_f32_16x16x32_bf16 v[112:115], v[174:177], v[182:185], v[112:115]
	v_mfma_f32_16x16x32_bf16 v[100:103], v[148:151], v[200:203], v[100:103]
	v_mfma_f32_16x16x32_bf16 v[96:99], v[174:177], v[200:203], v[96:99]
	v_mfma_f32_16x16x32_bf16 v[84:87], v[148:151], v[208:211], v[84:87]
	v_mfma_f32_16x16x32_bf16 v[80:83], v[174:177], v[208:211], v[80:83]
	v_mfma_f32_16x16x32_bf16 v[68:71], v[148:151], v[216:219], v[68:71]
	v_mfma_f32_16x16x32_bf16 v[64:67], v[174:177], v[216:219], v[64:67]
	s_setprio 0
	s_barrier
; #define PG8_BAR __builtin_amdgcn_s_barrier()
; template <class Epi, class Sched, bool ALIGN_EPI>
; __device__ __forceinline__ void gemm_phase(LAS unsigned char* lds, const Gemm g, const Sched& S, const Epi& E) {
;     ...
;         if constexpr (ALIGN_EPI) { if (wr == 0) PG8_BAR; }
	s_add_i32 s36, s53, s33
	v_lshl_add_u64 v[186:187], v[186:187], 0, s[14:15]
	s_mov_b32 m0, s36
	ds_read_b128 v[178:181], v193 offset:49152
	ds_read_b128 v[182:185], v193 offset:50176
	global_load_lds_dwordx4 v[186:187], off
	s_add_i32 m0, s36, 0x2000
	s_add_u32 s34, s34, 0x40080
	v_lshl_add_u64 v[186:187], v[220:221], 0, s[14:15]
	s_addc_u32 s35, s35, 0
	s_add_i32 s36, s54, s33
	ds_read_b128 v[196:199], v193 offset:51200
	ds_read_b128 v[200:203], v193 offset:52224
	global_load_lds_dwordx4 v[186:187], off
	v_lshl_add_u64 v[186:187], s[34:35], 0, v[156:157]
	s_mov_b32 m0, s36
	ds_read_b128 v[204:207], v193 offset:53248
	global_load_lds_dwordx4 v[186:187], off
	v_lshl_add_u64 v[186:187], s[34:35], 0, v[160:161]
	s_add_i32 m0, s36, 0x2000
	ds_read_b128 v[208:211], v193 offset:54272
	global_load_lds_dwordx4 v[186:187], off
	v_lshl_add_u64 v[186:187], v[222:223], 0, s[14:15]
	s_mov_b32 m0, s42
	ds_read_b128 v[212:215], v193 offset:55296
	global_load_lds_dwordx4 v[186:187], off
	v_lshl_add_u64 v[186:187], v[224:225], 0, s[14:15]
	s_mov_b32 m0, s43
	ds_read_b128 v[216:219], v193 offset:56320
	global_load_lds_dwordx4 v[186:187], off
	s_waitcnt vmcnt(8)
	s_waitcnt lgkmcnt(0)
	s_barrier
	s_setprio 1
	s_waitcnt lgkmcnt(0)
	v_mfma_f32_16x16x32_bf16 v[60:63], v[128:131], v[178:181], v[60:63]
	v_mfma_f32_16x16x32_bf16 v[56:59], v[136:139], v[178:181], v[56:59]
	v_mfma_f32_16x16x32_bf16 v[44:47], v[128:131], v[196:199], v[44:47]
	v_mfma_f32_16x16x32_bf16 v[40:43], v[136:139], v[196:199], v[40:43]
	v_mfma_f32_16x16x32_bf16 v[28:31], v[128:131], v[204:207], v[28:31]
	v_mfma_f32_16x16x32_bf16 v[24:27], v[136:139], v[204:207], v[24:27]
	v_mfma_f32_16x16x32_bf16 v[12:15], v[128:131], v[212:215], v[12:15]
	v_mfma_f32_16x16x32_bf16 v[8:11], v[136:139], v[212:215], v[8:11]
	v_mfma_f32_16x16x32_bf16 v[60:63], v[132:135], v[182:185], v[60:63]
	v_mfma_f32_16x16x32_bf16 v[56:59], v[140:143], v[182:185], v[56:59]
	v_mfma_f32_16x16x32_bf16 v[44:47], v[132:135], v[200:203], v[44:47]
	v_mfma_f32_16x16x32_bf16 v[40:43], v[140:143], v[200:203], v[40:43]
	v_mfma_f32_16x16x32_bf16 v[28:31], v[132:135], v[208:211], v[28:31]
	v_mfma_f32_16x16x32_bf16 v[24:27], v[140:143], v[208:211], v[24:27]
	v_mfma_f32_16x16x32_bf16 v[12:15], v[132:135], v[216:219], v[12:15]
	v_mfma_f32_16x16x32_bf16 v[8:11], v[140:143], v[216:219], v[8:11]
	s_setprio 0
	s_setprio 1
	v_mfma_f32_16x16x32_bf16 v[52:55], v[144:147], v[178:181], v[52:55]
	v_mfma_f32_16x16x32_bf16 v[48:51], v[170:173], v[178:181], v[48:51]
	v_mfma_f32_16x16x32_bf16 v[36:39], v[144:147], v[196:199], v[36:39]
	v_mfma_f32_16x16x32_bf16 v[32:35], v[170:173], v[196:199], v[32:35]
	v_mfma_f32_16x16x32_bf16 v[20:23], v[144:147], v[204:207], v[20:23]
	v_mfma_f32_16x16x32_bf16 v[16:19], v[170:173], v[204:207], v[16:19]
	v_mfma_f32_16x16x32_bf16 v[4:7], v[144:147], v[212:215], v[4:7]
	v_mfma_f32_16x16x32_bf16 v[0:3], v[170:173], v[212:215], v[0:3]
	v_mfma_f32_16x16x32_bf16 v[52:55], v[148:151], v[182:185], v[52:55]
	v_mfma_f32_16x16x32_bf16 v[48:51], v[174:177], v[182:185], v[48:51]
	v_mfma_f32_16x16x32_bf16 v[36:39], v[148:151], v[200:203], v[36:39]
	v_mfma_f32_16x16x32_bf16 v[32:35], v[174:177], v[200:203], v[32:35]
	v_mfma_f32_16x16x32_bf16 v[20:23], v[148:151], v[208:211], v[20:23]
	v_mfma_f32_16x16x32_bf16 v[16:19], v[174:177], v[208:211], v[16:19]
	v_mfma_f32_16x16x32_bf16 v[4:7], v[148:151], v[216:219], v[4:7]
	v_mfma_f32_16x16x32_bf16 v[0:3], v[174:177], v[216:219], v[0:3]
	s_setprio 0
	s_barrier
	s_add_i32 s52, s52, 2
	s_add_u32 s30, s30, 0x100
	s_addc_u32 s31, s31, 0
	s_add_u32 s50, s50, 0x100
	s_addc_u32 s51, s51, 0
	s_cmp_gt_u32 s52, 13
	s_cbranch_scc0 .LBB0_1457
	s_and_b64 vcc, exec, s[16:17]
	s_cbranch_vccz .LBB0_1460
	s_barrier

; template <class Epi, class Sched, bool ALIGN_EPI>
; __device__ __forceinline__ void gemm_phase(LAS unsigned char* lds, const Gemm g, const Sched& S, const Epi& E) {
;     ...
;         const bool has_next = S.next(ui + 1, nxt);
;         const char* nA = has_next ? (const char*)g.A + (size_t)nxt.pm * tstepA : cA; const char* nB = has_next ? (const char*)g.Bt + (size_t)nxt.pn * tstepB : cB;
.LBB0_1612:
	s_ashr_i32 s13, s12, 31
	s_lshl_b64 s[14:15], s[12:13], 19
	s_add_u32 s14, s27, s14
	s_addc_u32 s15, s28, s15
	s_and_b64 s[16:17], s[2:3], exec
	s_cselect_b32 s13, s15, s21
	s_cselect_b32 s45, s14, s20
	s_ashr_i32 s11, s10, 31
	s_lshl_b64 s[16:17], s[10:11], 19
	s_add_u32 s16, s29, s16
	s_addc_u32 s17, s30, s17
	s_and_b64 s[24:25], s[2:3], exec
	s_cselect_b32 s11, s17, s23
	s_cselect_b32 s46, s16, s22
	s_add_u32 s20, s20, 0x40080
	s_addc_u32 s21, s21, 0
	s_add_u32 s47, s22, 0x100
	v_mov_b32_e32 v0, 0
	s_addc_u32 s48, s23, 0
	s_mov_b32 s49, -2
	ds_read_b128 v[154:157], v148
	ds_read_b128 v[158:161], v148 offset:1024
	ds_read_b128 v[162:165], v148 offset:2048
	ds_read_b128 v[166:169], v148 offset:3072
	ds_read_b128 v[170:173], v149
	ds_read_b128 v[174:177], v149 offset:1024
	ds_read_b128 v[178:181], v149 offset:2048
	ds_read_b128 v[182:185], v149 offset:3072
	s_add_u32 s22, s20, 0xfffc0080
	s_addc_u32 s23, s21, -1
	s_cmp_eq_u32 s49, 12
	s_cselect_b32 s25, s13, s23
	s_cselect_b32 s24, s45, s22
	s_cselect_b32 s23, s11, s48
	s_cselect_b32 s22, s46, s47
	v_lshl_add_u64 v[218:219], s[20:21], 0, v[136:137]
	s_add_i32 m0, s19, 0xc000
	ds_read_b128 v[186:189], v150
	ds_read_b128 v[190:193], v150 offset:1024
	ds_read_b128 v[194:197], v150 offset:2048
	ds_read_b128 v[198:201], v150 offset:3072
	ds_read_b128 v[202:205], v150 offset:4096
	ds_read_b128 v[206:209], v150 offset:5120
	ds_read_b128 v[210:213], v150 offset:6144
	ds_read_b128 v[214:217], v150 offset:7168
	global_load_lds_dwordx4 v[218:219], off
	v_lshl_add_u64 v[218:219], s[20:21], 0, v[138:139]
	s_add_i32 m0, s19, 0xe000
	s_nop 0
	global_load_lds_dwordx4 v[218:219], off
	s_cmp_eq_u32 s101, 1
	s_cbranch_scc1 .Lpk1613_r1
	s_waitcnt vmcnt(8)
	s_branch .Lpk1613_j1

.Lpk1613_j1:
	s_waitcnt lgkmcnt(0)
	s_barrier
	s_setprio 1
	s_waitcnt lgkmcnt(0)
	v_mfma_f32_16x16x32_bf16 v[124:127], v[154:157], v[186:189], 0
	v_mfma_f32_16x16x32_bf16 v[116:119], v[162:165], v[186:189], 0
	v_mfma_f32_16x16x32_bf16 v[108:111], v[154:157], v[194:197], 0
	v_mfma_f32_16x16x32_bf16 v[100:103], v[162:165], v[194:197], 0
	v_mfma_f32_16x16x32_bf16 v[92:95], v[154:157], v[202:205], 0
	v_mfma_f32_16x16x32_bf16 v[84:87], v[162:165], v[202:205], 0
	v_mfma_f32_16x16x32_bf16 v[76:79], v[154:157], v[210:213], 0
	v_mfma_f32_16x16x32_bf16 v[68:71], v[162:165], v[210:213], 0
	v_mfma_f32_16x16x32_bf16 v[124:127], v[158:161], v[190:193], v[124:127]
	v_mfma_f32_16x16x32_bf16 v[116:119], v[166:169], v[190:193], v[116:119]
	v_mfma_f32_16x16x32_bf16 v[108:111], v[158:161], v[198:201], v[108:111]
	v_mfma_f32_16x16x32_bf16 v[100:103], v[166:169], v[198:201], v[100:103]
	v_mfma_f32_16x16x32_bf16 v[92:95], v[158:161], v[206:209], v[92:95]
	v_mfma_f32_16x16x32_bf16 v[84:87], v[166:169], v[206:209], v[84:87]
	v_mfma_f32_16x16x32_bf16 v[76:79], v[158:161], v[214:217], v[76:79]
	v_mfma_f32_16x16x32_bf16 v[68:71], v[166:169], v[214:217], v[68:71]
	s_setprio 0
	s_setprio 1
	v_mfma_f32_16x16x32_bf16 v[120:123], v[170:173], v[186:189], 0
	v_mfma_f32_16x16x32_bf16 v[112:115], v[178:181], v[186:189], 0
	v_mfma_f32_16x16x32_bf16 v[104:107], v[170:173], v[194:197], 0
	v_mfma_f32_16x16x32_bf16 v[96:99], v[178:181], v[194:197], 0
	v_mfma_f32_16x16x32_bf16 v[88:91], v[170:173], v[202:205], 0
	v_mfma_f32_16x16x32_bf16 v[80:83], v[178:181], v[202:205], 0
	v_mfma_f32_16x16x32_bf16 v[72:75], v[170:173], v[210:213], 0
	v_mfma_f32_16x16x32_bf16 v[64:67], v[178:181], v[210:213], 0
	v_mfma_f32_16x16x32_bf16 v[120:123], v[174:177], v[190:193], v[120:123]
	v_mfma_f32_16x16x32_bf16 v[112:115], v[182:185], v[190:193], v[112:115]
	v_mfma_f32_16x16x32_bf16 v[104:107], v[174:177], v[198:201], v[104:107]
	v_mfma_f32_16x16x32_bf16 v[96:99], v[182:185], v[198:201], v[96:99]
	v_mfma_f32_16x16x32_bf16 v[88:91], v[174:177], v[206:209], v[88:91]
	v_mfma_f32_16x16x32_bf16 v[80:83], v[182:185], v[206:209], v[80:83]
	v_mfma_f32_16x16x32_bf16 v[72:75], v[174:177], v[214:217], v[72:75]
	v_mfma_f32_16x16x32_bf16 v[64:67], v[182:185], v[214:217], v[64:67]
	s_setprio 0
	s_barrier
	s_add_i32 s50, s38, s26
	v_lshl_add_u64 v[218:219], s[22:23], 0, v[132:133]
	s_mov_b32 m0, s50
	ds_read_b128 v[186:189], v150 offset:16384
	ds_read_b128 v[190:193], v150 offset:17408
	global_load_lds_dwordx4 v[218:219], off
	s_add_i32 m0, s50, 0x2000
	s_add_u32 s50, s22, 0x40000
	v_lshl_add_u64 v[220:221], s[22:23], 0, v[128:129]
	s_addc_u32 s51, s23, 0
	s_add_i32 s52, s39, s26
	ds_read_b128 v[194:197], v150 offset:18432
	ds_read_b128 v[198:201], v150 offset:19456
	global_load_lds_dwordx4 v[220:221], off
	v_lshl_add_u64 v[222:223], s[50:51], 0, v[132:133]
	s_mov_b32 m0, s52
	v_lshl_add_u64 v[224:225], s[24:25], 0, v[130:131]
	ds_read_b128 v[202:205], v150 offset:20480
	global_load_lds_dwordx4 v[222:223], off
	v_lshl_add_u64 v[222:223], s[50:51], 0, v[128:129]
	s_add_i32 m0, s52, 0x2000
	ds_read_b128 v[206:209], v150 offset:21504
	global_load_lds_dwordx4 v[222:223], off
	v_lshl_add_u64 v[222:223], s[24:25], 0, v[134:135]
	s_mov_b32 m0, s19
	ds_read_b128 v[210:213], v150 offset:22528
	global_load_lds_dwordx4 v[222:223], off
	s_mov_b32 m0, s33
	ds_read_b128 v[214:217], v150 offset:23552
	global_load_lds_dwordx4 v[224:225], off
	s_cmp_eq_u32 s101, 1
	s_cbranch_scc1 .Lpk1613_r2
	s_waitcnt vmcnt(8)
	s_branch .Lpk1613_j2

.Lpk1613_seg3:
	s_add_i32 s50, 0, 0x18000
	v_add_u32_e32 v151, s50, v145
	s_add_i32 s51, 0, 0x1c000
	ds_read_b128 v[154:157], v151
	ds_read_b128 v[158:161], v151 offset:1024
	ds_read_b128 v[162:165], v151 offset:2048
	ds_read_b128 v[166:169], v151 offset:3072
	v_add_u32_e32 v151, s51, v145
	ds_read_b128 v[170:173], v151
	ds_read_b128 v[174:177], v151 offset:1024
	ds_read_b128 v[178:181], v151 offset:2048
	ds_read_b128 v[182:185], v151 offset:3072
	s_add_u32 s24, s24, 0x40000
	s_addc_u32 s25, s25, 0
	s_mov_b32 m0, s34
	v_lshl_add_u64 v[226:227], s[24:25], 0, v[134:135]
	ds_read_b128 v[186:189], v150 offset:32768
	ds_read_b128 v[190:193], v150 offset:33792
	ds_read_b128 v[194:197], v150 offset:34816
	ds_read_b128 v[198:201], v150 offset:35840
	ds_read_b128 v[202:205], v150 offset:36864
	ds_read_b128 v[206:209], v150 offset:37888
	ds_read_b128 v[210:213], v150 offset:38912
	ds_read_b128 v[214:217], v150 offset:39936
	global_load_lds_dwordx4 v[226:227], off
	v_lshl_add_u64 v[226:227], s[24:25], 0, v[130:131]
	s_mov_b32 m0, s35
	s_nop 0
	global_load_lds_dwordx4 v[226:227], off
	s_waitcnt vmcnt(8)
	s_waitcnt lgkmcnt(0)
	s_barrier
	s_setprio 1
	s_waitcnt lgkmcnt(0)
	v_mfma_f32_16x16x32_bf16 v[124:127], v[154:157], v[186:189], v[124:127]
	v_mfma_f32_16x16x32_bf16 v[116:119], v[162:165], v[186:189], v[116:119]
	v_mfma_f32_16x16x32_bf16 v[108:111], v[154:157], v[194:197], v[108:111]
	v_mfma_f32_16x16x32_bf16 v[100:103], v[162:165], v[194:197], v[100:103]
	v_mfma_f32_16x16x32_bf16 v[92:95], v[154:157], v[202:205], v[92:95]
	v_mfma_f32_16x16x32_bf16 v[84:87], v[162:165], v[202:205], v[84:87]
	v_mfma_f32_16x16x32_bf16 v[76:79], v[154:157], v[210:213], v[76:79]
	v_mfma_f32_16x16x32_bf16 v[68:71], v[162:165], v[210:213], v[68:71]
	v_mfma_f32_16x16x32_bf16 v[124:127], v[158:161], v[190:193], v[124:127]
	v_mfma_f32_16x16x32_bf16 v[116:119], v[166:169], v[190:193], v[116:119]
	v_mfma_f32_16x16x32_bf16 v[108:111], v[158:161], v[198:201], v[108:111]
	v_mfma_f32_16x16x32_bf16 v[100:103], v[166:169], v[198:201], v[100:103]
	v_mfma_f32_16x16x32_bf16 v[92:95], v[158:161], v[206:209], v[92:95]
	v_mfma_f32_16x16x32_bf16 v[84:87], v[166:169], v[206:209], v[84:87]
	v_mfma_f32_16x16x32_bf16 v[76:79], v[158:161], v[214:217], v[76:79]
	v_mfma_f32_16x16x32_bf16 v[68:71], v[166:169], v[214:217], v[68:71]
	s_setprio 0
	s_setprio 1
	v_mfma_f32_16x16x32_bf16 v[120:123], v[170:173], v[186:189], v[120:123]
	v_mfma_f32_16x16x32_bf16 v[112:115], v[178:181], v[186:189], v[112:115]
	v_mfma_f32_16x16x32_bf16 v[104:107], v[170:173], v[194:197], v[104:107]
	v_mfma_f32_16x16x32_bf16 v[96:99], v[178:181], v[194:197], v[96:99]
	v_mfma_f32_16x16x32_bf16 v[88:91], v[170:173], v[202:205], v[88:91]
	v_mfma_f32_16x16x32_bf16 v[80:83], v[178:181], v[202:205], v[80:83]
	v_mfma_f32_16x16x32_bf16 v[72:75], v[170:173], v[210:213], v[72:75]
	v_mfma_f32_16x16x32_bf16 v[64:67], v[178:181], v[210:213], v[64:67]
	v_mfma_f32_16x16x32_bf16 v[120:123], v[174:177], v[190:193], v[120:123]
	v_mfma_f32_16x16x32_bf16 v[112:115], v[182:185], v[190:193], v[112:115]
	v_mfma_f32_16x16x32_bf16 v[104:107], v[174:177], v[198:201], v[104:107]
	v_mfma_f32_16x16x32_bf16 v[96:99], v[182:185], v[198:201], v[96:99]
	v_mfma_f32_16x16x32_bf16 v[88:91], v[174:177], v[206:209], v[88:91]
	v_mfma_f32_16x16x32_bf16 v[80:83], v[182:185], v[206:209], v[80:83]
	v_mfma_f32_16x16x32_bf16 v[72:75], v[174:177], v[214:217], v[72:75]
	v_mfma_f32_16x16x32_bf16 v[64:67], v[182:185], v[214:217], v[64:67]
	s_setprio 0
	s_barrier
	s_add_i32 s24, s50, s26
	v_lshl_add_u64 v[218:219], v[218:219], 0, s[6:7]
	s_mov_b32 m0, s24
	ds_read_b128 v[186:189], v150 offset:49152
	ds_read_b128 v[190:193], v150 offset:50176
	global_load_lds_dwordx4 v[218:219], off
	s_add_i32 m0, s24, 0x2000
	s_add_u32 s22, s22, 0x40080
	v_lshl_add_u64 v[218:219], v[220:221], 0, s[6:7]
	s_addc_u32 s23, s23, 0
	s_add_i32 s24, s51, s26
	ds_read_b128 v[194:197], v150 offset:51200
	ds_read_b128 v[198:201], v150 offset:52224
	global_load_lds_dwordx4 v[218:219], off
	v_lshl_add_u64 v[218:219], s[22:23], 0, v[132:133]
	s_mov_b32 m0, s24
	ds_read_b128 v[202:205], v150 offset:53248
	global_load_lds_dwordx4 v[218:219], off
	v_lshl_add_u64 v[218:219], s[22:23], 0, v[128:129]
	s_add_i32 m0, s24, 0x2000
	ds_read_b128 v[206:209], v150 offset:54272
	global_load_lds_dwordx4 v[218:219], off
	v_lshl_add_u64 v[218:219], v[222:223], 0, s[6:7]
	s_mov_b32 m0, s36
	ds_read_b128 v[210:213], v150 offset:55296
	global_load_lds_dwordx4 v[218:219], off
	v_lshl_add_u64 v[218:219], v[224:225], 0, s[6:7]
	s_mov_b32 m0, s37
	ds_read_b128 v[214:217], v150 offset:56320
	global_load_lds_dwordx4 v[218:219], off
	s_waitcnt vmcnt(8)
	s_waitcnt lgkmcnt(0)
	s_barrier
; __device__ __forceinline__ unsigned cvt_pk_bf16(float lo, float hi) { unsigned r; asm volatile("v_cvt_pk_bf16_f32 %0, %1, %2" : "=v"(r) : "v"(lo), "v"(hi)); return r; }
;     __device__ __forceinline__ void operator()(Acc& acc, const Unit& u, int wr, int wc, int fr, int fq) const { scale(acc, u, wr, wc, fr, fq, PC_GA, true); }
;     __device__ __forceinline__ void operator()(Acc& acc, const Unit& u, int wr, int wc, int fr, int fq) const {
;         const int row0 = u.pm * BM + wr * 64 + fr, col0 = u.pn * 128 + wc * 32 + 8 * fq;
; #pragma unroll
;         for (int ai = 0; ai < 2; ++ai)
; #pragma unroll
;             for (int m = 0; m < 4; ++m) {
;                 const int row = row0 + ai * HALF + m * 16;
;                 const float r = rs[u.idx * BM + wr * 64 + fr + ai * HALF + m * 16];
;                 const float c1 = -r * 1.4426950408889634f, r2 = r * r;
;                 f32x4 o[2];
; #pragma unroll
;                 for (int n = 0; n < 2; ++n) {
;                     const f32x4 g = acc[ai][0][m][n], up = acc[ai][1][m][n];
;                     const f32x4 t = g * c1; f32x4 e;
; #pragma unroll
;                     for (int i = 0; i < 4; ++i) e[i] = __builtin_amdgcn_exp2f(t[i]);
;                     const f32x4 d = e + 1.0f; f32x4 q;
; #pragma unroll
;                     for (int i = 0; i < 4; ++i) q[i] = __builtin_amdgcn_rcpf(d[i]);
;                     o[n] = (g * up) * (q * r2);
;                 }
;                 u32x4 w; w.x = cvt_pk_bf16(o[0][0], o[0][1]); w.y = cvt_pk_bf16(o[0][2], o[0][3]); w.z = cvt_pk_bf16(o[1][0], o[1][1]); w.w = cvt_pk_bf16(o[1][2], o[1][3]);
;                 *(u32x4*)(O + (size_t)row * DFF + col0) = w;
;             }
	s_setprio 1
	s_waitcnt lgkmcnt(0)
	v_mfma_f32_16x16x32_bf16 v[60:63], v[154:157], v[186:189], v[60:63]
	v_mfma_f32_16x16x32_bf16 v[52:55], v[162:165], v[186:189], v[52:55]
	v_mfma_f32_16x16x32_bf16 v[44:47], v[154:157], v[194:197], v[44:47]
	v_mfma_f32_16x16x32_bf16 v[36:39], v[162:165], v[194:197], v[36:39]
	v_mfma_f32_16x16x32_bf16 v[28:31], v[154:157], v[202:205], v[28:31]
	v_mfma_f32_16x16x32_bf16 v[20:23], v[162:165], v[202:205], v[20:23]
	v_mfma_f32_16x16x32_bf16 v[12:15], v[154:157], v[210:213], v[12:15]
	v_mfma_f32_16x16x32_bf16 v[4:7], v[162:165], v[210:213], v[4:7]
	v_mfma_f32_16x16x32_bf16 v[60:63], v[158:161], v[190:193], v[60:63]
	v_mfma_f32_16x16x32_bf16 v[52:55], v[166:169], v[190:193], v[52:55]
	v_mfma_f32_16x16x32_bf16 v[44:47], v[158:161], v[198:201], v[44:47]
	v_mfma_f32_16x16x32_bf16 v[36:39], v[166:169], v[198:201], v[36:39]
	v_mfma_f32_16x16x32_bf16 v[28:31], v[158:161], v[206:209], v[28:31]
	v_mfma_f32_16x16x32_bf16 v[20:23], v[166:169], v[206:209], v[20:23]
	v_mfma_f32_16x16x32_bf16 v[12:15], v[158:161], v[214:217], v[12:15]
	v_mfma_f32_16x16x32_bf16 v[4:7], v[166:169], v[214:217], v[4:7]
	s_setprio 0
	s_setprio 1
	v_mfma_f32_16x16x32_bf16 v[56:59], v[170:173], v[186:189], v[56:59]
	v_mfma_f32_16x16x32_bf16 v[48:51], v[178:181], v[186:189], v[48:51]
	v_mfma_f32_16x16x32_bf16 v[40:43], v[170:173], v[194:197], v[40:43]
	v_mfma_f32_16x16x32_bf16 v[32:35], v[178:181], v[194:197], v[32:35]
	v_mfma_f32_16x16x32_bf16 v[24:27], v[170:173], v[202:205], v[24:27]
	v_mfma_f32_16x16x32_bf16 v[16:19], v[178:181], v[202:205], v[16:19]
	v_mfma_f32_16x16x32_bf16 v[8:11], v[170:173], v[210:213], v[8:11]
	v_mfma_f32_16x16x32_bf16 v[0:3], v[178:181], v[210:213], v[0:3]
	v_mfma_f32_16x16x32_bf16 v[56:59], v[174:177], v[190:193], v[56:59]
	v_mfma_f32_16x16x32_bf16 v[48:51], v[182:185], v[190:193], v[48:51]
	v_mfma_f32_16x16x32_bf16 v[40:43], v[174:177], v[198:201], v[40:43]
	v_mfma_f32_16x16x32_bf16 v[32:35], v[182:185], v[198:201], v[32:35]
	v_mfma_f32_16x16x32_bf16 v[24:27], v[174:177], v[206:209], v[24:27]
	v_mfma_f32_16x16x32_bf16 v[16:19], v[182:185], v[206:209], v[16:19]
	v_mfma_f32_16x16x32_bf16 v[8:11], v[174:177], v[214:217], v[8:11]
	v_mfma_f32_16x16x32_bf16 v[0:3], v[182:185], v[214:217], v[0:3]
	s_setprio 0
	s_barrier
	s_add_i32 s49, s49, 2
	s_add_u32 s20, s20, 0x100
	s_addc_u32 s21, s21, 0
	s_add_u32 s47, s47, 0x100
	s_addc_u32 s48, s48, 0
	s_cmp_gt_u32 s49, 13
	s_cbranch_scc0 .LBB0_1613
	s_and_b64 vcc, exec, s[8:9]
	s_cbranch_vccz .LBB0_1616
	s_barrier
.LBB0_1616:
	v_lshl_add_u32 v154, s43, 10, v146
	ds_read_b32 v155, v154
	v_pk_mul_f32 v[122:123], v[126:127], v[122:123]
	v_pk_mul_f32 v[120:121], v[124:125], v[120:121]
	v_pk_mul_f32 v[114:115], v[118:119], v[114:115]
	v_pk_mul_f32 v[112:113], v[116:117], v[112:113]
	s_waitcnt lgkmcnt(0)
	v_mul_f32_e32 v158, 0xbfb8aa3b, v155
	v_pk_mul_f32 v[164:165], v[124:125], v[158:159] op_sel_hi:[1,0]
	v_mul_f32_e32 v160, v155, v155
	v_exp_f32_e32 v155, v164
	v_pk_mul_f32 v[162:163], v[126:127], v[158:159] op_sel_hi:[1,0]
	v_exp_f32_e32 v159, v165
	v_exp_f32_e32 v161, v162
	v_exp_f32_e32 v165, v163
	v_add_f32_e32 v155, 1.0, v155
	v_rcp_f32_e32 v162, v155
	v_add_f32_e32 v155, 1.0, v159
	v_rcp_f32_e32 v163, v155
	v_add_f32_e32 v155, 1.0, v161
	v_rcp_f32_e32 v164, v155
	v_add_f32_e32 v155, 1.0, v165
	v_rcp_f32_e32 v165, v155
	v_pk_mul_f32 v[124:125], v[160:161], v[162:163] op_sel_hi:[0,1]
	v_pk_mul_f32 v[120:121], v[120:121], v[124:125]
	v_pk_mul_f32 v[124:125], v[118:119], v[158:159] op_sel_hi:[1,0]
	v_pk_mul_f32 v[126:127], v[160:161], v[164:165] op_sel_hi:[0,1]
	v_pk_mul_f32 v[122:123], v[122:123], v[126:127]
	v_pk_mul_f32 v[126:127], v[116:117], v[158:159] op_sel_hi:[1,0]
	v_exp_f32_e32 v155, v124
	v_exp_f32_e32 v126, v126
	v_exp_f32_e32 v127, v127
	v_exp_f32_e32 v158, v125
	v_lshl_or_b32 v156, s44, 7, v147
	v_add_f32_e32 v124, 1.0, v126
	v_add_f32_e32 v125, 1.0, v127
	v_add_f32_e32 v126, 1.0, v155
	v_add_f32_e32 v127, 1.0, v158
	v_rcp_f32_e32 v124, v124
	v_rcp_f32_e32 v125, v125
	v_rcp_f32_e32 v126, v126
	v_rcp_f32_e32 v127, v127
	v_lshl_add_u32 v151, s18, 8, v144
	v_pk_mul_f32 v[116:117], v[160:161], v[124:125] op_sel_hi:[0,1]
	v_pk_mul_f32 v[112:113], v[112:113], v[116:117]
	v_pk_mul_f32 v[118:119], v[160:161], v[126:127] op_sel_hi:[0,1]
	v_pk_mul_f32 v[114:115], v[114:115], v[118:119]
	v_cvt_pk_bf16_f32 v116, v120, v121
	v_cvt_pk_bf16_f32 v117, v122, v123
	v_cvt_pk_bf16_f32 v118, v112, v113
	v_ashrrev_i32_e32 v157, 31, v156
	v_cvt_pk_bf16_f32 v119, v114, v115
	ds_read_b32 v122, v154 offset:64
	v_mov_b64_e32 v[112:113], s[64:65]
	v_mad_i64_i32 v[120:121], s[20:21], v151, s40, v[112:113]
	v_lshlrev_b64 v[114:115], 1, v[156:157]
	v_lshl_add_u64 v[120:121], v[120:121], 0, v[114:115]
	global_store_dwordx4 v[120:121], v[116:119], off
	v_pk_mul_f32 v[106:107], v[110:111], v[106:107]
	v_pk_mul_f32 v[104:105], v[108:109], v[104:105]
	s_waitcnt lgkmcnt(0)
; __device__ __forceinline__ unsigned cvt_pk_bf16(float lo, float hi) { unsigned r; asm volatile("v_cvt_pk_bf16_f32 %0, %1, %2" : "=v"(r) : "v"(lo), "v"(hi)); return r; }
;     __device__ __forceinline__ void operator()(Acc& acc, const Unit& u, int wr, int wc, int fr, int fq) const {
;         const int row0 = u.pm * BM + wr * 64 + fr, col0 = u.pn * 128 + wc * 32 + 8 * fq;
; #pragma unroll
;         for (int ai = 0; ai < 2; ++ai)
; #pragma unroll
;             for (int m = 0; m < 4; ++m) {
;                 const int row = row0 + ai * HALF + m * 16;
;                 const float r = rs[u.idx * BM + wr * 64 + fr + ai * HALF + m * 16];
;                 const float c1 = -r * 1.4426950408889634f, r2 = r * r;
;                 f32x4 o[2];
; #pragma unroll
;                 for (int n = 0; n < 2; ++n) {
;                     const f32x4 g = acc[ai][0][m][n], up = acc[ai][1][m][n];
;                     const f32x4 t = g * c1; f32x4 e;
; #pragma unroll
;                     for (int i = 0; i < 4; ++i) e[i] = __builtin_amdgcn_exp2f(t[i]);
;                     const f32x4 d = e + 1.0f; f32x4 q;
; #pragma unroll
;                     for (int i = 0; i < 4; ++i) q[i] = __builtin_amdgcn_rcpf(d[i]);
;                     o[n] = (g * up) * (q * r2);
;                 }
;                 u32x4 w; w.x = cvt_pk_bf16(o[0][0], o[0][1]); w.y = cvt_pk_bf16(o[0][2], o[0][3]); w.z = cvt_pk_bf16(o[1][0], o[1][1]); w.w = cvt_pk_bf16(o[1][2], o[1][3]);
;                 *(u32x4*)(O + (size_t)row * DFF + col0) = w;
	v_mul_f32_e32 v116, 0xbfb8aa3b, v122
	v_mul_f32_e32 v118, v122, v122
	v_pk_mul_f32 v[122:123], v[108:109], v[116:117] op_sel_hi:[1,0]
	v_pk_mul_f32 v[120:121], v[110:111], v[116:117] op_sel_hi:[1,0]
	v_exp_f32_e32 v117, v122
	v_exp_f32_e32 v119, v123
	v_exp_f32_e32 v122, v120
	v_exp_f32_e32 v123, v121
	v_add_f32_e32 v117, 1.0, v117
	v_rcp_f32_e32 v120, v117
	v_add_f32_e32 v117, 1.0, v119
	v_rcp_f32_e32 v121, v117
	v_add_f32_e32 v117, 1.0, v122
	v_rcp_f32_e32 v122, v117
	v_add_f32_e32 v117, 1.0, v123
	v_rcp_f32_e32 v123, v117
	v_pk_mul_f32 v[108:109], v[118:119], v[120:121] op_sel_hi:[0,1]
	v_pk_mul_f32 v[104:105], v[104:105], v[108:109]
	v_pk_mul_f32 v[108:109], v[102:103], v[116:117] op_sel_hi:[1,0]
	v_pk_mul_f32 v[110:111], v[118:119], v[122:123] op_sel_hi:[0,1]
	v_pk_mul_f32 v[106:107], v[106:107], v[110:111]
	v_pk_mul_f32 v[110:111], v[100:101], v[116:117] op_sel_hi:[1,0]
	v_exp_f32_e32 v116, v108
	v_exp_f32_e32 v110, v110
	v_exp_f32_e32 v111, v111
	v_exp_f32_e32 v117, v109
	v_pk_mul_f32 v[98:99], v[102:103], v[98:99]
	v_add_f32_e32 v108, 1.0, v110
	v_add_f32_e32 v109, 1.0, v111
	v_add_f32_e32 v110, 1.0, v116
	v_add_f32_e32 v111, 1.0, v117
	v_rcp_f32_e32 v108, v108
	v_rcp_f32_e32 v109, v109
	v_rcp_f32_e32 v110, v110
	v_rcp_f32_e32 v111, v111
	v_pk_mul_f32 v[96:97], v[100:101], v[96:97]
	v_pk_mul_f32 v[100:101], v[118:119], v[108:109] op_sel_hi:[0,1]
	v_pk_mul_f32 v[90:91], v[94:95], v[90:91]
	v_pk_mul_f32 v[102:103], v[118:119], v[110:111] op_sel_hi:[0,1]
	v_pk_mul_f32 v[102:103], v[98:99], v[102:103]
	v_pk_mul_f32 v[98:99], v[96:97], v[100:101]
	v_cvt_pk_bf16_f32 v96, v104, v105
	v_cvt_pk_bf16_f32 v97, v106, v107
	v_or_b32_e32 v100, 16, v151
	v_cvt_pk_bf16_f32 v98, v98, v99
	v_cvt_pk_bf16_f32 v99, v102, v103
	ds_read_b32 v102, v154 offset:128
	v_mad_i64_i32 v[100:101], s[20:21], v100, s40, v[112:113]
	v_lshl_add_u64 v[100:101], v[100:101], 0, v[114:115]
	global_store_dwordx4 v[100:101], v[96:99], off
	v_pk_mul_f32 v[88:89], v[92:93], v[88:89]
	v_pk_mul_f32 v[82:83], v[86:87], v[82:83]
	s_waitcnt lgkmcnt(0)
	v_mul_f32_e32 v96, 0xbfb8aa3b, v102
	v_mul_f32_e32 v98, v102, v102
	v_pk_mul_f32 v[102:103], v[92:93], v[96:97] op_sel_hi:[1,0]
	v_pk_mul_f32 v[100:101], v[94:95], v[96:97] op_sel_hi:[1,0]
	v_exp_f32_e32 v97, v102
	v_exp_f32_e32 v99, v103
	v_exp_f32_e32 v102, v100
	v_exp_f32_e32 v103, v101
	v_add_f32_e32 v97, 1.0, v97
	v_rcp_f32_e32 v100, v97
	v_add_f32_e32 v97, 1.0, v99
	v_rcp_f32_e32 v101, v97
	v_add_f32_e32 v97, 1.0, v102
	v_rcp_f32_e32 v102, v97
	v_add_f32_e32 v97, 1.0, v103
	v_rcp_f32_e32 v103, v97
	v_pk_mul_f32 v[92:93], v[98:99], v[100:101] op_sel_hi:[0,1]
	v_pk_mul_f32 v[88:89], v[88:89], v[92:93]
	v_pk_mul_f32 v[92:93], v[86:87], v[96:97] op_sel_hi:[1,0]
	v_pk_mul_f32 v[94:95], v[98:99], v[102:103] op_sel_hi:[0,1]
	v_pk_mul_f32 v[90:91], v[90:91], v[94:95]
	v_pk_mul_f32 v[94:95], v[84:85], v[96:97] op_sel_hi:[1,0]
	v_exp_f32_e32 v96, v92
	v_exp_f32_e32 v94, v94
	v_exp_f32_e32 v95, v95
	v_exp_f32_e32 v97, v93
	v_pk_mul_f32 v[80:81], v[84:85], v[80:81]
	v_add_f32_e32 v92, 1.0, v94
	v_add_f32_e32 v93, 1.0, v95
	v_add_f32_e32 v94, 1.0, v96
	v_add_f32_e32 v95, 1.0, v97
	v_rcp_f32_e32 v92, v92
	v_rcp_f32_e32 v93, v93
	v_rcp_f32_e32 v94, v94
	v_rcp_f32_e32 v95, v95
	v_pk_mul_f32 v[74:75], v[78:79], v[74:75]
	v_pk_mul_f32 v[84:85], v[98:99], v[92:93] op_sel_hi:[0,1]
	v_pk_mul_f32 v[72:73], v[76:77], v[72:73]
	v_pk_mul_f32 v[86:87], v[98:99], v[94:95] op_sel_hi:[0,1]
	v_pk_mul_f32 v[86:87], v[82:83], v[86:87]
	v_pk_mul_f32 v[82:83], v[80:81], v[84:85]
	v_cvt_pk_bf16_f32 v80, v88, v89
	v_cvt_pk_bf16_f32 v81, v90, v91
	v_or_b32_e32 v84, 32, v151
	v_cvt_pk_bf16_f32 v82, v82, v83
	v_cvt_pk_bf16_f32 v83, v86, v87
	ds_read_b32 v86, v154 offset:192
	v_mad_i64_i32 v[84:85], s[20:21], v84, s40, v[112:113]
	v_lshl_add_u64 v[84:85], v[84:85], 0, v[114:115]
	global_store_dwordx4 v[84:85], v[80:83], off
	v_pk_mul_f32 v[66:67], v[70:71], v[66:67]
	v_pk_mul_f32 v[64:65], v[68:69], v[64:65]
	s_waitcnt lgkmcnt(0)
	v_mul_f32_e32 v80, 0xbfb8aa3b, v86
	v_mul_f32_e32 v82, v86, v86
	v_pk_mul_f32 v[86:87], v[76:77], v[80:81] op_sel_hi:[1,0]
	v_pk_mul_f32 v[84:85], v[78:79], v[80:81] op_sel_hi:[1,0]
	v_exp_f32_e32 v81, v86
	v_exp_f32_e32 v83, v87
	v_exp_f32_e32 v86, v84
	v_exp_f32_e32 v87, v85
	v_add_f32_e32 v81, 1.0, v81
	v_rcp_f32_e32 v84, v81
	v_add_f32_e32 v81, 1.0, v83
	v_rcp_f32_e32 v85, v81
	v_add_f32_e32 v81, 1.0, v86
	v_rcp_f32_e32 v86, v81
	v_add_f32_e32 v81, 1.0, v87
	v_rcp_f32_e32 v87, v81
	v_pk_mul_f32 v[76:77], v[82:83], v[84:85] op_sel_hi:[0,1]
	v_pk_mul_f32 v[72:73], v[72:73], v[76:77]
	v_pk_mul_f32 v[76:77], v[70:71], v[80:81] op_sel_hi:[1,0]
	v_pk_mul_f32 v[78:79], v[82:83], v[86:87] op_sel_hi:[0,1]
	v_pk_mul_f32 v[74:75], v[74:75], v[78:79]
	v_pk_mul_f32 v[78:79], v[68:69], v[80:81] op_sel_hi:[1,0]
	v_exp_f32_e32 v80, v76
	v_exp_f32_e32 v78, v78
	v_exp_f32_e32 v79, v79
	v_exp_f32_e32 v81, v77
	v_pk_mul_f32 v[58:59], v[62:63], v[58:59]
	v_add_f32_e32 v76, 1.0, v78
	v_add_f32_e32 v77, 1.0, v79
	v_add_f32_e32 v78, 1.0, v80
	v_add_f32_e32 v79, 1.0, v81
	v_rcp_f32_e32 v76, v76
	v_rcp_f32_e32 v77, v77
	v_rcp_f32_e32 v78, v78
	v_rcp_f32_e32 v79, v79
	v_pk_mul_f32 v[56:57], v[60:61], v[56:57]
	v_pk_mul_f32 v[68:69], v[82:83], v[76:77] op_sel_hi:[0,1]
	v_pk_mul_f32 v[50:51], v[54:55], v[50:51]
	v_pk_mul_f32 v[70:71], v[82:83], v[78:79] op_sel_hi:[0,1]
	v_pk_mul_f32 v[70:71], v[66:67], v[70:71]
	v_pk_mul_f32 v[66:67], v[64:65], v[68:69]
	v_cvt_pk_bf16_f32 v64, v72, v73
	v_cvt_pk_bf16_f32 v65, v74, v75
	v_or_b32_e32 v68, 48, v151
	v_cvt_pk_bf16_f32 v66, v66, v67
	v_cvt_pk_bf16_f32 v67, v70, v71
	ds_read_b32 v70, v154 offset:512
	v_mad_i64_i32 v[68:69], s[20:21], v68, s40, v[112:113]
	v_lshl_add_u64 v[68:69], v[68:69], 0, v[114:115]
	global_store_dwordx4 v[68:69], v[64:67], off
	v_pk_mul_f32 v[48:49], v[52:53], v[48:49]
	v_pk_mul_f32 v[42:43], v[46:47], v[42:43]
	v_add_u32_e32 v65, 0x80, v151
	s_waitcnt lgkmcnt(0)
; __device__ __forceinline__ unsigned cvt_pk_bf16(float lo, float hi) { unsigned r; asm volatile("v_cvt_pk_bf16_f32 %0, %1, %2" : "=v"(r) : "v"(lo), "v"(hi)); return r; }
;     __device__ __forceinline__ void operator()(Acc& acc, const Unit& u, int wr, int wc, int fr, int fq) const {
;         const int row0 = u.pm * BM + wr * 64 + fr, col0 = u.pn * 128 + wc * 32 + 8 * fq;
; #pragma unroll
;         for (int ai = 0; ai < 2; ++ai)
; #pragma unroll
;             for (int m = 0; m < 4; ++m) {
;                 const int row = row0 + ai * HALF + m * 16;
;                 const float r = rs[u.idx * BM + wr * 64 + fr + ai * HALF + m * 16];
;                 const float c1 = -r * 1.4426950408889634f, r2 = r * r;
;                 f32x4 o[2];
; #pragma unroll
;                 for (int n = 0; n < 2; ++n) {
;                     const f32x4 g = acc[ai][0][m][n], up = acc[ai][1][m][n];
;                     const f32x4 t = g * c1; f32x4 e;
; #pragma unroll
;                     for (int i = 0; i < 4; ++i) e[i] = __builtin_amdgcn_exp2f(t[i]);
;                     const f32x4 d = e + 1.0f; f32x4 q;
; #pragma unroll
;                     for (int i = 0; i < 4; ++i) q[i] = __builtin_amdgcn_rcpf(d[i]);
;                     o[n] = (g * up) * (q * r2);
;                 }
;                 u32x4 w; w.x = cvt_pk_bf16(o[0][0], o[0][1]); w.y = cvt_pk_bf16(o[0][2], o[0][3]); w.z = cvt_pk_bf16(o[1][0], o[1][1]); w.w = cvt_pk_bf16(o[1][2], o[1][3]);
;                 *(u32x4*)(O + (size_t)row * DFF + col0) = w;
	v_mul_f32_e32 v64, 0xbfb8aa3b, v70
	v_mul_f32_e32 v66, v70, v70
	v_pk_mul_f32 v[70:71], v[60:61], v[64:65] op_sel_hi:[1,0]
	v_pk_mul_f32 v[68:69], v[62:63], v[64:65] op_sel_hi:[1,0]
	v_exp_f32_e32 v67, v70
	v_exp_f32_e32 v70, v71
	v_exp_f32_e32 v71, v68
	v_exp_f32_e32 v72, v69
	v_add_f32_e32 v67, 1.0, v67
	v_rcp_f32_e32 v68, v67
	v_add_f32_e32 v67, 1.0, v70
	v_rcp_f32_e32 v69, v67
	v_add_f32_e32 v67, 1.0, v71
	v_rcp_f32_e32 v70, v67
	v_add_f32_e32 v67, 1.0, v72
	v_rcp_f32_e32 v71, v67
	v_pk_mul_f32 v[60:61], v[66:67], v[68:69] op_sel_hi:[0,1]
	v_pk_mul_f32 v[56:57], v[56:57], v[60:61]
	v_pk_mul_f32 v[60:61], v[54:55], v[64:65] op_sel_hi:[1,0]
	v_pk_mul_f32 v[62:63], v[66:67], v[70:71] op_sel_hi:[0,1]
	v_pk_mul_f32 v[58:59], v[58:59], v[62:63]
	v_pk_mul_f32 v[62:63], v[52:53], v[64:65] op_sel_hi:[1,0]
	v_exp_f32_e32 v64, v60
	v_exp_f32_e32 v62, v62
	v_exp_f32_e32 v63, v63
	v_exp_f32_e32 v67, v61
	v_pk_mul_f32 v[40:41], v[44:45], v[40:41]
	v_add_f32_e32 v60, 1.0, v62
	v_add_f32_e32 v61, 1.0, v63
	v_add_f32_e32 v62, 1.0, v64
	v_add_f32_e32 v63, 1.0, v67
	v_rcp_f32_e32 v60, v60
	v_rcp_f32_e32 v61, v61
	v_rcp_f32_e32 v62, v62
	v_rcp_f32_e32 v63, v63
	v_pk_mul_f32 v[34:35], v[38:39], v[34:35]
	v_pk_mul_f32 v[52:53], v[66:67], v[60:61] op_sel_hi:[0,1]
	v_pk_mul_f32 v[32:33], v[36:37], v[32:33]
	v_pk_mul_f32 v[54:55], v[66:67], v[62:63] op_sel_hi:[0,1]
	v_pk_mul_f32 v[54:55], v[50:51], v[54:55]
	v_pk_mul_f32 v[50:51], v[48:49], v[52:53]
	v_cvt_pk_bf16_f32 v48, v56, v57
	v_cvt_pk_bf16_f32 v49, v58, v59
	v_mad_i64_i32 v[52:53], s[20:21], v65, s40, v[112:113]
	v_cvt_pk_bf16_f32 v50, v50, v51
	v_cvt_pk_bf16_f32 v51, v54, v55
	ds_read_b32 v54, v154 offset:576
	v_lshl_add_u64 v[52:53], v[52:53], 0, v[114:115]
	global_store_dwordx4 v[52:53], v[48:51], off
	v_pk_mul_f32 v[26:27], v[30:31], v[26:27]
	v_pk_mul_f32 v[24:25], v[28:29], v[24:25]
	s_waitcnt lgkmcnt(0)
	v_mul_f32_e32 v48, 0xbfb8aa3b, v54
	v_mul_f32_e32 v50, v54, v54
	v_pk_mul_f32 v[54:55], v[44:45], v[48:49] op_sel_hi:[1,0]
	v_pk_mul_f32 v[52:53], v[46:47], v[48:49] op_sel_hi:[1,0]
	v_exp_f32_e32 v49, v54
	v_exp_f32_e32 v51, v55
	v_exp_f32_e32 v54, v52
	v_exp_f32_e32 v55, v53
	v_add_f32_e32 v49, 1.0, v49
	v_rcp_f32_e32 v52, v49
	v_add_f32_e32 v49, 1.0, v51
	v_rcp_f32_e32 v53, v49
	v_add_f32_e32 v49, 1.0, v54
	v_rcp_f32_e32 v54, v49
	v_add_f32_e32 v49, 1.0, v55
	v_rcp_f32_e32 v55, v49
	v_pk_mul_f32 v[44:45], v[50:51], v[52:53] op_sel_hi:[0,1]
	v_pk_mul_f32 v[40:41], v[40:41], v[44:45]
	v_pk_mul_f32 v[44:45], v[38:39], v[48:49] op_sel_hi:[1,0]
	v_pk_mul_f32 v[46:47], v[50:51], v[54:55] op_sel_hi:[0,1]
	v_pk_mul_f32 v[42:43], v[42:43], v[46:47]
	v_pk_mul_f32 v[46:47], v[36:37], v[48:49] op_sel_hi:[1,0]
	v_exp_f32_e32 v48, v44
	v_exp_f32_e32 v46, v46
	v_exp_f32_e32 v47, v47
	v_exp_f32_e32 v49, v45
	v_pk_mul_f32 v[18:19], v[22:23], v[18:19]
	v_add_f32_e32 v44, 1.0, v46
	v_add_f32_e32 v45, 1.0, v47
	v_add_f32_e32 v46, 1.0, v48
	v_add_f32_e32 v47, 1.0, v49
	v_rcp_f32_e32 v44, v44
	v_rcp_f32_e32 v45, v45
	v_rcp_f32_e32 v46, v46
	v_rcp_f32_e32 v47, v47
	v_pk_mul_f32 v[16:17], v[20:21], v[16:17]
	v_pk_mul_f32 v[36:37], v[50:51], v[44:45] op_sel_hi:[0,1]
	v_pk_mul_f32 v[10:11], v[14:15], v[10:11]
	v_pk_mul_f32 v[38:39], v[50:51], v[46:47] op_sel_hi:[0,1]
	v_pk_mul_f32 v[38:39], v[34:35], v[38:39]
	v_pk_mul_f32 v[34:35], v[32:33], v[36:37]
	v_cvt_pk_bf16_f32 v32, v40, v41
	v_cvt_pk_bf16_f32 v33, v42, v43
	v_add_u32_e32 v36, 0x90, v151
	v_cvt_pk_bf16_f32 v34, v34, v35
	v_cvt_pk_bf16_f32 v35, v38, v39
	ds_read_b32 v38, v154 offset:640
	v_mad_i64_i32 v[36:37], s[20:21], v36, s40, v[112:113]
	v_lshl_add_u64 v[36:37], v[36:37], 0, v[114:115]
	global_store_dwordx4 v[36:37], v[32:35], off
	v_pk_mul_f32 v[8:9], v[12:13], v[8:9]
	v_pk_mul_f32 v[2:3], v[6:7], v[2:3]
	s_waitcnt lgkmcnt(0)
; __device__ __forceinline__ unsigned cvt_pk_bf16(float lo, float hi) { unsigned r; asm volatile("v_cvt_pk_bf16_f32 %0, %1, %2" : "=v"(r) : "v"(lo), "v"(hi)); return r; }
; #define PG8_WAIT_V(n) asm volatile("s_waitcnt vmcnt(" #n ")" ::: "memory")
; #define PG8_BAR __builtin_amdgcn_s_barrier()
;     __device__ __forceinline__ void operator()(Acc& acc, const Unit& u, int wr, int wc, int fr, int fq) const {
;     ...
;                 const int row = row0 + ai * HALF + m * 16;
;                 const float r = rs[u.idx * BM + wr * 64 + fr + ai * HALF + m * 16];
;                 const float c1 = -r * 1.4426950408889634f, r2 = r * r;
;                 f32x4 o[2];
; #pragma unroll
;                 for (int n = 0; n < 2; ++n) {
;                     const f32x4 g = acc[ai][0][m][n], up = acc[ai][1][m][n];
;                     const f32x4 t = g * c1; f32x4 e;
; #pragma unroll
;                     for (int i = 0; i < 4; ++i) e[i] = __builtin_amdgcn_exp2f(t[i]);
;                     const f32x4 d = e + 1.0f; f32x4 q;
; #pragma unroll
;                     for (int i = 0; i < 4; ++i) q[i] = __builtin_amdgcn_rcpf(d[i]);
;                     o[n] = (g * up) * (q * r2);
;                 }
;                 u32x4 w; w.x = cvt_pk_bf16(o[0][0], o[0][1]); w.y = cvt_pk_bf16(o[0][2], o[0][3]); w.z = cvt_pk_bf16(o[1][0], o[1][1]); w.w = cvt_pk_bf16(o[1][2], o[1][3]);
;                 *(u32x4*)(O + (size_t)row * DFF + col0) = w;
; template <class Epi, class Sched, bool ALIGN_EPI>
; __device__ __forceinline__ void gemm_phase(LAS unsigned char* lds, const Gemm g, const Sched& S, const Epi& E) {
;     ...
;         if constexpr (ALIGN_EPI) { if (wr == 0) PG8_BAR; }
;         E(acc, cur, wr, wc, fr, fq);
;         if (!has_next) break;
; #pragma unroll
;         for (int a = 0; a < 2; ++a)
; #pragma unroll
;             for (int b = 0; b < 2; ++b)
; #pragma unroll
;                 for (int m = 0; m < 4; ++m)
; #pragma unroll
;                     for (int n = 0; n < 2; ++n) acc[a][b][m][n] = (f32x4){0.f, 0.f, 0.f, 0.f};
;         cur = nxt; cA = nA; cB = nB; ++ui;
;         if constexpr (ALIGN_EPI) { if (wr == 1) PG8_BAR; }
;     }
;     PG8_WAIT_V(0);
;     if constexpr (!ALIGN_EPI) { if (wr == 0) PG8_BAR; }
	v_mul_f32_e32 v32, 0xbfb8aa3b, v38
	v_mul_f32_e32 v34, v38, v38
	v_pk_mul_f32 v[38:39], v[28:29], v[32:33] op_sel_hi:[1,0]
	v_pk_mul_f32 v[36:37], v[30:31], v[32:33] op_sel_hi:[1,0]
	v_exp_f32_e32 v33, v38
	v_exp_f32_e32 v35, v39
	v_exp_f32_e32 v38, v36
	v_exp_f32_e32 v39, v37
	v_add_f32_e32 v33, 1.0, v33
	v_rcp_f32_e32 v36, v33
	v_add_f32_e32 v33, 1.0, v35
	v_rcp_f32_e32 v37, v33
	v_add_f32_e32 v33, 1.0, v38
	v_rcp_f32_e32 v38, v33
	v_add_f32_e32 v33, 1.0, v39
	v_rcp_f32_e32 v39, v33
	v_pk_mul_f32 v[28:29], v[34:35], v[36:37] op_sel_hi:[0,1]
	v_pk_mul_f32 v[24:25], v[24:25], v[28:29]
	v_pk_mul_f32 v[28:29], v[22:23], v[32:33] op_sel_hi:[1,0]
	v_pk_mul_f32 v[30:31], v[34:35], v[38:39] op_sel_hi:[0,1]
	v_pk_mul_f32 v[26:27], v[26:27], v[30:31]
	v_pk_mul_f32 v[30:31], v[20:21], v[32:33] op_sel_hi:[1,0]
	v_exp_f32_e32 v32, v28
	v_exp_f32_e32 v30, v30
	v_exp_f32_e32 v31, v31
	v_exp_f32_e32 v33, v29
	v_pk_mul_f32 v[0:1], v[4:5], v[0:1]
	v_add_f32_e32 v28, 1.0, v30
	v_add_f32_e32 v29, 1.0, v31
	v_add_f32_e32 v30, 1.0, v32
	v_add_f32_e32 v31, 1.0, v33
	v_rcp_f32_e32 v28, v28
	v_rcp_f32_e32 v29, v29
	v_rcp_f32_e32 v30, v30
	v_rcp_f32_e32 v31, v31
	s_andn2_b64 vcc, exec, s[2:3]
	v_pk_mul_f32 v[20:21], v[34:35], v[28:29] op_sel_hi:[0,1]
	s_mov_b64 s[2:3], -1
	v_pk_mul_f32 v[22:23], v[34:35], v[30:31] op_sel_hi:[0,1]
	v_pk_mul_f32 v[22:23], v[18:19], v[22:23]
	v_pk_mul_f32 v[18:19], v[16:17], v[20:21]
	v_cvt_pk_bf16_f32 v16, v24, v25
	v_cvt_pk_bf16_f32 v17, v26, v27
	v_add_u32_e32 v20, 0xa0, v151
	v_cvt_pk_bf16_f32 v18, v18, v19
	v_cvt_pk_bf16_f32 v19, v22, v23
	ds_read_b32 v22, v154 offset:704
	v_mad_i64_i32 v[20:21], s[20:21], v20, s40, v[112:113]
	v_lshl_add_u64 v[20:21], v[20:21], 0, v[114:115]
	global_store_dwordx4 v[20:21], v[16:19], off
	s_waitcnt lgkmcnt(0)
	s_nop 0
	v_mul_f32_e32 v16, 0xbfb8aa3b, v22
	v_mul_f32_e32 v18, v22, v22
	v_pk_mul_f32 v[22:23], v[12:13], v[16:17] op_sel_hi:[1,0]
	v_pk_mul_f32 v[20:21], v[14:15], v[16:17] op_sel_hi:[1,0]
	v_exp_f32_e32 v17, v22
	v_exp_f32_e32 v19, v23
	v_exp_f32_e32 v22, v20
	v_exp_f32_e32 v23, v21
	v_add_f32_e32 v17, 1.0, v17
	v_rcp_f32_e32 v20, v17
	v_add_f32_e32 v17, 1.0, v19
	v_rcp_f32_e32 v21, v17
	v_add_f32_e32 v17, 1.0, v22
	v_rcp_f32_e32 v22, v17
	v_add_f32_e32 v17, 1.0, v23
	v_rcp_f32_e32 v23, v17
	v_pk_mul_f32 v[12:13], v[18:19], v[20:21] op_sel_hi:[0,1]
	v_pk_mul_f32 v[8:9], v[8:9], v[12:13]
	v_pk_mul_f32 v[12:13], v[6:7], v[16:17] op_sel_hi:[1,0]
	v_pk_mul_f32 v[14:15], v[18:19], v[22:23] op_sel_hi:[0,1]
	v_pk_mul_f32 v[10:11], v[10:11], v[14:15]
	v_pk_mul_f32 v[14:15], v[4:5], v[16:17] op_sel_hi:[1,0]
	v_exp_f32_e32 v16, v12
	v_exp_f32_e32 v14, v14
	v_exp_f32_e32 v15, v15
	v_exp_f32_e32 v17, v13
	v_add_f32_e32 v12, 1.0, v14
	v_add_f32_e32 v13, 1.0, v15
	v_add_f32_e32 v14, 1.0, v16
	v_add_f32_e32 v15, 1.0, v17
	v_rcp_f32_e32 v12, v12
	v_rcp_f32_e32 v13, v13
	v_rcp_f32_e32 v14, v14
	v_rcp_f32_e32 v15, v15
	v_pk_mul_f32 v[4:5], v[18:19], v[12:13] op_sel_hi:[0,1]
	v_pk_mul_f32 v[6:7], v[18:19], v[14:15] op_sel_hi:[0,1]
	v_pk_mul_f32 v[6:7], v[2:3], v[6:7]
	v_pk_mul_f32 v[2:3], v[0:1], v[4:5]
	v_add_u32_e32 v4, 0xb0, v151
	v_mad_i64_i32 v[4:5], s[20:21], v4, s40, v[112:113]
	v_lshl_add_u64 v[4:5], v[4:5], 0, v[114:115]
	v_cvt_pk_bf16_f32 v0, v8, v9
	v_cvt_pk_bf16_f32 v1, v10, v11
	v_cvt_pk_bf16_f32 v2, v2, v3
	v_cvt_pk_bf16_f32 v3, v6, v7
	global_store_dwordx4 v[4:5], v[0:3], off
	s_mov_b32 s101, 1
	s_cbranch_vccnz .LBB0_1609
	s_andn2_b64 vcc, exec, s[4:5]
	s_cbranch_vccnz .LBB0_1608
	s_barrier
	s_branch .LBB0_1608

;     __device__ __forceinline__ void mid(Acc& acc, const Unit& u, int wr, int wc, int fr, int fq) const { scale(acc, u, wr, wc, fr, fq, PC_GM, false); }
; template <class Epi, class Sched, bool ALIGN_EPI>
; __device__ __forceinline__ void gemm_phase(LAS unsigned char* lds, const Gemm g, const Sched& S, const Epi& E) {
;     ...
;                 for (int n = 0; n < 2; ++n) acc[a][b][m][n] = (f32x4){0.f, 0.f, 0.f, 0.f};
;     ...
;             for (int t = 0; t < Epi::MID_T; t += 2) PG8_KBODY(t);
;             E.mid(acc, cur, wr, wc, fr, fq);
;             for (int t = Epi::MID_T; t < nt; t += 2) PG8_KBODY(t);
;         } else {
;             for (int t = 0; t < nt; t += 2) PG8_KBODY(t);
.LBB0_1721:
	s_add_u32 s6, s24, 0xb0080
	s_addc_u32 s7, s25, 0
	s_add_u32 s48, s22, 0x100
	v_mov_b32_e32 v0, 0
	s_addc_u32 s49, s23, 0
	s_mov_b32 s50, -2
	ds_read_b128 v[128:131], v199
	ds_read_b128 v[132:135], v199 offset:1024
	ds_read_b128 v[136:139], v199 offset:2048
	ds_read_b128 v[140:143], v199 offset:3072
	ds_read_b128 v[144:147], v200
	ds_read_b128 v[148:151], v200 offset:1024
	ds_read_b128 v[168:171], v200 offset:2048
	ds_read_b128 v[172:175], v200 offset:3072
	s_add_u32 s22, s6, 0xfff50080
	s_addc_u32 s23, s7, -1
	s_cmp_eq_u32 s50, 40
	s_cselect_b32 s25, s19, s23
	s_cselect_b32 s24, s18, s22
	s_cselect_b32 s23, s21, s49
	s_cselect_b32 s22, s20, s48
	v_lshl_add_u64 v[216:217], s[6:7], 0, v[152:153]
	s_add_i32 m0, s29, 0xc000
	ds_read_b128 v[176:179], v201
	ds_read_b128 v[180:183], v201 offset:1024
	ds_read_b128 v[184:187], v201 offset:2048
	ds_read_b128 v[188:191], v201 offset:3072
	ds_read_b128 v[192:195], v201 offset:4096
	ds_read_b128 v[204:207], v201 offset:5120
	ds_read_b128 v[208:211], v201 offset:6144
	ds_read_b128 v[212:215], v201 offset:7168
	global_load_lds_dwordx4 v[216:217], off
	v_lshl_add_u64 v[216:217], s[6:7], 0, v[162:163]
	s_add_i32 m0, s29, 0xe000
	s_nop 0
	global_load_lds_dwordx4 v[216:217], off
	s_waitcnt vmcnt(8)
	s_waitcnt lgkmcnt(0)
	s_barrier
	s_setprio 1
	s_waitcnt lgkmcnt(0)
	v_mfma_f32_16x16x32_bf16 v[124:127], v[128:131], v[176:179], 0
	v_mfma_f32_16x16x32_bf16 v[120:123], v[136:139], v[176:179], 0
	v_mfma_f32_16x16x32_bf16 v[108:111], v[128:131], v[184:187], 0
	v_mfma_f32_16x16x32_bf16 v[104:107], v[136:139], v[184:187], 0
	v_mfma_f32_16x16x32_bf16 v[92:95], v[128:131], v[192:195], 0
	v_mfma_f32_16x16x32_bf16 v[88:91], v[136:139], v[192:195], 0
	v_mfma_f32_16x16x32_bf16 v[76:79], v[128:131], v[208:211], 0
	v_mfma_f32_16x16x32_bf16 v[72:75], v[136:139], v[208:211], 0
	v_mfma_f32_16x16x32_bf16 v[124:127], v[132:135], v[180:183], v[124:127]
	v_mfma_f32_16x16x32_bf16 v[120:123], v[140:143], v[180:183], v[120:123]
	v_mfma_f32_16x16x32_bf16 v[108:111], v[132:135], v[188:191], v[108:111]
	v_mfma_f32_16x16x32_bf16 v[104:107], v[140:143], v[188:191], v[104:107]
	v_mfma_f32_16x16x32_bf16 v[92:95], v[132:135], v[204:207], v[92:95]
	v_mfma_f32_16x16x32_bf16 v[88:91], v[140:143], v[204:207], v[88:91]
	v_mfma_f32_16x16x32_bf16 v[76:79], v[132:135], v[212:215], v[76:79]
	v_mfma_f32_16x16x32_bf16 v[72:75], v[140:143], v[212:215], v[72:75]
	s_setprio 0
	s_setprio 1
	v_mfma_f32_16x16x32_bf16 v[116:119], v[144:147], v[176:179], 0
	v_mfma_f32_16x16x32_bf16 v[112:115], v[168:171], v[176:179], 0
	v_mfma_f32_16x16x32_bf16 v[100:103], v[144:147], v[184:187], 0
	v_mfma_f32_16x16x32_bf16 v[96:99], v[168:171], v[184:187], 0
	v_mfma_f32_16x16x32_bf16 v[84:87], v[144:147], v[192:195], 0
	v_mfma_f32_16x16x32_bf16 v[80:83], v[168:171], v[192:195], 0
	v_mfma_f32_16x16x32_bf16 v[68:71], v[144:147], v[208:211], 0
	v_mfma_f32_16x16x32_bf16 v[64:67], v[168:171], v[208:211], 0
	v_mfma_f32_16x16x32_bf16 v[116:119], v[148:151], v[180:183], v[116:119]
	v_mfma_f32_16x16x32_bf16 v[112:115], v[172:175], v[180:183], v[112:115]
	v_mfma_f32_16x16x32_bf16 v[100:103], v[148:151], v[188:191], v[100:103]
	v_mfma_f32_16x16x32_bf16 v[96:99], v[172:175], v[188:191], v[96:99]
	v_mfma_f32_16x16x32_bf16 v[84:87], v[148:151], v[204:207], v[84:87]
	v_mfma_f32_16x16x32_bf16 v[80:83], v[172:175], v[204:207], v[80:83]
	v_mfma_f32_16x16x32_bf16 v[68:71], v[148:151], v[212:215], v[68:71]
	v_mfma_f32_16x16x32_bf16 v[64:67], v[172:175], v[212:215], v[64:67]
	s_setprio 0
	s_barrier
	s_add_i32 s51, s41, s28
	v_lshl_add_u64 v[216:217], s[22:23], 0, v[156:157]
	s_mov_b32 m0, s51
	ds_read_b128 v[176:179], v201 offset:16384
	ds_read_b128 v[180:183], v201 offset:17408
	global_load_lds_dwordx4 v[216:217], off
	s_add_i32 m0, s51, 0x2000
	s_add_u32 s52, s22, 0xb0000
	v_lshl_add_u64 v[218:219], s[22:23], 0, v[160:161]
	s_addc_u32 s53, s23, 0
	s_add_i32 s51, s42, s28
	ds_read_b128 v[184:187], v201 offset:18432
	ds_read_b128 v[188:191], v201 offset:19456
	global_load_lds_dwordx4 v[218:219], off
	v_lshl_add_u64 v[220:221], s[52:53], 0, v[156:157]
	s_mov_b32 m0, s51
	v_lshl_add_u64 v[222:223], s[24:25], 0, v[158:159]
	ds_read_b128 v[192:195], v201 offset:20480
	global_load_lds_dwordx4 v[220:221], off
	v_lshl_add_u64 v[220:221], s[52:53], 0, v[160:161]
	s_add_i32 m0, s51, 0x2000
	ds_read_b128 v[204:207], v201 offset:21504
	global_load_lds_dwordx4 v[220:221], off
	v_lshl_add_u64 v[220:221], s[24:25], 0, v[154:155]
	s_mov_b32 m0, s29
	ds_read_b128 v[208:211], v201 offset:22528
	global_load_lds_dwordx4 v[220:221], off
	s_mov_b32 m0, s30
	ds_read_b128 v[212:215], v201 offset:23552
	global_load_lds_dwordx4 v[222:223], off
	s_waitcnt vmcnt(8)
	s_waitcnt lgkmcnt(0)
	s_barrier
	s_setprio 1
	s_waitcnt lgkmcnt(0)
	v_mfma_f32_16x16x32_bf16 v[60:63], v[128:131], v[176:179], 0
	v_mfma_f32_16x16x32_bf16 v[56:59], v[136:139], v[176:179], 0
	v_mfma_f32_16x16x32_bf16 v[44:47], v[128:131], v[184:187], 0
	v_mfma_f32_16x16x32_bf16 v[40:43], v[136:139], v[184:187], 0
	v_mfma_f32_16x16x32_bf16 v[28:31], v[128:131], v[192:195], 0
	v_mfma_f32_16x16x32_bf16 v[24:27], v[136:139], v[192:195], 0
	v_mfma_f32_16x16x32_bf16 v[12:15], v[128:131], v[208:211], 0
	v_mfma_f32_16x16x32_bf16 v[8:11], v[136:139], v[208:211], 0
	v_mfma_f32_16x16x32_bf16 v[60:63], v[132:135], v[180:183], v[60:63]
	v_mfma_f32_16x16x32_bf16 v[56:59], v[140:143], v[180:183], v[56:59]
	v_mfma_f32_16x16x32_bf16 v[44:47], v[132:135], v[188:191], v[44:47]
	v_mfma_f32_16x16x32_bf16 v[40:43], v[140:143], v[188:191], v[40:43]
	v_mfma_f32_16x16x32_bf16 v[28:31], v[132:135], v[204:207], v[28:31]
	v_mfma_f32_16x16x32_bf16 v[24:27], v[140:143], v[204:207], v[24:27]
	v_mfma_f32_16x16x32_bf16 v[12:15], v[132:135], v[212:215], v[12:15]
	v_mfma_f32_16x16x32_bf16 v[8:11], v[140:143], v[212:215], v[8:11]
	s_setprio 0
	s_setprio 1
	v_mfma_f32_16x16x32_bf16 v[52:55], v[144:147], v[176:179], 0
	v_mfma_f32_16x16x32_bf16 v[48:51], v[168:171], v[176:179], 0
	v_mfma_f32_16x16x32_bf16 v[36:39], v[144:147], v[184:187], 0
	v_mfma_f32_16x16x32_bf16 v[32:35], v[168:171], v[184:187], 0
	v_mfma_f32_16x16x32_bf16 v[20:23], v[144:147], v[192:195], 0
	v_mfma_f32_16x16x32_bf16 v[16:19], v[168:171], v[192:195], 0
	v_mfma_f32_16x16x32_bf16 v[4:7], v[144:147], v[208:211], 0
	v_mfma_f32_16x16x32_bf16 v[0:3], v[168:171], v[208:211], 0
	v_mfma_f32_16x16x32_bf16 v[52:55], v[148:151], v[180:183], v[52:55]
	v_mfma_f32_16x16x32_bf16 v[48:51], v[172:175], v[180:183], v[48:51]
	v_mfma_f32_16x16x32_bf16 v[36:39], v[148:151], v[188:191], v[36:39]
	v_mfma_f32_16x16x32_bf16 v[32:35], v[172:175], v[188:191], v[32:35]
	v_mfma_f32_16x16x32_bf16 v[20:23], v[148:151], v[204:207], v[20:23]
	v_mfma_f32_16x16x32_bf16 v[16:19], v[172:175], v[204:207], v[16:19]
	v_mfma_f32_16x16x32_bf16 v[4:7], v[148:151], v[212:215], v[4:7]
	v_mfma_f32_16x16x32_bf16 v[0:3], v[172:175], v[212:215], v[0:3]
	s_setprio 0
	s_barrier
	s_branch .Lpk1722_seg3

.Lpk1722_seg3:
	s_add_i32 s51, 0, 0x18000
	s_add_i32 s52, 0, 0x1c000
	v_add_u32_e32 v140, s51, v197
	v_add_u32_e32 v172, s52, v197
	ds_read_b128 v[128:131], v140
	ds_read_b128 v[132:135], v140 offset:1024
	ds_read_b128 v[136:139], v140 offset:2048
	ds_read_b128 v[140:143], v140 offset:3072
	ds_read_b128 v[144:147], v172
	ds_read_b128 v[148:151], v172 offset:1024
	ds_read_b128 v[168:171], v172 offset:2048
	ds_read_b128 v[172:175], v172 offset:3072
	s_add_u32 s24, s24, 0xb0000
	s_addc_u32 s25, s25, 0
	s_mov_b32 m0, s31
	v_lshl_add_u64 v[224:225], s[24:25], 0, v[154:155]
	ds_read_b128 v[176:179], v201 offset:32768
	ds_read_b128 v[180:183], v201 offset:33792
	ds_read_b128 v[184:187], v201 offset:34816
	ds_read_b128 v[188:191], v201 offset:35840
	ds_read_b128 v[192:195], v201 offset:36864
	ds_read_b128 v[204:207], v201 offset:37888
	ds_read_b128 v[208:211], v201 offset:38912
	ds_read_b128 v[212:215], v201 offset:39936
	global_load_lds_dwordx4 v[224:225], off
	v_lshl_add_u64 v[224:225], s[24:25], 0, v[158:159]
	s_mov_b32 m0, s33
	s_nop 0
	global_load_lds_dwordx4 v[224:225], off
	s_waitcnt vmcnt(8)
	s_waitcnt lgkmcnt(0)
	s_barrier
	s_setprio 1
	s_waitcnt lgkmcnt(0)
	v_mfma_f32_16x16x32_bf16 v[124:127], v[128:131], v[176:179], v[124:127]
	v_mfma_f32_16x16x32_bf16 v[120:123], v[136:139], v[176:179], v[120:123]
	v_mfma_f32_16x16x32_bf16 v[108:111], v[128:131], v[184:187], v[108:111]
	v_mfma_f32_16x16x32_bf16 v[104:107], v[136:139], v[184:187], v[104:107]
	v_mfma_f32_16x16x32_bf16 v[92:95], v[128:131], v[192:195], v[92:95]
	v_mfma_f32_16x16x32_bf16 v[88:91], v[136:139], v[192:195], v[88:91]
	v_mfma_f32_16x16x32_bf16 v[76:79], v[128:131], v[208:211], v[76:79]
	v_mfma_f32_16x16x32_bf16 v[72:75], v[136:139], v[208:211], v[72:75]
	v_mfma_f32_16x16x32_bf16 v[124:127], v[132:135], v[180:183], v[124:127]
	v_mfma_f32_16x16x32_bf16 v[120:123], v[140:143], v[180:183], v[120:123]
	v_mfma_f32_16x16x32_bf16 v[108:111], v[132:135], v[188:191], v[108:111]
	v_mfma_f32_16x16x32_bf16 v[104:107], v[140:143], v[188:191], v[104:107]
	v_mfma_f32_16x16x32_bf16 v[92:95], v[132:135], v[204:207], v[92:95]
	v_mfma_f32_16x16x32_bf16 v[88:91], v[140:143], v[204:207], v[88:91]
	v_mfma_f32_16x16x32_bf16 v[76:79], v[132:135], v[212:215], v[76:79]
	v_mfma_f32_16x16x32_bf16 v[72:75], v[140:143], v[212:215], v[72:75]
	s_setprio 0
	s_setprio 1
	v_mfma_f32_16x16x32_bf16 v[116:119], v[144:147], v[176:179], v[116:119]
	v_mfma_f32_16x16x32_bf16 v[112:115], v[168:171], v[176:179], v[112:115]
	v_mfma_f32_16x16x32_bf16 v[100:103], v[144:147], v[184:187], v[100:103]
	v_mfma_f32_16x16x32_bf16 v[96:99], v[168:171], v[184:187], v[96:99]
	v_mfma_f32_16x16x32_bf16 v[84:87], v[144:147], v[192:195], v[84:87]
	v_mfma_f32_16x16x32_bf16 v[80:83], v[168:171], v[192:195], v[80:83]
	v_mfma_f32_16x16x32_bf16 v[68:71], v[144:147], v[208:211], v[68:71]
	v_mfma_f32_16x16x32_bf16 v[64:67], v[168:171], v[208:211], v[64:67]
	v_mfma_f32_16x16x32_bf16 v[116:119], v[148:151], v[180:183], v[116:119]
	v_mfma_f32_16x16x32_bf16 v[112:115], v[172:175], v[180:183], v[112:115]
	v_mfma_f32_16x16x32_bf16 v[100:103], v[148:151], v[188:191], v[100:103]
	v_mfma_f32_16x16x32_bf16 v[96:99], v[172:175], v[188:191], v[96:99]
	v_mfma_f32_16x16x32_bf16 v[84:87], v[148:151], v[204:207], v[84:87]
	v_mfma_f32_16x16x32_bf16 v[80:83], v[172:175], v[204:207], v[80:83]
	v_mfma_f32_16x16x32_bf16 v[68:71], v[148:151], v[212:215], v[68:71]
	v_mfma_f32_16x16x32_bf16 v[64:67], v[172:175], v[212:215], v[64:67]
	s_setprio 0
	s_barrier
; #define PG8_BAR __builtin_amdgcn_s_barrier()
; template <class Epi, class Sched, bool ALIGN_EPI>
; __device__ __forceinline__ void gemm_phase(LAS unsigned char* lds, const Gemm g, const Sched& S, const Epi& E) {
;     ...
;             for (int t = 0; t < nt; t += 2) PG8_KBODY(t);
;         }
;         if constexpr (ALIGN_EPI) { if (wr == 0) PG8_BAR; }
	s_add_i32 s24, s51, s28
	v_lshl_add_u64 v[216:217], v[216:217], 0, s[14:15]
	s_mov_b32 m0, s24
	ds_read_b128 v[176:179], v201 offset:49152
	ds_read_b128 v[180:183], v201 offset:50176
	global_load_lds_dwordx4 v[216:217], off
	s_add_i32 m0, s24, 0x2000
	s_add_u32 s22, s22, 0xb0080
	v_lshl_add_u64 v[216:217], v[218:219], 0, s[14:15]
	s_addc_u32 s23, s23, 0
	s_add_i32 s24, s52, s28
	ds_read_b128 v[184:187], v201 offset:51200
	ds_read_b128 v[188:191], v201 offset:52224
	global_load_lds_dwordx4 v[216:217], off
	v_lshl_add_u64 v[216:217], s[22:23], 0, v[156:157]
	s_mov_b32 m0, s24
	ds_read_b128 v[192:195], v201 offset:53248
	global_load_lds_dwordx4 v[216:217], off
	v_lshl_add_u64 v[216:217], s[22:23], 0, v[160:161]
	s_add_i32 m0, s24, 0x2000
	ds_read_b128 v[204:207], v201 offset:54272
	global_load_lds_dwordx4 v[216:217], off
	v_lshl_add_u64 v[216:217], v[220:221], 0, s[14:15]
	s_mov_b32 m0, s37
	ds_read_b128 v[208:211], v201 offset:55296
	global_load_lds_dwordx4 v[216:217], off
	v_lshl_add_u64 v[216:217], v[222:223], 0, s[14:15]
	s_mov_b32 m0, s38
	ds_read_b128 v[212:215], v201 offset:56320
	global_load_lds_dwordx4 v[216:217], off
	s_waitcnt vmcnt(8)
	s_waitcnt lgkmcnt(0)
	s_barrier
	s_setprio 1
	s_waitcnt lgkmcnt(0)
	v_mfma_f32_16x16x32_bf16 v[60:63], v[128:131], v[176:179], v[60:63]
	v_mfma_f32_16x16x32_bf16 v[56:59], v[136:139], v[176:179], v[56:59]
	v_mfma_f32_16x16x32_bf16 v[44:47], v[128:131], v[184:187], v[44:47]
	v_mfma_f32_16x16x32_bf16 v[40:43], v[136:139], v[184:187], v[40:43]
	v_mfma_f32_16x16x32_bf16 v[28:31], v[128:131], v[192:195], v[28:31]
	v_mfma_f32_16x16x32_bf16 v[24:27], v[136:139], v[192:195], v[24:27]
	v_mfma_f32_16x16x32_bf16 v[12:15], v[128:131], v[208:211], v[12:15]
	v_mfma_f32_16x16x32_bf16 v[8:11], v[136:139], v[208:211], v[8:11]
	v_mfma_f32_16x16x32_bf16 v[60:63], v[132:135], v[180:183], v[60:63]
	v_mfma_f32_16x16x32_bf16 v[56:59], v[140:143], v[180:183], v[56:59]
	v_mfma_f32_16x16x32_bf16 v[44:47], v[132:135], v[188:191], v[44:47]
	v_mfma_f32_16x16x32_bf16 v[40:43], v[140:143], v[188:191], v[40:43]
	v_mfma_f32_16x16x32_bf16 v[28:31], v[132:135], v[204:207], v[28:31]
	v_mfma_f32_16x16x32_bf16 v[24:27], v[140:143], v[204:207], v[24:27]
	v_mfma_f32_16x16x32_bf16 v[12:15], v[132:135], v[212:215], v[12:15]
	v_mfma_f32_16x16x32_bf16 v[8:11], v[140:143], v[212:215], v[8:11]
	s_setprio 0
	s_setprio 1
	v_mfma_f32_16x16x32_bf16 v[52:55], v[144:147], v[176:179], v[52:55]
	v_mfma_f32_16x16x32_bf16 v[48:51], v[168:171], v[176:179], v[48:51]
	v_mfma_f32_16x16x32_bf16 v[36:39], v[144:147], v[184:187], v[36:39]
	v_mfma_f32_16x16x32_bf16 v[32:35], v[168:171], v[184:187], v[32:35]
	v_mfma_f32_16x16x32_bf16 v[20:23], v[144:147], v[192:195], v[20:23]
	v_mfma_f32_16x16x32_bf16 v[16:19], v[168:171], v[192:195], v[16:19]
	v_mfma_f32_16x16x32_bf16 v[4:7], v[144:147], v[208:211], v[4:7]
	v_mfma_f32_16x16x32_bf16 v[0:3], v[168:171], v[208:211], v[0:3]
	v_mfma_f32_16x16x32_bf16 v[52:55], v[148:151], v[180:183], v[52:55]
	v_mfma_f32_16x16x32_bf16 v[48:51], v[172:175], v[180:183], v[48:51]
	v_mfma_f32_16x16x32_bf16 v[36:39], v[148:151], v[188:191], v[36:39]
	v_mfma_f32_16x16x32_bf16 v[32:35], v[172:175], v[188:191], v[32:35]
	v_mfma_f32_16x16x32_bf16 v[20:23], v[148:151], v[204:207], v[20:23]
	v_mfma_f32_16x16x32_bf16 v[16:19], v[172:175], v[204:207], v[16:19]
	v_mfma_f32_16x16x32_bf16 v[4:7], v[148:151], v[212:215], v[4:7]
	v_mfma_f32_16x16x32_bf16 v[0:3], v[172:175], v[212:215], v[0:3]
	s_setprio 0
	s_barrier
	s_add_i32 s50, s50, 2
	s_add_u32 s6, s6, 0x100
	s_addc_u32 s7, s7, 0
	s_add_u32 s48, s48, 0x100
	s_addc_u32 s49, s49, 0
	s_cmp_gt_u32 s50, 41
	s_cbranch_scc0 .LBB0_1722
	s_and_b64 vcc, exec, s[16:17]
	s_cbranch_vccz .LBB0_1725
	s_barrier
